# nt (non-temporal) loads for the read-once f32 inputs in P0 (x rows, weights)
# speedup vs baseline: 1.0218x; 1.0198x over previous
;     if (ldw == 0) ldw = K;
;     const int nblk = N / 32, kb = item / nblk, nb = item % nblk, k0 = 64 * kb, n0 = 32 * nb;
;     float tv_[32];
; #pragma unroll
;     for (int i = 0; i < 32; ++i) tv_[i] = W[(size_t)(k0 + 2 * i + (lane >> 5)) * N + n0 + (lane & 31)];
; #pragma unroll
;     for (int i = 0; i < 32; ++i) scr[(2 * i + (lane >> 5)) * 33 + (lane & 31)] = tv_[i];
;     LDS_WAIT(); asm volatile("" ::: "memory");
;     const int c = lane & 7;
; #pragma unroll
;     for (int j = 0; j < 4; ++j) { const int n = (lane >> 3) + 8 * j; const LAS float* s = scr + (8 * c) * 33 + n;
;         v4u o; o.x = pk2(s[0 * 33], s[1 * 33]); o.y = pk2(s[2 * 33], s[3 * 33]); o.z = pk2(s[4 * 33], s[5 * 33]); o.w = pk2(s[6 * 33], s[7 * 33]);
; __device__ __forceinline__ void convert_range(LAS unsigned char* lds, const Params& p, const int lo, const int hi, const int gw, const int NGW) {
;     ...
;     for (int it = lo + gw; it < hi; it += NGW) {
;         int r = it;
;         if (r < 2 * I_IN) { const int l = r / I_IN; r -= l * I_IN; p0_transpose_item(p.in[5] + (size_t)l * DM * NC, DM, NC, (bf16*)(ws + WS_WIN + l * SZ_WIN), scr, r, lane); continue; } r -= 2 * I_IN;
;         if (r < 2 * I_PA) { const int l = r / I_PA; r -= l * I_PA; p0_transpose_item(p.in[16] + (size_t)l * PW * DM, PW, DM, (bf16*)(ws + WS_WCAT + l * SZ_WCAT), scr, r, lane, KCAT, 0); continue; } r -= 2 * I_PA;
;         if (r < 2 * I_PB) { const int l = r / I_PB; r -= l * I_PB; p0_transpose_item(p.in[17] + (size_t)l * LW * DM, LW, DM, (bf16*)(ws + WS_WCAT + l * SZ_WCAT), scr, r, lane, KCAT, PW); continue; } r -= 2 * I_PB;
;         if (r < 2 * I_OUT) { const int l = r / I_OUT; r -= l * I_OUT; p0_transpose_item(p.in[18] + (size_t)l * DM * DM, DM, DM, (bf16*)(ws + WS_WOUT + l * SZ_WOUT), scr, r, lane); continue; } r -= 2 * I_OUT;
;         if (r < I_PL) { const int mi = r / 32; r -= mi * 32; p0_transpose_item(p.in[7] + (size_t)mi * 65536, 256, 256, (bf16*)(ws + WS_POOLW) + (size_t)mi * 65536, scr, r, lane); continue; } r -= I_PL;
;         if (r < I_LR) { const int mi = r / 8; r -= mi * 8; p0_transpose_item(p.in[11] + (size_t)mi * 16384, 128, 128, (bf16*)(ws + WS_WA) + (size_t)mi * 16384, scr, r, lane); continue; } r -= I_LR;
;         { const int mi = r / 8; r -= mi * 8; p0_transpose_item(p.in[13] + (size_t)mi * 16384, 128, 128, (bf16*)(ws + WS_WX) + (size_t)mi * 16384, scr, r, lane); }
.LBB0_22:
	v_add_u32_e32 v20, 0x7a00, v27
	s_movk_i32 s24, 0x4fff
	v_cmp_lt_i32_e32 vcc, s24, v20
	s_and_saveexec_b64 s[24:25], vcc
	s_xor_b64 s[24:25], exec, s[24:25]
	s_cbranch_execz .LBB0_44
	s_movk_i32 s26, 0x57ff
	v_cmp_lt_u32_e32 vcc, s26, v20
	s_and_saveexec_b64 s[26:27], vcc
	s_xor_b64 s[26:27], exec, s[26:27]
	s_cbranch_execz .LBB0_41
	s_movk_i32 s28, 0x67ff
	v_cmp_lt_u32_e32 vcc, s28, v20
	s_and_saveexec_b64 s[28:29], vcc
	s_xor_b64 s[28:29], exec, s[28:29]
	s_cbranch_execz .LBB0_38
	s_movk_i32 s30, 0x77ff
	v_cmp_lt_u32_e32 vcc, s30, v20
	s_and_saveexec_b64 s[30:31], vcc
	s_xor_b64 s[30:31], exec, s[30:31]
	s_cbranch_execz .LBB0_35
	s_movk_i32 s34, 0x78ff
	v_cmp_lt_u32_e32 vcc, s34, v20
	s_and_saveexec_b64 s[34:35], vcc
	s_xor_b64 s[34:35], exec, s[34:35]
	s_cbranch_execz .LBB0_32
	s_movk_i32 s36, 0x79ff
	v_cmp_lt_u32_e32 vcc, s36, v20
	v_and_b32_e32 v20, 64, v28
	v_or_b32_e32 v4, v20, v1
	v_lshlrev_b32_e32 v21, 7, v4
	s_and_saveexec_b64 s[36:37], vcc
	s_xor_b64 s[36:37], exec, s[36:37]
	s_cbranch_execz .LBB0_29
	v_lshrrev_b32_e32 v4, 3, v27
	v_lshlrev_b64 v[36:37], 16, v[4:5]
	v_lshlrev_b64 v[34:35], 15, v[4:5]
	v_lshl_add_u64 v[36:37], v[16:17], 0, v[36:37]
	v_lshlrev_b32_e32 v4, 2, v21
	v_lshl_add_u64 v[36:37], v[36:37], 0, v[4:5]
	v_add_co_u32_e32 v38, vcc, 0x1000, v36
	v_add_u32_e32 v66, 0x1000, v3
	s_nop 0
	v_addc_co_u32_e32 v39, vcc, 0, v37, vcc
	global_load_dword v4, v[36:37], off nt
	global_load_dword v21, v[36:37], off offset:1024 nt
	global_load_dword v33, v[36:37], off offset:2048 nt
	global_load_dword v42, v[36:37], off offset:3072 nt
	global_load_dword v43, v[38:39], off nt
	global_load_dword v44, v[38:39], off offset:1024 nt
	global_load_dword v45, v[38:39], off offset:2048 nt
	global_load_dword v46, v[38:39], off offset:3072 nt
	v_add_co_u32_e32 v38, vcc, 0x2000, v36
	v_add_u32_e32 v67, 0x1400, v3
	s_nop 0
	v_addc_co_u32_e32 v39, vcc, 0, v37, vcc
	v_add_co_u32_e32 v40, vcc, 0x3000, v36
	v_add_u32_e32 v68, 0x1800, v3
	s_nop 0
	v_addc_co_u32_e32 v41, vcc, 0, v37, vcc
	global_load_dword v47, v[38:39], off nt
	global_load_dword v48, v[38:39], off offset:1024 nt
	global_load_dword v49, v[38:39], off offset:2048 nt
	global_load_dword v50, v[38:39], off offset:3072 nt
	global_load_dword v51, v[40:41], off nt
	global_load_dword v52, v[40:41], off offset:1024 nt
	global_load_dword v53, v[40:41], off offset:2048 nt
	global_load_dword v54, v[40:41], off offset:3072 nt
	v_add_co_u32_e32 v38, vcc, 0x4000, v36
	v_add_u32_e32 v69, 0x1c00, v3
	s_nop 0
	v_addc_co_u32_e32 v39, vcc, 0, v37, vcc
	v_add_co_u32_e32 v40, vcc, 0x5000, v36
	v_lshl_add_u64 v[34:35], s[12:13], 0, v[34:35]
	s_nop 0
	v_addc_co_u32_e32 v41, vcc, 0, v37, vcc
	global_load_dword v55, v[38:39], off nt
	global_load_dword v56, v[38:39], off offset:1024 nt
	global_load_dword v57, v[38:39], off offset:2048 nt
	global_load_dword v58, v[38:39], off offset:3072 nt
	global_load_dword v59, v[40:41], off nt
	global_load_dword v60, v[40:41], off offset:1024 nt
	global_load_dword v61, v[40:41], off offset:2048 nt
	s_nop 0
	global_load_dword v40, v[40:41], off offset:3072 nt
	v_add_co_u32_e32 v38, vcc, 0x6000, v36
	s_nop 1
	v_addc_co_u32_e32 v39, vcc, 0, v37, vcc
	v_add_co_u32_e32 v36, vcc, 0x7000, v36
	s_nop 1
	v_addc_co_u32_e32 v37, vcc, 0, v37, vcc
	global_load_dword v41, v[38:39], off nt
	global_load_dword v62, v[38:39], off offset:1024 nt
	global_load_dword v63, v[38:39], off offset:2048 nt
	s_nop 0
	global_load_dword v38, v[38:39], off offset:3072 nt
	s_nop 0
	global_load_dword v39, v[36:37], off nt
	global_load_dword v64, v[36:37], off offset:1024 nt
	global_load_dword v65, v[36:37], off offset:2048 nt
	s_nop 0
	global_load_dword v36, v[36:37], off offset:3072 nt
	v_add_u32_e32 v37, 0xc00, v3
	s_waitcnt vmcnt(30)
	ds_write2_b32 v3, v4, v21 offset1:66
	s_waitcnt vmcnt(28)
	ds_write2_b32 v3, v33, v42 offset0:132 offset1:198
	s_waitcnt vmcnt(26)
	ds_write2_b32 v31, v43, v44 offset0:8 offset1:74
	s_waitcnt vmcnt(24)
	ds_write2_b32 v31, v45, v46 offset0:140 offset1:206
	s_waitcnt vmcnt(22)
	ds_write2_b32 v32, v47, v48 offset0:16 offset1:82
	s_waitcnt vmcnt(20)
	ds_write2_b32 v32, v49, v50 offset0:148 offset1:214
	s_waitcnt vmcnt(18)
	ds_write2_b32 v37, v51, v52 offset0:24 offset1:90
	s_waitcnt vmcnt(16)
	ds_write2_b32 v37, v53, v54 offset0:156 offset1:222
	s_waitcnt vmcnt(14)
	ds_write2_b32 v66, v55, v56 offset0:32 offset1:98
	s_waitcnt vmcnt(12)
	ds_write2_b32 v66, v57, v58 offset0:164 offset1:230
	s_waitcnt vmcnt(10)
	ds_write2_b32 v67, v59, v60 offset0:40 offset1:106
	s_waitcnt vmcnt(8)
	ds_write2_b32 v67, v61, v40 offset0:172 offset1:238
	s_waitcnt vmcnt(6)
	ds_write2_b32 v68, v41, v62 offset0:48 offset1:114
	s_waitcnt vmcnt(4)
	ds_write2_b32 v68, v63, v38 offset0:180 offset1:246
	s_waitcnt vmcnt(2)
	ds_write2_b32 v69, v39, v64 offset0:56 offset1:122
	s_waitcnt vmcnt(0)
	ds_write2_b32 v69, v65, v36 offset0:188 offset1:254
	s_waitcnt lgkmcnt(0)
	v_lshlrev_b32_e32 v4, 1, v20
	v_lshl_add_u64 v[20:21], v[34:35], 0, v[4:5]
	v_lshlrev_b32_e32 v4, 1, v6
	v_lshl_add_u64 v[20:21], v[20:21], 0, v[4:5]
	ds_read_b32 v4, v23
	ds_read_b32 v33, v23 offset:132
	ds_read_b32 v35, v23 offset:264
	ds_read_b32 v36, v23 offset:396
	ds_read_b32 v37, v23 offset:528
	ds_read_b32 v38, v23 offset:660
	ds_read_b32 v39, v23 offset:792
	ds_read_b32 v40, v23 offset:924
	s_waitcnt lgkmcnt(7)
	v_bfe_u32 v34, v4, 16, 1
	v_add3_u32 v4, v4, v34, s41
	s_waitcnt lgkmcnt(6)
	v_bfe_u32 v34, v33, 16, 1
	v_lshrrev_b32_e32 v4, 16, v4
	v_add3_u32 v33, v33, v34, s41
	v_and_or_b32 v34, v33, s42, v4
	s_waitcnt lgkmcnt(5)
	v_bfe_u32 v4, v35, 16, 1
	v_add3_u32 v4, v35, v4, s41
	s_waitcnt lgkmcnt(4)
; #define LAS __attribute__((address_space(3)))
; #define LDS_WAIT() asm volatile("s_waitcnt lgkmcnt(0)" ::: "memory")
; __device__ __forceinline__ unsigned pk2(float lo, float hi) { return f2bf(lo) | (f2bf(hi) << 16); }
;     if (ldw == 0) ldw = K;
;     const int nblk = N / 32, kb = item / nblk, nb = item % nblk, k0 = 64 * kb, n0 = 32 * nb;
;     float tv_[32];
; #pragma unroll
;     for (int i = 0; i < 32; ++i) tv_[i] = W[(size_t)(k0 + 2 * i + (lane >> 5)) * N + n0 + (lane & 31)];
; #pragma unroll
;     for (int i = 0; i < 32; ++i) scr[(2 * i + (lane >> 5)) * 33 + (lane & 31)] = tv_[i];
;     LDS_WAIT(); asm volatile("" ::: "memory");
;     const int c = lane & 7;
; #pragma unroll
;     for (int j = 0; j < 4; ++j) { const int n = (lane >> 3) + 8 * j; const LAS float* s = scr + (8 * c) * 33 + n;
;         v4u o; o.x = pk2(s[0 * 33], s[1 * 33]); o.y = pk2(s[2 * 33], s[3 * 33]); o.z = pk2(s[4 * 33], s[5 * 33]); o.w = pk2(s[6 * 33], s[7 * 33]);
;         *(v4u*)(WT + (size_t)(n0 + n) * ldw + koff + k0 + 8 * c) = o; }
;     LDS_WAIT(); asm volatile("" ::: "memory");
; }
; __device__ __forceinline__ void convert_range(LAS unsigned char* lds, const Params& p, const int lo, const int hi, const int gw, const int NGW) {
;     ...
;         if (r < I_LR) { const int mi = r / 8; r -= mi * 8; p0_transpose_item(p.in[11] + (size_t)mi * 16384, 128, 128, (bf16*)(ws + WS_WA) + (size_t)mi * 16384, scr, r, lane); continue; } r -= I_LR;
	v_bfe_u32 v33, v36, 16, 1
	v_lshrrev_b32_e32 v4, 16, v4
	v_add3_u32 v33, v36, v33, s41
	v_and_or_b32 v35, v33, s42, v4
	s_waitcnt lgkmcnt(3)
	v_bfe_u32 v4, v37, 16, 1
	v_add3_u32 v4, v37, v4, s41
	s_waitcnt lgkmcnt(2)
	v_bfe_u32 v33, v38, 16, 1
	v_lshrrev_b32_e32 v4, 16, v4
	v_add3_u32 v33, v38, v33, s41
	v_and_or_b32 v36, v33, s42, v4
	s_waitcnt lgkmcnt(1)
	v_bfe_u32 v4, v39, 16, 1
	v_add3_u32 v4, v39, v4, s41
	s_waitcnt lgkmcnt(0)
	v_bfe_u32 v33, v40, 16, 1
	v_lshrrev_b32_e32 v4, 16, v4
	v_add3_u32 v33, v40, v33, s41
	v_and_or_b32 v37, v33, s42, v4
	v_lshl_add_u64 v[38:39], v[20:21], 0, v[8:9]
	global_store_dwordx4 v[38:39], v[34:37], off
	ds_read_b32 v4, v23 offset:32
	ds_read_b32 v33, v23 offset:164
	ds_read_b32 v35, v23 offset:296
	ds_read_b32 v36, v23 offset:428
	ds_read_b32 v37, v23 offset:560
	ds_read_b32 v38, v23 offset:692
	ds_read_b32 v39, v23 offset:824
	ds_read_b32 v40, v23 offset:956
	s_waitcnt lgkmcnt(0)
	v_bfe_u32 v34, v4, 16, 1
	v_add3_u32 v4, v4, v34, s41
	v_bfe_u32 v34, v33, 16, 1
	v_lshrrev_b32_e32 v4, 16, v4
	v_add3_u32 v33, v33, v34, s41
	v_and_or_b32 v34, v33, s42, v4
	v_bfe_u32 v4, v35, 16, 1
	v_add3_u32 v4, v35, v4, s41
	v_bfe_u32 v33, v36, 16, 1
	v_lshrrev_b32_e32 v4, 16, v4
	v_add3_u32 v33, v36, v33, s41
	v_and_or_b32 v35, v33, s42, v4
	v_bfe_u32 v4, v37, 16, 1
	v_add3_u32 v4, v37, v4, s41
	v_bfe_u32 v33, v38, 16, 1
	v_lshrrev_b32_e32 v4, 16, v4
	v_add3_u32 v33, v38, v33, s41
	v_and_or_b32 v36, v33, s42, v4
	v_bfe_u32 v4, v39, 16, 1
	v_add3_u32 v4, v39, v4, s41
	v_bfe_u32 v33, v40, 16, 1
	v_lshrrev_b32_e32 v4, 16, v4
	v_add3_u32 v33, v40, v33, s41
	v_and_or_b32 v37, v33, s42, v4
	v_lshl_add_u64 v[38:39], v[20:21], 0, v[10:11]
	global_store_dwordx4 v[38:39], v[34:37], off
	ds_read_b32 v4, v23 offset:64
	ds_read_b32 v33, v23 offset:196
	ds_read_b32 v35, v23 offset:328
	ds_read_b32 v36, v23 offset:460
	ds_read_b32 v37, v23 offset:592
	ds_read_b32 v38, v23 offset:724
	ds_read_b32 v39, v23 offset:856
	ds_read_b32 v40, v23 offset:988
	s_waitcnt lgkmcnt(0)
	v_bfe_u32 v34, v4, 16, 1
	v_add3_u32 v4, v4, v34, s41
	v_bfe_u32 v34, v33, 16, 1
	v_lshrrev_b32_e32 v4, 16, v4
	v_add3_u32 v33, v33, v34, s41
	v_and_or_b32 v34, v33, s42, v4
	v_bfe_u32 v4, v35, 16, 1
	v_add3_u32 v4, v35, v4, s41
	v_bfe_u32 v33, v36, 16, 1
	v_lshrrev_b32_e32 v4, 16, v4
	v_add3_u32 v33, v36, v33, s41
	v_and_or_b32 v35, v33, s42, v4
	v_bfe_u32 v4, v37, 16, 1
	v_add3_u32 v4, v37, v4, s41
	v_bfe_u32 v33, v38, 16, 1
	v_lshrrev_b32_e32 v4, 16, v4
	v_add3_u32 v33, v38, v33, s41
	v_and_or_b32 v36, v33, s42, v4
	v_bfe_u32 v4, v39, 16, 1
	v_add3_u32 v4, v39, v4, s41
	v_bfe_u32 v33, v40, 16, 1
	v_lshrrev_b32_e32 v4, 16, v4
	v_add3_u32 v33, v40, v33, s41
	v_and_or_b32 v37, v33, s42, v4
	v_lshl_add_u64 v[38:39], v[20:21], 0, v[12:13]
	global_store_dwordx4 v[38:39], v[34:37], off
	ds_read_b32 v4, v23 offset:96
	ds_read_b32 v33, v23 offset:228
	ds_read_b32 v35, v23 offset:360
	ds_read_b32 v36, v23 offset:492
	ds_read_b32 v37, v23 offset:624
	ds_read_b32 v38, v23 offset:756
	ds_read_b32 v39, v23 offset:888
	ds_read_b32 v40, v23 offset:1020
	s_waitcnt lgkmcnt(0)
	v_bfe_u32 v34, v4, 16, 1
	v_add3_u32 v4, v4, v34, s41
	v_bfe_u32 v34, v33, 16, 1
	v_lshrrev_b32_e32 v4, 16, v4
	v_add3_u32 v33, v33, v34, s41
	v_and_or_b32 v34, v33, s42, v4
	v_bfe_u32 v4, v35, 16, 1
	v_add3_u32 v4, v35, v4, s41
	v_bfe_u32 v33, v36, 16, 1
	v_lshrrev_b32_e32 v4, 16, v4
	v_add3_u32 v33, v36, v33, s41
	v_and_or_b32 v35, v33, s42, v4
	v_bfe_u32 v4, v37, 16, 1
	v_add3_u32 v4, v37, v4, s41
	v_bfe_u32 v33, v38, 16, 1
	v_lshrrev_b32_e32 v4, 16, v4
	v_add3_u32 v33, v38, v33, s41
	v_and_or_b32 v36, v33, s42, v4
	v_bfe_u32 v4, v39, 16, 1
	v_add3_u32 v4, v39, v4, s41
	v_bfe_u32 v33, v40, 16, 1
	v_lshrrev_b32_e32 v4, 16, v4
	v_add3_u32 v33, v40, v33, s41
	v_and_or_b32 v37, v33, s42, v4
	v_lshl_add_u64 v[20:21], v[20:21], 0, v[14:15]
	global_store_dwordx4 v[20:21], v[34:37], off
	s_waitcnt lgkmcnt(0)
.LBB0_29:
	s_andn2_saveexec_b64 s[36:37], s[36:37]
	s_cbranch_execz .LBB0_31
	v_add_u32_e32 v4, 0x100, v27
	v_lshrrev_b32_e32 v4, 3, v4
	v_lshlrev_b64 v[36:37], 16, v[4:5]
	v_lshlrev_b64 v[34:35], 15, v[4:5]
	v_lshl_add_u64 v[36:37], v[18:19], 0, v[36:37]
	v_lshlrev_b32_e32 v4, 2, v21
	v_lshl_add_u64 v[36:37], v[36:37], 0, v[4:5]
	v_add_co_u32_e32 v38, vcc, 0x1000, v36
	v_add_u32_e32 v66, 0x1000, v3
	s_nop 0
	v_addc_co_u32_e32 v39, vcc, 0, v37, vcc
	global_load_dword v4, v[36:37], off nt
	global_load_dword v21, v[36:37], off offset:1024 nt
	global_load_dword v33, v[36:37], off offset:2048 nt
	global_load_dword v42, v[36:37], off offset:3072 nt
	global_load_dword v43, v[38:39], off nt
	global_load_dword v44, v[38:39], off offset:1024 nt
	global_load_dword v45, v[38:39], off offset:2048 nt
	global_load_dword v46, v[38:39], off offset:3072 nt
	v_add_co_u32_e32 v38, vcc, 0x2000, v36
	v_add_u32_e32 v67, 0x1400, v3
	s_nop 0
	v_addc_co_u32_e32 v39, vcc, 0, v37, vcc
	v_add_co_u32_e32 v40, vcc, 0x3000, v36
	v_add_u32_e32 v68, 0x1800, v3
	s_nop 0
	v_addc_co_u32_e32 v41, vcc, 0, v37, vcc
	global_load_dword v47, v[38:39], off nt
	global_load_dword v48, v[38:39], off offset:1024 nt
	global_load_dword v49, v[38:39], off offset:2048 nt
	global_load_dword v50, v[38:39], off offset:3072 nt
	global_load_dword v51, v[40:41], off nt
	global_load_dword v52, v[40:41], off offset:1024 nt
	global_load_dword v53, v[40:41], off offset:2048 nt
	global_load_dword v54, v[40:41], off offset:3072 nt
	v_add_co_u32_e32 v38, vcc, 0x4000, v36
	v_add_u32_e32 v69, 0x1c00, v3
	s_nop 0
	v_addc_co_u32_e32 v39, vcc, 0, v37, vcc
	v_add_co_u32_e32 v40, vcc, 0x5000, v36
	v_lshl_add_u64 v[34:35], s[14:15], 0, v[34:35]
	s_nop 0
	v_addc_co_u32_e32 v41, vcc, 0, v37, vcc
	global_load_dword v55, v[38:39], off nt
	global_load_dword v56, v[38:39], off offset:1024 nt
	global_load_dword v57, v[38:39], off offset:2048 nt
	global_load_dword v58, v[38:39], off offset:3072 nt
	global_load_dword v59, v[40:41], off nt
	global_load_dword v60, v[40:41], off offset:1024 nt
	global_load_dword v61, v[40:41], off offset:2048 nt
	s_nop 0
	global_load_dword v40, v[40:41], off offset:3072 nt
	v_add_co_u32_e32 v38, vcc, 0x6000, v36
	s_nop 1
	v_addc_co_u32_e32 v39, vcc, 0, v37, vcc
	v_add_co_u32_e32 v36, vcc, 0x7000, v36
	s_nop 1
	v_addc_co_u32_e32 v37, vcc, 0, v37, vcc
	global_load_dword v41, v[38:39], off nt
	global_load_dword v62, v[38:39], off offset:1024 nt
	global_load_dword v63, v[38:39], off offset:2048 nt
	s_nop 0
	global_load_dword v38, v[38:39], off offset:3072 nt
	s_nop 0
	global_load_dword v39, v[36:37], off nt
	global_load_dword v64, v[36:37], off offset:1024 nt
	global_load_dword v65, v[36:37], off offset:2048 nt
	s_nop 0
	global_load_dword v36, v[36:37], off offset:3072 nt
	v_add_u32_e32 v37, 0xc00, v3
	s_waitcnt vmcnt(30)
; #define LAS __attribute__((address_space(3)))
; #define LDS_WAIT() asm volatile("s_waitcnt lgkmcnt(0)" ::: "memory")
; __device__ __forceinline__ unsigned pk2(float lo, float hi) { return f2bf(lo) | (f2bf(hi) << 16); }
;     ...
;     for (int i = 0; i < 32; ++i) scr[(2 * i + (lane >> 5)) * 33 + (lane & 31)] = tv_[i];
;     LDS_WAIT(); asm volatile("" ::: "memory");
;     const int c = lane & 7;
; #pragma unroll
;     for (int j = 0; j < 4; ++j) { const int n = (lane >> 3) + 8 * j; const LAS float* s = scr + (8 * c) * 33 + n;
;         v4u o; o.x = pk2(s[0 * 33], s[1 * 33]); o.y = pk2(s[2 * 33], s[3 * 33]); o.z = pk2(s[4 * 33], s[5 * 33]); o.w = pk2(s[6 * 33], s[7 * 33]);
;         *(v4u*)(WT + (size_t)(n0 + n) * ldw + koff + k0 + 8 * c) = o; }
;     LDS_WAIT(); asm volatile("" ::: "memory");
	ds_write2_b32 v3, v4, v21 offset1:66
	s_waitcnt vmcnt(28)
	ds_write2_b32 v3, v33, v42 offset0:132 offset1:198
	s_waitcnt vmcnt(26)
	ds_write2_b32 v31, v43, v44 offset0:8 offset1:74
	s_waitcnt vmcnt(24)
	ds_write2_b32 v31, v45, v46 offset0:140 offset1:206
	s_waitcnt vmcnt(22)
	ds_write2_b32 v32, v47, v48 offset0:16 offset1:82
	s_waitcnt vmcnt(20)
	ds_write2_b32 v32, v49, v50 offset0:148 offset1:214
	s_waitcnt vmcnt(18)
	ds_write2_b32 v37, v51, v52 offset0:24 offset1:90
	s_waitcnt vmcnt(16)
	ds_write2_b32 v37, v53, v54 offset0:156 offset1:222
	s_waitcnt vmcnt(14)
	ds_write2_b32 v66, v55, v56 offset0:32 offset1:98
	s_waitcnt vmcnt(12)
	ds_write2_b32 v66, v57, v58 offset0:164 offset1:230
	s_waitcnt vmcnt(10)
	ds_write2_b32 v67, v59, v60 offset0:40 offset1:106
	s_waitcnt vmcnt(8)
	ds_write2_b32 v67, v61, v40 offset0:172 offset1:238
	s_waitcnt vmcnt(6)
	ds_write2_b32 v68, v41, v62 offset0:48 offset1:114
	s_waitcnt vmcnt(4)
	ds_write2_b32 v68, v63, v38 offset0:180 offset1:246
	s_waitcnt vmcnt(2)
	ds_write2_b32 v69, v39, v64 offset0:56 offset1:122
	s_waitcnt vmcnt(0)
	ds_write2_b32 v69, v65, v36 offset0:188 offset1:254
	s_waitcnt lgkmcnt(0)
	v_lshlrev_b32_e32 v4, 1, v20
	v_lshl_add_u64 v[20:21], v[34:35], 0, v[4:5]
	v_lshlrev_b32_e32 v4, 1, v6
	v_lshl_add_u64 v[20:21], v[20:21], 0, v[4:5]
	ds_read_b32 v4, v23
	ds_read_b32 v33, v23 offset:132
	ds_read_b32 v35, v23 offset:264
	ds_read_b32 v36, v23 offset:396
	ds_read_b32 v37, v23 offset:528
	ds_read_b32 v38, v23 offset:660
	ds_read_b32 v39, v23 offset:792
	ds_read_b32 v40, v23 offset:924
	s_waitcnt lgkmcnt(0)
	v_bfe_u32 v34, v4, 16, 1
	v_add3_u32 v4, v4, v34, s41
	v_bfe_u32 v34, v33, 16, 1
	v_lshrrev_b32_e32 v4, 16, v4
	v_add3_u32 v33, v33, v34, s41
	v_and_or_b32 v34, v33, s42, v4
	v_bfe_u32 v4, v35, 16, 1
	v_add3_u32 v4, v35, v4, s41
	v_bfe_u32 v33, v36, 16, 1
	v_lshrrev_b32_e32 v4, 16, v4
	v_add3_u32 v33, v36, v33, s41
	v_and_or_b32 v35, v33, s42, v4
	v_bfe_u32 v4, v37, 16, 1
	v_add3_u32 v4, v37, v4, s41
	v_bfe_u32 v33, v38, 16, 1
	v_lshrrev_b32_e32 v4, 16, v4
	v_add3_u32 v33, v38, v33, s41
	v_and_or_b32 v36, v33, s42, v4
	v_bfe_u32 v4, v39, 16, 1
	v_add3_u32 v4, v39, v4, s41
	v_bfe_u32 v33, v40, 16, 1
	v_lshrrev_b32_e32 v4, 16, v4
	v_add3_u32 v33, v40, v33, s41
	v_and_or_b32 v37, v33, s42, v4
	v_lshl_add_u64 v[38:39], v[20:21], 0, v[8:9]
	global_store_dwordx4 v[38:39], v[34:37], off
	ds_read_b32 v4, v23 offset:32
	ds_read_b32 v33, v23 offset:164
	ds_read_b32 v35, v23 offset:296
	ds_read_b32 v36, v23 offset:428
	ds_read_b32 v37, v23 offset:560
	ds_read_b32 v38, v23 offset:692
	ds_read_b32 v39, v23 offset:824
	ds_read_b32 v40, v23 offset:956
	s_waitcnt lgkmcnt(0)
	v_bfe_u32 v34, v4, 16, 1
	v_add3_u32 v4, v4, v34, s41
	v_bfe_u32 v34, v33, 16, 1
	v_lshrrev_b32_e32 v4, 16, v4
	v_add3_u32 v33, v33, v34, s41
	v_and_or_b32 v34, v33, s42, v4
	v_bfe_u32 v4, v35, 16, 1
	v_add3_u32 v4, v35, v4, s41
	v_bfe_u32 v33, v36, 16, 1
	v_lshrrev_b32_e32 v4, 16, v4
	v_add3_u32 v33, v36, v33, s41
	v_and_or_b32 v35, v33, s42, v4
	v_bfe_u32 v4, v37, 16, 1
	v_add3_u32 v4, v37, v4, s41
	v_bfe_u32 v33, v38, 16, 1
	v_lshrrev_b32_e32 v4, 16, v4
	v_add3_u32 v33, v38, v33, s41
	v_and_or_b32 v36, v33, s42, v4
	v_bfe_u32 v4, v39, 16, 1
	v_add3_u32 v4, v39, v4, s41
	v_bfe_u32 v33, v40, 16, 1
	v_lshrrev_b32_e32 v4, 16, v4
	v_add3_u32 v33, v40, v33, s41
	v_and_or_b32 v37, v33, s42, v4
	v_lshl_add_u64 v[38:39], v[20:21], 0, v[10:11]
	global_store_dwordx4 v[38:39], v[34:37], off
	ds_read_b32 v4, v23 offset:64
	ds_read_b32 v33, v23 offset:196
	ds_read_b32 v35, v23 offset:328
	ds_read_b32 v36, v23 offset:460
	ds_read_b32 v37, v23 offset:592
	ds_read_b32 v38, v23 offset:724
	ds_read_b32 v39, v23 offset:856
	ds_read_b32 v40, v23 offset:988
	s_waitcnt lgkmcnt(0)
	v_bfe_u32 v34, v4, 16, 1
	v_add3_u32 v4, v4, v34, s41
	v_bfe_u32 v34, v33, 16, 1
	v_lshrrev_b32_e32 v4, 16, v4
	v_add3_u32 v33, v33, v34, s41
	v_and_or_b32 v34, v33, s42, v4
	v_bfe_u32 v4, v35, 16, 1
	v_add3_u32 v4, v35, v4, s41
	v_bfe_u32 v33, v36, 16, 1
	v_lshrrev_b32_e32 v4, 16, v4
	v_add3_u32 v33, v36, v33, s41
	v_and_or_b32 v35, v33, s42, v4
	v_bfe_u32 v4, v37, 16, 1
	v_add3_u32 v4, v37, v4, s41
	v_bfe_u32 v33, v38, 16, 1
	v_lshrrev_b32_e32 v4, 16, v4
	v_add3_u32 v33, v38, v33, s41
	v_and_or_b32 v36, v33, s42, v4
	v_bfe_u32 v4, v39, 16, 1
	v_add3_u32 v4, v39, v4, s41
	v_bfe_u32 v33, v40, 16, 1
	v_lshrrev_b32_e32 v4, 16, v4
	v_add3_u32 v33, v40, v33, s41
	v_and_or_b32 v37, v33, s42, v4
	v_lshl_add_u64 v[38:39], v[20:21], 0, v[12:13]
	global_store_dwordx4 v[38:39], v[34:37], off
	ds_read_b32 v4, v23 offset:96
	ds_read_b32 v33, v23 offset:228
	ds_read_b32 v35, v23 offset:360
	ds_read_b32 v36, v23 offset:492
	ds_read_b32 v37, v23 offset:624
	ds_read_b32 v38, v23 offset:756
	ds_read_b32 v39, v23 offset:888
	ds_read_b32 v40, v23 offset:1020
	s_waitcnt lgkmcnt(0)
	v_bfe_u32 v34, v4, 16, 1
	v_add3_u32 v4, v4, v34, s41
	v_bfe_u32 v34, v33, 16, 1
	v_lshrrev_b32_e32 v4, 16, v4
	v_add3_u32 v33, v33, v34, s41
	v_and_or_b32 v34, v33, s42, v4
	v_bfe_u32 v4, v35, 16, 1
	v_add3_u32 v4, v35, v4, s41
	v_bfe_u32 v33, v36, 16, 1
	v_lshrrev_b32_e32 v4, 16, v4
	v_add3_u32 v33, v36, v33, s41
	v_and_or_b32 v35, v33, s42, v4
	v_bfe_u32 v4, v37, 16, 1
	v_add3_u32 v4, v37, v4, s41
	v_bfe_u32 v33, v38, 16, 1
	v_lshrrev_b32_e32 v4, 16, v4
	v_add3_u32 v33, v38, v33, s41
	v_and_or_b32 v36, v33, s42, v4
	v_bfe_u32 v4, v39, 16, 1
	v_add3_u32 v4, v39, v4, s41
	v_bfe_u32 v33, v40, 16, 1
	v_lshrrev_b32_e32 v4, 16, v4
	v_add3_u32 v33, v40, v33, s41
	v_and_or_b32 v37, v33, s42, v4
	v_lshl_add_u64 v[20:21], v[20:21], 0, v[14:15]
	global_store_dwordx4 v[20:21], v[34:37], off
	s_waitcnt lgkmcnt(0)

; #define LAS __attribute__((address_space(3)))
; #define LDS_WAIT() asm volatile("s_waitcnt lgkmcnt(0)" ::: "memory")
; __device__ __forceinline__ unsigned pk2(float lo, float hi) { return f2bf(lo) | (f2bf(hi) << 16); }
;     if (ldw == 0) ldw = K;
;     const int nblk = N / 32, kb = item / nblk, nb = item % nblk, k0 = 64 * kb, n0 = 32 * nb;
;     float tv_[32];
; #pragma unroll
;     for (int i = 0; i < 32; ++i) tv_[i] = W[(size_t)(k0 + 2 * i + (lane >> 5)) * N + n0 + (lane & 31)];
; #pragma unroll
;     for (int i = 0; i < 32; ++i) scr[(2 * i + (lane >> 5)) * 33 + (lane & 31)] = tv_[i];
;     LDS_WAIT(); asm volatile("" ::: "memory");
;     const int c = lane & 7;
; #pragma unroll
;     for (int j = 0; j < 4; ++j) { const int n = (lane >> 3) + 8 * j; const LAS float* s = scr + (8 * c) * 33 + n;
;         v4u o; o.x = pk2(s[0 * 33], s[1 * 33]); o.y = pk2(s[2 * 33], s[3 * 33]); o.z = pk2(s[4 * 33], s[5 * 33]); o.w = pk2(s[6 * 33], s[7 * 33]);
;         *(v4u*)(WT + (size_t)(n0 + n) * ldw + koff + k0 + 8 * c) = o; }
;     LDS_WAIT(); asm volatile("" ::: "memory");
; }
; __device__ __forceinline__ void convert_range(LAS unsigned char* lds, const Params& p, const int lo, const int hi, const int gw, const int NGW) {
;     ...
;         if (r < I_PL) { const int mi = r / 32; r -= mi * 32; p0_transpose_item(p.in[7] + (size_t)mi * 65536, 256, 256, (bf16*)(ws + WS_POOLW) + (size_t)mi * 65536, scr, r, lane); continue; } r -= I_PL;
.LBB0_32:
	s_andn2_saveexec_b64 s[34:35], s[34:35]
	s_cbranch_execz .LBB0_34
	v_add_u32_e32 v4, 0x200, v27
	v_lshrrev_b32_e32 v4, 5, v4
	v_readlane_b32 s60, v251, 21
	v_lshlrev_b64 v[20:21], 18, v[4:5]
	v_readlane_b32 s74, v251, 35
	v_readlane_b32 s75, v251, 36
	v_and_b32_e32 v54, 0xe0, v30
	v_lshlrev_b64 v[34:35], 17, v[4:5]
	v_lshl_add_u64 v[20:21], s[74:75], 0, v[20:21]
	v_and_b32_e32 v33, 0xc0, v29
	v_lshlrev_b32_e32 v4, 2, v54
	v_or_b32_e32 v36, v33, v1
	v_lshl_add_u64 v[20:21], v[20:21], 0, v[4:5]
	v_lshlrev_b32_e32 v4, 2, v2
	v_lshl_add_u64 v[20:21], v[20:21], 0, v[4:5]
	v_lshlrev_b32_e32 v4, 10, v36
	v_lshl_add_u64 v[20:21], v[20:21], 0, v[4:5]
	s_movk_i32 s36, 0x1000
	v_add_co_u32_e32 v36, vcc, s36, v20
	s_movk_i32 s36, 0x2000
	s_nop 0
	v_addc_co_u32_e32 v37, vcc, 0, v21, vcc
	v_add_co_u32_e32 v38, vcc, s36, v20
	s_movk_i32 s36, 0x3000
	s_nop 0
	v_addc_co_u32_e32 v39, vcc, 0, v21, vcc
	v_add_co_u32_e32 v40, vcc, s36, v20
	s_movk_i32 s36, 0x5000
	s_nop 0
	v_addc_co_u32_e32 v41, vcc, 0, v21, vcc
	v_add_co_u32_e32 v42, vcc, s40, v20
	v_readlane_b32 s61, v251, 22
	s_nop 0
	v_addc_co_u32_e32 v43, vcc, 0, v21, vcc
	global_load_dword v4, v[38:39], off offset:-4096 nt
	global_load_dword v55, v[38:39], off nt
	global_load_dword v56, v[38:39], off offset:2048 nt
	global_load_dword v57, v[42:43], off offset:-4096 nt
	global_load_dword v58, v[42:43], off nt
	v_add_co_u32_e32 v38, vcc, s36, v20
	s_movk_i32 s36, 0x6000
	s_nop 0
	v_addc_co_u32_e32 v39, vcc, 0, v21, vcc
	v_add_co_u32_e32 v44, vcc, s36, v20
	s_movk_i32 s36, 0x7000
	s_nop 0
	v_addc_co_u32_e32 v45, vcc, 0, v21, vcc
	v_add_co_u32_e32 v46, vcc, s36, v20
	s_mov_b32 s36, 0x9000
	s_nop 0
	v_addc_co_u32_e32 v47, vcc, 0, v21, vcc
	v_add_co_u32_e32 v48, vcc, s43, v20
	v_readlane_b32 s62, v251, 23
	s_nop 0
	v_addc_co_u32_e32 v49, vcc, 0, v21, vcc
	v_add_co_u32_e32 v50, vcc, s36, v20
	s_mov_b32 s36, 0xb000
	s_nop 0
	v_addc_co_u32_e32 v51, vcc, 0, v21, vcc
	v_add_co_u32_e32 v52, vcc, s44, v20
	v_readlane_b32 s63, v251, 24
	s_nop 0
	v_addc_co_u32_e32 v53, vcc, 0, v21, vcc
	global_load_dword v59, v[42:43], off offset:2048 nt
	global_load_dword v60, v[44:45], off offset:-4096 nt
	global_load_dword v61, v[44:45], off nt
	global_load_dword v62, v[44:45], off offset:2048 nt
	global_load_dword v63, v[48:49], off offset:-4096 nt
	global_load_dword v64, v[48:49], off nt
	s_nop 0
	global_load_dword v48, v[48:49], off offset:2048 nt
	s_nop 0
	global_load_dword v49, v[52:53], off offset:-4096 nt
	v_add_co_u32_e32 v42, vcc, s36, v20
	s_mov_b32 s36, 0xd000
	s_nop 0
	v_addc_co_u32_e32 v43, vcc, 0, v21, vcc
	v_add_co_u32_e32 v44, vcc, s45, v20
	global_load_dword v65, v[20:21], off nt
	global_load_dword v66, v[20:21], off offset:2048 nt
	global_load_dword v67, v[36:37], off offset:2048 nt
	s_nop 0
	global_load_dword v40, v[40:41], off offset:2048 nt
	s_nop 0
	global_load_dword v41, v[38:39], off offset:2048 nt
	s_nop 0
	global_load_dword v46, v[46:47], off offset:2048 nt
	s_nop 0
	global_load_dword v47, v[50:51], off offset:2048 nt
	s_nop 0
	global_load_dword v42, v[42:43], off offset:2048 nt
	v_addc_co_u32_e32 v45, vcc, 0, v21, vcc
	v_add_co_u32_e32 v36, vcc, s36, v20
	s_mov_b32 s36, 0xe000
	s_nop 0
	v_addc_co_u32_e32 v37, vcc, 0, v21, vcc
	v_add_co_u32_e32 v38, vcc, s36, v20
	s_mov_b32 s36, 0xf000
	s_nop 0
	v_addc_co_u32_e32 v39, vcc, 0, v21, vcc
	v_add_co_u32_e32 v20, vcc, s36, v20
	global_load_dword v36, v[36:37], off offset:2048 nt
	s_nop 0
	global_load_dword v37, v[52:53], off nt
	global_load_dword v43, v[52:53], off offset:2048 nt
	global_load_dword v50, v[44:45], off offset:-4096 nt
	global_load_dword v51, v[44:45], off nt
	s_nop 0
	global_load_dword v44, v[44:45], off offset:2048 nt
	s_nop 0
	global_load_dword v45, v[38:39], off offset:-4096 nt
	global_load_dword v52, v[38:39], off nt
	s_nop 0
	global_load_dword v38, v[38:39], off offset:2048 nt
	v_addc_co_u32_e32 v21, vcc, 0, v21, vcc
	global_load_dword v39, v[20:21], off nt
	global_load_dword v53, v[20:21], off offset:2048 nt
	v_lshl_add_u64 v[20:21], s[16:17], 0, v[34:35]
	v_readlane_b32 s64, v251, 25
	v_readlane_b32 s65, v251, 26
	v_readlane_b32 s66, v251, 27
	v_readlane_b32 s67, v251, 28
	v_readlane_b32 s68, v251, 29
	v_readlane_b32 s69, v251, 30
	v_readlane_b32 s70, v251, 31
	v_readlane_b32 s71, v251, 32
	s_waitcnt vmcnt(17)
	ds_write2_b32 v3, v65, v66 offset1:66
	s_waitcnt vmcnt(16)
	ds_write2_b32 v3, v4, v67 offset0:132 offset1:198
	ds_write2_b32 v31, v55, v56 offset0:8 offset1:74
	s_waitcnt vmcnt(15)
	ds_write2_b32 v31, v57, v40 offset0:140 offset1:206
	ds_write2_b32 v32, v58, v59 offset0:16 offset1:82
	s_waitcnt vmcnt(14)
	ds_write2_b32 v32, v60, v41 offset0:148 offset1:214
	v_add_u32_e32 v4, 0xc00, v3
	ds_write2_b32 v4, v61, v62 offset0:24 offset1:90
	s_waitcnt vmcnt(13)
	ds_write2_b32 v4, v63, v46 offset0:156 offset1:222
	v_add_u32_e32 v4, 0x1000, v3
	ds_write2_b32 v4, v64, v48 offset0:32 offset1:98
	s_waitcnt vmcnt(12)
	ds_write2_b32 v4, v49, v47 offset0:164 offset1:230
	v_add_u32_e32 v4, 0x1400, v3
	s_waitcnt vmcnt(8)
	ds_write2_b32 v4, v37, v43 offset0:40 offset1:106
	s_waitcnt vmcnt(7)
; #define LAS __attribute__((address_space(3)))
; #define LDS_WAIT() asm volatile("s_waitcnt lgkmcnt(0)" ::: "memory")
; __device__ __forceinline__ unsigned pk2(float lo, float hi) { return f2bf(lo) | (f2bf(hi) << 16); }
;     ...
;     for (int i = 0; i < 32; ++i) scr[(2 * i + (lane >> 5)) * 33 + (lane & 31)] = tv_[i];
;     LDS_WAIT(); asm volatile("" ::: "memory");
;     const int c = lane & 7;
; #pragma unroll
;     for (int j = 0; j < 4; ++j) { const int n = (lane >> 3) + 8 * j; const LAS float* s = scr + (8 * c) * 33 + n;
;         v4u o; o.x = pk2(s[0 * 33], s[1 * 33]); o.y = pk2(s[2 * 33], s[3 * 33]); o.z = pk2(s[4 * 33], s[5 * 33]); o.w = pk2(s[6 * 33], s[7 * 33]);
;         *(v4u*)(WT + (size_t)(n0 + n) * ldw + koff + k0 + 8 * c) = o; }
;     LDS_WAIT(); asm volatile("" ::: "memory");
	ds_write2_b32 v4, v50, v42 offset0:172 offset1:238
	v_add_u32_e32 v4, 0x1800, v3
	s_waitcnt vmcnt(5)
	ds_write2_b32 v4, v51, v44 offset0:48 offset1:114
	s_waitcnt vmcnt(4)
	ds_write2_b32 v4, v45, v36 offset0:180 offset1:246
	v_add_u32_e32 v4, 0x1c00, v3
	s_waitcnt vmcnt(2)
	ds_write2_b32 v4, v52, v38 offset0:56 offset1:122
	s_waitcnt vmcnt(0)
	ds_write2_b32 v4, v39, v53 offset0:188 offset1:254
	s_waitcnt lgkmcnt(0)
	v_lshlrev_b32_e32 v4, 1, v33
	v_lshl_add_u64 v[20:21], v[20:21], 0, v[4:5]
	v_lshlrev_b32_e32 v4, 1, v6
	v_lshl_add_u64 v[20:21], v[20:21], 0, v[4:5]
	ds_read_b32 v4, v23
	ds_read_b32 v33, v23 offset:132
	ds_read_b32 v35, v23 offset:264
	ds_read_b32 v36, v23 offset:396
	ds_read_b32 v37, v23 offset:528
	ds_read_b32 v38, v23 offset:660
	ds_read_b32 v39, v23 offset:792
	ds_read_b32 v40, v23 offset:924
	s_waitcnt lgkmcnt(0)
	v_bfe_u32 v34, v4, 16, 1
	v_add3_u32 v4, v4, v34, s41
	v_bfe_u32 v34, v33, 16, 1
	v_lshrrev_b32_e32 v4, 16, v4
	v_add3_u32 v33, v33, v34, s41
	v_and_or_b32 v34, v33, s42, v4
	v_bfe_u32 v4, v35, 16, 1
	v_add3_u32 v4, v35, v4, s41
	v_bfe_u32 v33, v36, 16, 1
	v_lshrrev_b32_e32 v4, 16, v4
	v_add3_u32 v33, v36, v33, s41
	v_and_or_b32 v35, v33, s42, v4
	v_bfe_u32 v4, v37, 16, 1
	v_add3_u32 v4, v37, v4, s41
	v_bfe_u32 v33, v38, 16, 1
	v_lshrrev_b32_e32 v4, 16, v4
	v_add3_u32 v33, v38, v33, s41
	v_and_or_b32 v36, v33, s42, v4
	v_bfe_u32 v4, v39, 16, 1
	v_add3_u32 v4, v39, v4, s41
	v_bfe_u32 v33, v40, 16, 1
	v_lshrrev_b32_e32 v4, 16, v4
	v_add3_u32 v33, v40, v33, s41
	v_and_or_b32 v37, v33, s42, v4
	v_or_b32_e32 v4, v54, v7
	v_lshlrev_b32_e32 v4, 9, v4
	v_lshl_add_u64 v[38:39], v[20:21], 0, v[4:5]
	global_store_dwordx4 v[38:39], v[34:37], off
	ds_read_b32 v4, v23 offset:32
	ds_read_b32 v33, v23 offset:164
	ds_read_b32 v35, v23 offset:296
	ds_read_b32 v36, v23 offset:428
	ds_read_b32 v37, v23 offset:560
	ds_read_b32 v38, v23 offset:692
	ds_read_b32 v39, v23 offset:824
	ds_read_b32 v40, v23 offset:956
	s_waitcnt lgkmcnt(0)
	v_bfe_u32 v34, v4, 16, 1
	v_add3_u32 v4, v4, v34, s41
	v_bfe_u32 v34, v33, 16, 1
	v_lshrrev_b32_e32 v4, 16, v4
	v_add3_u32 v33, v33, v34, s41
	v_and_or_b32 v34, v33, s42, v4
	v_bfe_u32 v4, v35, 16, 1
	v_add3_u32 v4, v35, v4, s41
	v_bfe_u32 v33, v36, 16, 1
	v_lshrrev_b32_e32 v4, 16, v4
	v_add3_u32 v33, v36, v33, s41
	v_and_or_b32 v35, v33, s42, v4
	v_bfe_u32 v4, v37, 16, 1
	v_add3_u32 v4, v37, v4, s41
	v_bfe_u32 v33, v38, 16, 1
	v_lshrrev_b32_e32 v4, 16, v4
	v_add3_u32 v33, v38, v33, s41
	v_and_or_b32 v36, v33, s42, v4
	v_bfe_u32 v4, v39, 16, 1
	v_add3_u32 v4, v39, v4, s41
	v_bfe_u32 v33, v40, 16, 1
	v_lshrrev_b32_e32 v4, 16, v4
	v_add3_u32 v33, v40, v33, s41
	v_and_or_b32 v37, v33, s42, v4
	v_or_b32_e32 v4, v54, v24
	v_lshlrev_b32_e32 v4, 9, v4
	v_lshl_add_u64 v[38:39], v[20:21], 0, v[4:5]
	global_store_dwordx4 v[38:39], v[34:37], off
	ds_read_b32 v4, v23 offset:64
	ds_read_b32 v33, v23 offset:196
	ds_read_b32 v35, v23 offset:328
	ds_read_b32 v36, v23 offset:460
	ds_read_b32 v37, v23 offset:592
	ds_read_b32 v38, v23 offset:724
	ds_read_b32 v39, v23 offset:856
	ds_read_b32 v40, v23 offset:988
	s_waitcnt lgkmcnt(0)
	v_bfe_u32 v34, v4, 16, 1
	v_add3_u32 v4, v4, v34, s41
	v_bfe_u32 v34, v33, 16, 1
	v_lshrrev_b32_e32 v4, 16, v4
	v_add3_u32 v33, v33, v34, s41
	v_and_or_b32 v34, v33, s42, v4
	v_bfe_u32 v4, v35, 16, 1
	v_add3_u32 v4, v35, v4, s41
	v_bfe_u32 v33, v36, 16, 1
	v_lshrrev_b32_e32 v4, 16, v4
	v_add3_u32 v33, v36, v33, s41
	v_and_or_b32 v35, v33, s42, v4
	v_bfe_u32 v4, v37, 16, 1
	v_add3_u32 v4, v37, v4, s41
	v_bfe_u32 v33, v38, 16, 1
	v_lshrrev_b32_e32 v4, 16, v4
	v_add3_u32 v33, v38, v33, s41
	v_and_or_b32 v36, v33, s42, v4
	v_bfe_u32 v4, v39, 16, 1
	v_add3_u32 v4, v39, v4, s41
	v_bfe_u32 v33, v40, 16, 1
	v_lshrrev_b32_e32 v4, 16, v4
	v_add3_u32 v33, v40, v33, s41
	v_and_or_b32 v37, v33, s42, v4
	v_or_b32_e32 v4, v54, v25
	v_lshlrev_b32_e32 v4, 9, v4
	v_lshl_add_u64 v[38:39], v[20:21], 0, v[4:5]
	global_store_dwordx4 v[38:39], v[34:37], off
	ds_read_b32 v4, v23 offset:96
	ds_read_b32 v33, v23 offset:228
	ds_read_b32 v35, v23 offset:360
	ds_read_b32 v36, v23 offset:492
	ds_read_b32 v37, v23 offset:624
	ds_read_b32 v38, v23 offset:756
	ds_read_b32 v39, v23 offset:888
	ds_read_b32 v40, v23 offset:1020
	s_waitcnt lgkmcnt(0)
	v_bfe_u32 v34, v4, 16, 1
	v_add3_u32 v4, v4, v34, s41
	v_bfe_u32 v34, v33, 16, 1
	v_lshrrev_b32_e32 v4, 16, v4
	v_add3_u32 v33, v33, v34, s41
	v_and_or_b32 v34, v33, s42, v4
	v_bfe_u32 v4, v35, 16, 1
	v_add3_u32 v4, v35, v4, s41
	v_bfe_u32 v33, v36, 16, 1
	v_lshrrev_b32_e32 v4, 16, v4
	v_add3_u32 v33, v36, v33, s41
	v_and_or_b32 v35, v33, s42, v4
	v_bfe_u32 v4, v37, 16, 1
	v_add3_u32 v4, v37, v4, s41
	v_bfe_u32 v33, v38, 16, 1
	v_lshrrev_b32_e32 v4, 16, v4
	v_add3_u32 v33, v38, v33, s41
	v_and_or_b32 v36, v33, s42, v4
	v_bfe_u32 v4, v39, 16, 1
	v_add3_u32 v4, v39, v4, s41
	v_bfe_u32 v33, v40, 16, 1
	v_lshrrev_b32_e32 v4, 16, v4
	v_add3_u32 v33, v40, v33, s41
	v_and_or_b32 v37, v33, s42, v4
	v_or_b32_e32 v4, v54, v26
	v_lshlrev_b32_e32 v4, 9, v4
	v_lshl_add_u64 v[20:21], v[20:21], 0, v[4:5]
	global_store_dwordx4 v[20:21], v[34:37], off
	s_waitcnt lgkmcnt(0)
	v_readlane_b32 s72, v251, 33
	v_readlane_b32 s73, v251, 34

; #define LAS __attribute__((address_space(3)))
; #define LDS_WAIT() asm volatile("s_waitcnt lgkmcnt(0)" ::: "memory")
; __device__ __forceinline__ unsigned pk2(float lo, float hi) { return f2bf(lo) | (f2bf(hi) << 16); }
;     if (ldw == 0) ldw = K;
;     const int nblk = N / 32, kb = item / nblk, nb = item % nblk, k0 = 64 * kb, n0 = 32 * nb;
;     float tv_[32];
; #pragma unroll
;     for (int i = 0; i < 32; ++i) tv_[i] = W[(size_t)(k0 + 2 * i + (lane >> 5)) * N + n0 + (lane & 31)];
; #pragma unroll
;     for (int i = 0; i < 32; ++i) scr[(2 * i + (lane >> 5)) * 33 + (lane & 31)] = tv_[i];
;     LDS_WAIT(); asm volatile("" ::: "memory");
;     const int c = lane & 7;
; #pragma unroll
;     for (int j = 0; j < 4; ++j) { const int n = (lane >> 3) + 8 * j; const LAS float* s = scr + (8 * c) * 33 + n;
;         v4u o; o.x = pk2(s[0 * 33], s[1 * 33]); o.y = pk2(s[2 * 33], s[3 * 33]); o.z = pk2(s[4 * 33], s[5 * 33]); o.w = pk2(s[6 * 33], s[7 * 33]);
;         *(v4u*)(WT + (size_t)(n0 + n) * ldw + koff + k0 + 8 * c) = o; }
;     LDS_WAIT(); asm volatile("" ::: "memory");
; }
; __device__ __forceinline__ void convert_range(LAS unsigned char* lds, const Params& p, const int lo, const int hi, const int gw, const int NGW) {
;     ...
;         if (r < 2 * I_OUT) { const int l = r / I_OUT; r -= l * I_OUT; p0_transpose_item(p.in[18] + (size_t)l * DM * DM, DM, DM, (bf16*)(ws + WS_WOUT + l * SZ_WOUT), scr, r, lane); continue; } r -= 2 * I_OUT;
.LBB0_35:
	s_andn2_saveexec_b64 s[30:31], s[30:31]
	s_cbranch_execz .LBB0_37
	v_add_u32_e32 v4, 0x1200, v27
	v_lshrrev_b32_e32 v4, 11, v4
	v_readlane_b32 s68, v251, 9
	v_lshlrev_b64 v[34:35], 24, v[4:5]
	v_readlane_b32 s72, v251, 13
	v_readlane_b32 s73, v251, 14
	v_and_b32_e32 v52, 0x7e0, v30
	v_lshlrev_b64 v[36:37], 23, v[4:5]
	v_lshl_add_u64 v[34:35], s[72:73], 0, v[34:35]
	v_and_b32_e32 v33, 0x7c0, v20
	v_lshlrev_b32_e32 v4, 2, v52
	v_or_b32_e32 v38, v33, v1
	v_lshl_add_u64 v[20:21], v[34:35], 0, v[4:5]
	v_lshlrev_b32_e32 v4, 2, v2
	v_lshl_add_u64 v[20:21], v[20:21], 0, v[4:5]
	v_lshlrev_b32_e32 v4, 13, v38
	v_lshl_add_u64 v[20:21], v[20:21], 0, v[4:5]
	v_add_co_u32_e32 v34, vcc, s40, v20
	v_readlane_b32 s69, v251, 10
	s_nop 0
	v_addc_co_u32_e32 v35, vcc, 0, v21, vcc
	v_add_co_u32_e32 v38, vcc, s43, v20
	v_readlane_b32 s70, v251, 11
	s_nop 0
	v_addc_co_u32_e32 v39, vcc, 0, v21, vcc
	v_add_co_u32_e32 v40, vcc, s45, v20
	v_readlane_b32 s71, v251, 12
	s_nop 0
	v_addc_co_u32_e32 v41, vcc, 0, v21, vcc
	v_add_co_u32_e32 v42, vcc, s47, v20
	v_readlane_b32 s74, v251, 15
	s_nop 0
	v_addc_co_u32_e32 v43, vcc, 0, v21, vcc
	v_add_co_u32_e32 v44, vcc, s48, v20
	v_readlane_b32 s75, v251, 16
	s_nop 0
	v_addc_co_u32_e32 v45, vcc, 0, v21, vcc
	v_add_co_u32_e32 v46, vcc, s49, v20
	s_nop 1
	v_addc_co_u32_e32 v47, vcc, 0, v21, vcc
	v_add_co_u32_e32 v48, vcc, s50, v20
	s_nop 1
	v_addc_co_u32_e32 v49, vcc, 0, v21, vcc
	global_load_dword v4, v[20:21], off nt
	global_load_dword v53, v[34:35], off nt
	global_load_dword v54, v[38:39], off nt
	global_load_dword v55, v[40:41], off nt
	global_load_dword v56, v[42:43], off nt
	global_load_dword v57, v[44:45], off nt
	global_load_dword v58, v[46:47], off nt
	global_load_dword v59, v[48:49], off nt
	v_add_co_u32_e32 v34, vcc, s51, v20
	s_nop 1
	v_addc_co_u32_e32 v35, vcc, 0, v21, vcc
	v_add_co_u32_e32 v38, vcc, s52, v20
	s_nop 1
	v_addc_co_u32_e32 v39, vcc, 0, v21, vcc
	v_add_co_u32_e32 v40, vcc, s53, v20
	s_nop 1
	v_addc_co_u32_e32 v41, vcc, 0, v21, vcc
	v_add_co_u32_e32 v42, vcc, s54, v20
	s_nop 1
	v_addc_co_u32_e32 v43, vcc, 0, v21, vcc
	v_add_co_u32_e32 v44, vcc, s55, v20
	s_nop 1
	v_addc_co_u32_e32 v45, vcc, 0, v21, vcc
	v_add_co_u32_e32 v46, vcc, s56, v20
	s_nop 1
	v_addc_co_u32_e32 v47, vcc, 0, v21, vcc
	v_add_co_u32_e32 v48, vcc, s57, v20
	s_nop 1
	v_addc_co_u32_e32 v49, vcc, 0, v21, vcc
	v_add_co_u32_e32 v50, vcc, s58, v20
	s_nop 1
	v_addc_co_u32_e32 v51, vcc, 0, v21, vcc
	global_load_dword v60, v[34:35], off nt
	global_load_dword v61, v[38:39], off nt
	global_load_dword v62, v[40:41], off nt
	global_load_dword v63, v[42:43], off nt
	global_load_dword v64, v[44:45], off nt
	global_load_dword v65, v[46:47], off nt
	global_load_dword v66, v[48:49], off nt
	global_load_dword v67, v[50:51], off nt
	v_add_co_u32_e32 v34, vcc, s59, v20
	s_nop 1
	v_addc_co_u32_e32 v35, vcc, 0, v21, vcc
	v_add_co_u32_e32 v38, vcc, s76, v20
	s_nop 1
	v_addc_co_u32_e32 v39, vcc, 0, v21, vcc
	v_add_co_u32_e32 v40, vcc, s77, v20
	s_nop 1
	v_addc_co_u32_e32 v41, vcc, 0, v21, vcc
	v_add_co_u32_e32 v42, vcc, s78, v20
	s_nop 1
	v_addc_co_u32_e32 v43, vcc, 0, v21, vcc
	v_add_co_u32_e32 v44, vcc, s79, v20
	s_nop 1
	v_addc_co_u32_e32 v45, vcc, 0, v21, vcc
	v_add_co_u32_e32 v46, vcc, s80, v20
	s_nop 1
	v_addc_co_u32_e32 v47, vcc, 0, v21, vcc
	v_add_co_u32_e32 v48, vcc, s81, v20
	s_nop 1
	v_addc_co_u32_e32 v49, vcc, 0, v21, vcc
	v_add_co_u32_e32 v50, vcc, s82, v20
	s_nop 1
	v_addc_co_u32_e32 v51, vcc, 0, v21, vcc
	global_load_dword v68, v[34:35], off nt
	global_load_dword v69, v[38:39], off nt
	global_load_dword v70, v[40:41], off nt
	global_load_dword v71, v[42:43], off nt
	global_load_dword v72, v[44:45], off nt
	global_load_dword v73, v[46:47], off nt
	global_load_dword v74, v[48:49], off nt
	s_nop 0
	global_load_dword v50, v[50:51], off nt
	v_add_co_u32_e32 v34, vcc, s83, v20
	s_nop 1
	v_addc_co_u32_e32 v35, vcc, 0, v21, vcc
	v_add_co_u32_e32 v38, vcc, s84, v20
	s_nop 1
	v_addc_co_u32_e32 v39, vcc, 0, v21, vcc
	v_add_co_u32_e32 v40, vcc, s85, v20
	s_nop 1
	v_addc_co_u32_e32 v41, vcc, 0, v21, vcc
	v_add_co_u32_e32 v42, vcc, s86, v20
	s_nop 1
	v_addc_co_u32_e32 v43, vcc, 0, v21, vcc
	v_add_co_u32_e32 v44, vcc, s87, v20
	s_nop 1
	v_addc_co_u32_e32 v45, vcc, 0, v21, vcc
	v_add_co_u32_e32 v46, vcc, s88, v20
	s_nop 1
	v_addc_co_u32_e32 v47, vcc, 0, v21, vcc
	v_add_co_u32_e32 v48, vcc, s89, v20
	s_nop 1
	v_addc_co_u32_e32 v49, vcc, 0, v21, vcc
	v_add_co_u32_e32 v20, vcc, s90, v20
	s_nop 1
	v_addc_co_u32_e32 v21, vcc, 0, v21, vcc
	global_load_dword v34, v[34:35], off nt
	s_nop 0
	global_load_dword v35, v[38:39], off nt
	s_nop 0
	global_load_dword v38, v[40:41], off nt
	global_load_dword v39, v[42:43], off nt
	s_nop 0
	global_load_dword v40, v[44:45], off nt
	global_load_dword v41, v[46:47], off nt
	global_load_dword v42, v[48:49], off nt
	global_load_dword v43, v[20:21], off nt
	s_waitcnt vmcnt(30)
	ds_write2_b32 v3, v4, v53 offset1:66
	s_waitcnt vmcnt(28)
	ds_write2_b32 v3, v54, v55 offset0:132 offset1:198
	s_waitcnt vmcnt(26)
	ds_write2_b32 v31, v56, v57 offset0:8 offset1:74
	s_waitcnt vmcnt(24)
	ds_write2_b32 v31, v58, v59 offset0:140 offset1:206
	s_waitcnt vmcnt(22)
	ds_write2_b32 v32, v60, v61 offset0:16 offset1:82
	s_waitcnt vmcnt(20)
	ds_write2_b32 v32, v62, v63 offset0:148 offset1:214
	v_add_u32_e32 v4, 0xc00, v3
	s_waitcnt vmcnt(18)
	ds_write2_b32 v4, v64, v65 offset0:24 offset1:90
	s_waitcnt vmcnt(16)
	ds_write2_b32 v4, v66, v67 offset0:156 offset1:222
	v_add_u32_e32 v4, 0x1000, v3
	s_waitcnt vmcnt(14)
; #define LAS __attribute__((address_space(3)))
; #define LDS_WAIT() asm volatile("s_waitcnt lgkmcnt(0)" ::: "memory")
; __device__ __forceinline__ unsigned pk2(float lo, float hi) { return f2bf(lo) | (f2bf(hi) << 16); }
;     ...
;     for (int i = 0; i < 32; ++i) scr[(2 * i + (lane >> 5)) * 33 + (lane & 31)] = tv_[i];
;     LDS_WAIT(); asm volatile("" ::: "memory");
;     const int c = lane & 7;
; #pragma unroll
;     for (int j = 0; j < 4; ++j) { const int n = (lane >> 3) + 8 * j; const LAS float* s = scr + (8 * c) * 33 + n;
;         v4u o; o.x = pk2(s[0 * 33], s[1 * 33]); o.y = pk2(s[2 * 33], s[3 * 33]); o.z = pk2(s[4 * 33], s[5 * 33]); o.w = pk2(s[6 * 33], s[7 * 33]);
;         *(v4u*)(WT + (size_t)(n0 + n) * ldw + koff + k0 + 8 * c) = o; }
;     LDS_WAIT(); asm volatile("" ::: "memory");
	ds_write2_b32 v4, v68, v69 offset0:32 offset1:98
	s_waitcnt vmcnt(12)
	ds_write2_b32 v4, v70, v71 offset0:164 offset1:230
	v_add_u32_e32 v4, 0x1400, v3
	s_waitcnt vmcnt(10)
	ds_write2_b32 v4, v72, v73 offset0:40 offset1:106
	s_waitcnt vmcnt(8)
	ds_write2_b32 v4, v74, v50 offset0:172 offset1:238
	v_add_u32_e32 v4, 0x1800, v3
	s_waitcnt vmcnt(6)
	ds_write2_b32 v4, v34, v35 offset0:48 offset1:114
	s_waitcnt vmcnt(4)
	ds_write2_b32 v4, v38, v39 offset0:180 offset1:246
	v_add_u32_e32 v4, 0x1c00, v3
	s_waitcnt vmcnt(2)
	ds_write2_b32 v4, v40, v41 offset0:56 offset1:122
	s_waitcnt vmcnt(0)
	ds_write2_b32 v4, v42, v43 offset0:188 offset1:254
	v_lshl_add_u64 v[20:21], s[18:19], 0, v[36:37]
	s_waitcnt lgkmcnt(0)
	v_lshlrev_b32_e32 v4, 1, v33
	v_lshl_add_u64 v[20:21], v[20:21], 0, v[4:5]
	v_lshlrev_b32_e32 v4, 1, v6
	v_lshl_add_u64 v[20:21], v[20:21], 0, v[4:5]
	ds_read_b32 v4, v23
	ds_read_b32 v33, v23 offset:132
	ds_read_b32 v35, v23 offset:264
	ds_read_b32 v36, v23 offset:396
	ds_read_b32 v37, v23 offset:528
	ds_read_b32 v38, v23 offset:660
	ds_read_b32 v39, v23 offset:792
	ds_read_b32 v40, v23 offset:924
	s_waitcnt lgkmcnt(0)
	v_bfe_u32 v34, v4, 16, 1
	v_add3_u32 v4, v4, v34, s41
	v_bfe_u32 v34, v33, 16, 1
	v_lshrrev_b32_e32 v4, 16, v4
	v_add3_u32 v33, v33, v34, s41
	v_and_or_b32 v34, v33, s42, v4
	v_bfe_u32 v4, v35, 16, 1
	v_add3_u32 v4, v35, v4, s41
	v_bfe_u32 v33, v36, 16, 1
	v_lshrrev_b32_e32 v4, 16, v4
	v_add3_u32 v33, v36, v33, s41
	v_and_or_b32 v35, v33, s42, v4
	v_bfe_u32 v4, v37, 16, 1
	v_add3_u32 v4, v37, v4, s41
	v_bfe_u32 v33, v38, 16, 1
	v_lshrrev_b32_e32 v4, 16, v4
	v_add3_u32 v33, v38, v33, s41
	v_and_or_b32 v36, v33, s42, v4
	v_bfe_u32 v4, v39, 16, 1
	v_add3_u32 v4, v39, v4, s41
	v_bfe_u32 v33, v40, 16, 1
	v_lshrrev_b32_e32 v4, 16, v4
	v_add3_u32 v33, v40, v33, s41
	v_and_or_b32 v37, v33, s42, v4
	v_or_b32_e32 v4, v52, v7
	v_lshlrev_b32_e32 v4, 12, v4
	v_lshl_add_u64 v[38:39], v[20:21], 0, v[4:5]
	global_store_dwordx4 v[38:39], v[34:37], off
	ds_read_b32 v4, v23 offset:32
	ds_read_b32 v33, v23 offset:164
	ds_read_b32 v35, v23 offset:296
	ds_read_b32 v36, v23 offset:428
	ds_read_b32 v37, v23 offset:560
	ds_read_b32 v38, v23 offset:692
	ds_read_b32 v39, v23 offset:824
	ds_read_b32 v40, v23 offset:956
	s_waitcnt lgkmcnt(0)
	v_bfe_u32 v34, v4, 16, 1
	v_add3_u32 v4, v4, v34, s41
	v_bfe_u32 v34, v33, 16, 1
	v_lshrrev_b32_e32 v4, 16, v4
	v_add3_u32 v33, v33, v34, s41
	v_and_or_b32 v34, v33, s42, v4
	v_bfe_u32 v4, v35, 16, 1
	v_add3_u32 v4, v35, v4, s41
	v_bfe_u32 v33, v36, 16, 1
	v_lshrrev_b32_e32 v4, 16, v4
	v_add3_u32 v33, v36, v33, s41
	v_and_or_b32 v35, v33, s42, v4
	v_bfe_u32 v4, v37, 16, 1
	v_add3_u32 v4, v37, v4, s41
	v_bfe_u32 v33, v38, 16, 1
	v_lshrrev_b32_e32 v4, 16, v4
	v_add3_u32 v33, v38, v33, s41
	v_and_or_b32 v36, v33, s42, v4
	v_bfe_u32 v4, v39, 16, 1
	v_add3_u32 v4, v39, v4, s41
	v_bfe_u32 v33, v40, 16, 1
	v_lshrrev_b32_e32 v4, 16, v4
	v_add3_u32 v33, v40, v33, s41
	v_and_or_b32 v37, v33, s42, v4
	v_or_b32_e32 v4, v52, v24
	v_lshlrev_b32_e32 v4, 12, v4
	v_lshl_add_u64 v[38:39], v[20:21], 0, v[4:5]
	global_store_dwordx4 v[38:39], v[34:37], off
	ds_read_b32 v4, v23 offset:64
	ds_read_b32 v33, v23 offset:196
	ds_read_b32 v35, v23 offset:328
	ds_read_b32 v36, v23 offset:460
	ds_read_b32 v37, v23 offset:592
	ds_read_b32 v38, v23 offset:724
	ds_read_b32 v39, v23 offset:856
	ds_read_b32 v40, v23 offset:988
	s_waitcnt lgkmcnt(0)
	v_bfe_u32 v34, v4, 16, 1
	v_add3_u32 v4, v4, v34, s41
	v_bfe_u32 v34, v33, 16, 1
	v_lshrrev_b32_e32 v4, 16, v4
	v_add3_u32 v33, v33, v34, s41
	v_and_or_b32 v34, v33, s42, v4
	v_bfe_u32 v4, v35, 16, 1
	v_add3_u32 v4, v35, v4, s41
	v_bfe_u32 v33, v36, 16, 1
	v_lshrrev_b32_e32 v4, 16, v4
	v_add3_u32 v33, v36, v33, s41
	v_and_or_b32 v35, v33, s42, v4
	v_bfe_u32 v4, v37, 16, 1
	v_add3_u32 v4, v37, v4, s41
	v_bfe_u32 v33, v38, 16, 1
	v_lshrrev_b32_e32 v4, 16, v4
	v_add3_u32 v33, v38, v33, s41
	v_and_or_b32 v36, v33, s42, v4
	v_bfe_u32 v4, v39, 16, 1
	v_add3_u32 v4, v39, v4, s41
	v_bfe_u32 v33, v40, 16, 1
	v_lshrrev_b32_e32 v4, 16, v4
	v_add3_u32 v33, v40, v33, s41
	v_and_or_b32 v37, v33, s42, v4
	v_or_b32_e32 v4, v52, v25
	v_lshlrev_b32_e32 v4, 12, v4
	v_lshl_add_u64 v[38:39], v[20:21], 0, v[4:5]
	global_store_dwordx4 v[38:39], v[34:37], off
	ds_read_b32 v4, v23 offset:96
	ds_read_b32 v33, v23 offset:228
	ds_read_b32 v35, v23 offset:360
	ds_read_b32 v36, v23 offset:492
	ds_read_b32 v37, v23 offset:624
	ds_read_b32 v38, v23 offset:756
	ds_read_b32 v39, v23 offset:888
	ds_read_b32 v40, v23 offset:1020
	s_waitcnt lgkmcnt(0)
	v_bfe_u32 v34, v4, 16, 1
	v_add3_u32 v4, v4, v34, s41
	v_bfe_u32 v34, v33, 16, 1
	v_lshrrev_b32_e32 v4, 16, v4
	v_add3_u32 v33, v33, v34, s41
	v_and_or_b32 v34, v33, s42, v4
	v_bfe_u32 v4, v35, 16, 1
	v_add3_u32 v4, v35, v4, s41
	v_bfe_u32 v33, v36, 16, 1
	v_lshrrev_b32_e32 v4, 16, v4
	v_add3_u32 v33, v36, v33, s41
	v_and_or_b32 v35, v33, s42, v4
	v_bfe_u32 v4, v37, 16, 1
	v_add3_u32 v4, v37, v4, s41
	v_bfe_u32 v33, v38, 16, 1
	v_lshrrev_b32_e32 v4, 16, v4
	v_add3_u32 v33, v38, v33, s41
	v_and_or_b32 v36, v33, s42, v4
	v_bfe_u32 v4, v39, 16, 1
	v_add3_u32 v4, v39, v4, s41
	v_bfe_u32 v33, v40, 16, 1
	v_lshrrev_b32_e32 v4, 16, v4
	v_add3_u32 v33, v40, v33, s41
	v_and_or_b32 v37, v33, s42, v4
	v_or_b32_e32 v4, v52, v26
	v_lshlrev_b32_e32 v4, 12, v4
	v_lshl_add_u64 v[20:21], v[20:21], 0, v[4:5]
	global_store_dwordx4 v[20:21], v[34:37], off
	s_waitcnt lgkmcnt(0)

; #define LAS __attribute__((address_space(3)))
; #define LDS_WAIT() asm volatile("s_waitcnt lgkmcnt(0)" ::: "memory")
; __device__ __forceinline__ unsigned pk2(float lo, float hi) { return f2bf(lo) | (f2bf(hi) << 16); }
;     if (ldw == 0) ldw = K;
;     const int nblk = N / 32, kb = item / nblk, nb = item % nblk, k0 = 64 * kb, n0 = 32 * nb;
;     float tv_[32];
; #pragma unroll
;     for (int i = 0; i < 32; ++i) tv_[i] = W[(size_t)(k0 + 2 * i + (lane >> 5)) * N + n0 + (lane & 31)];
; #pragma unroll
;     for (int i = 0; i < 32; ++i) scr[(2 * i + (lane >> 5)) * 33 + (lane & 31)] = tv_[i];
;     LDS_WAIT(); asm volatile("" ::: "memory");
;     const int c = lane & 7;
; #pragma unroll
;     for (int j = 0; j < 4; ++j) { const int n = (lane >> 3) + 8 * j; const LAS float* s = scr + (8 * c) * 33 + n;
;         v4u o; o.x = pk2(s[0 * 33], s[1 * 33]); o.y = pk2(s[2 * 33], s[3 * 33]); o.z = pk2(s[4 * 33], s[5 * 33]); o.w = pk2(s[6 * 33], s[7 * 33]);
;         *(v4u*)(WT + (size_t)(n0 + n) * ldw + koff + k0 + 8 * c) = o; }
;     LDS_WAIT(); asm volatile("" ::: "memory");
; }
; __device__ __forceinline__ void convert_range(LAS unsigned char* lds, const Params& p, const int lo, const int hi, const int gw, const int NGW) {
;     ...
;         if (r < 2 * I_PB) { const int l = r / I_PB; r -= l * I_PB; p0_transpose_item(p.in[17] + (size_t)l * LW * DM, LW, DM, (bf16*)(ws + WS_WCAT + l * SZ_WCAT), scr, r, lane, KCAT, PW); continue; } r -= 2 * I_PB;
.LBB0_38:
	s_andn2_saveexec_b64 s[28:29], s[28:29]
	s_cbranch_execz .LBB0_40
	v_add_u32_e32 v4, 0x2200, v27
	v_lshrrev_b32_e32 v4, 11, v4
	v_readlane_b32 s68, v251, 9
	v_lshlrev_b64 v[34:35], 24, v[4:5]
	v_readlane_b32 s70, v251, 11
	v_readlane_b32 s71, v251, 12
	v_mov_b64_e32 v[36:37], s[8:9]
	v_and_b32_e32 v52, 0x7e0, v30
	v_lshl_add_u64 v[34:35], s[70:71], 0, v[34:35]
	v_mad_u64_u32 v[36:37], s[30:31], v4, s91, v[36:37]
	v_and_b32_e32 v33, 0x7c0, v20
	v_lshlrev_b32_e32 v4, 2, v52
	v_or_b32_e32 v38, v33, v1
	v_lshl_add_u64 v[20:21], v[34:35], 0, v[4:5]
	v_lshlrev_b32_e32 v4, 2, v2
	v_lshl_add_u64 v[20:21], v[20:21], 0, v[4:5]
	v_lshlrev_b32_e32 v4, 13, v38
	v_lshl_add_u64 v[20:21], v[20:21], 0, v[4:5]
	v_add_co_u32_e32 v34, vcc, s40, v20
	s_mov_b64 s[30:31], 0x5000800
	s_nop 0
	v_addc_co_u32_e32 v35, vcc, 0, v21, vcc
	v_add_co_u32_e32 v38, vcc, s43, v20
	v_readlane_b32 s69, v251, 10
	s_nop 0
	v_addc_co_u32_e32 v39, vcc, 0, v21, vcc
	v_add_co_u32_e32 v40, vcc, s45, v20
	v_readlane_b32 s72, v251, 13
	s_nop 0
	v_addc_co_u32_e32 v41, vcc, 0, v21, vcc
	v_add_co_u32_e32 v42, vcc, s47, v20
	v_readlane_b32 s73, v251, 14
	s_nop 0
	v_addc_co_u32_e32 v43, vcc, 0, v21, vcc
	v_add_co_u32_e32 v44, vcc, s48, v20
	v_readlane_b32 s74, v251, 15
	s_nop 0
	v_addc_co_u32_e32 v45, vcc, 0, v21, vcc
	v_add_co_u32_e32 v46, vcc, s49, v20
	v_readlane_b32 s75, v251, 16
	s_nop 0
	v_addc_co_u32_e32 v47, vcc, 0, v21, vcc
	v_add_co_u32_e32 v48, vcc, s50, v20
	s_nop 1
	v_addc_co_u32_e32 v49, vcc, 0, v21, vcc
	global_load_dword v4, v[20:21], off nt
	global_load_dword v53, v[34:35], off nt
	global_load_dword v54, v[38:39], off nt
	global_load_dword v55, v[40:41], off nt
	global_load_dword v56, v[42:43], off nt
	global_load_dword v57, v[44:45], off nt
	global_load_dword v58, v[46:47], off nt
	global_load_dword v59, v[48:49], off nt
	v_add_co_u32_e32 v34, vcc, s51, v20
	s_nop 1
	v_addc_co_u32_e32 v35, vcc, 0, v21, vcc
	v_add_co_u32_e32 v38, vcc, s52, v20
	s_nop 1
	v_addc_co_u32_e32 v39, vcc, 0, v21, vcc
	v_add_co_u32_e32 v40, vcc, s53, v20
	s_nop 1
	v_addc_co_u32_e32 v41, vcc, 0, v21, vcc
	v_add_co_u32_e32 v42, vcc, s54, v20
	s_nop 1
	v_addc_co_u32_e32 v43, vcc, 0, v21, vcc
	v_add_co_u32_e32 v44, vcc, s55, v20
	s_nop 1
	v_addc_co_u32_e32 v45, vcc, 0, v21, vcc
	v_add_co_u32_e32 v46, vcc, s56, v20
	s_nop 1
	v_addc_co_u32_e32 v47, vcc, 0, v21, vcc
	v_add_co_u32_e32 v48, vcc, s57, v20
	s_nop 1
	v_addc_co_u32_e32 v49, vcc, 0, v21, vcc
	v_add_co_u32_e32 v50, vcc, s58, v20
	s_nop 1
	v_addc_co_u32_e32 v51, vcc, 0, v21, vcc
	global_load_dword v60, v[34:35], off nt
	global_load_dword v61, v[38:39], off nt
	global_load_dword v62, v[40:41], off nt
	global_load_dword v63, v[42:43], off nt
	global_load_dword v64, v[44:45], off nt
	global_load_dword v65, v[46:47], off nt
	global_load_dword v66, v[48:49], off nt
	global_load_dword v67, v[50:51], off nt
	v_add_co_u32_e32 v34, vcc, s59, v20
	s_nop 1
	v_addc_co_u32_e32 v35, vcc, 0, v21, vcc
	v_add_co_u32_e32 v38, vcc, s76, v20
	s_nop 1
	v_addc_co_u32_e32 v39, vcc, 0, v21, vcc
	v_add_co_u32_e32 v40, vcc, s77, v20
	s_nop 1
	v_addc_co_u32_e32 v41, vcc, 0, v21, vcc
	v_add_co_u32_e32 v42, vcc, s78, v20
	s_nop 1
	v_addc_co_u32_e32 v43, vcc, 0, v21, vcc
	v_add_co_u32_e32 v44, vcc, s79, v20
	s_nop 1
	v_addc_co_u32_e32 v45, vcc, 0, v21, vcc
	v_add_co_u32_e32 v46, vcc, s80, v20
	s_nop 1
	v_addc_co_u32_e32 v47, vcc, 0, v21, vcc
	v_add_co_u32_e32 v48, vcc, s81, v20
	s_nop 1
	v_addc_co_u32_e32 v49, vcc, 0, v21, vcc
	v_add_co_u32_e32 v50, vcc, s82, v20
	s_nop 1
	v_addc_co_u32_e32 v51, vcc, 0, v21, vcc
	global_load_dword v68, v[34:35], off nt
	global_load_dword v69, v[38:39], off nt
	global_load_dword v70, v[40:41], off nt
	global_load_dword v71, v[42:43], off nt
	global_load_dword v72, v[44:45], off nt
	global_load_dword v73, v[46:47], off nt
	global_load_dword v74, v[48:49], off nt
	s_nop 0
	global_load_dword v50, v[50:51], off nt
	v_add_co_u32_e32 v34, vcc, s83, v20
	s_nop 1
	v_addc_co_u32_e32 v35, vcc, 0, v21, vcc
	v_add_co_u32_e32 v38, vcc, s84, v20
	s_nop 1
	v_addc_co_u32_e32 v39, vcc, 0, v21, vcc
	v_add_co_u32_e32 v40, vcc, s85, v20
	s_nop 1
	v_addc_co_u32_e32 v41, vcc, 0, v21, vcc
	v_add_co_u32_e32 v42, vcc, s86, v20
	s_nop 1
	v_addc_co_u32_e32 v43, vcc, 0, v21, vcc
	v_add_co_u32_e32 v44, vcc, s87, v20
	s_nop 1
	v_addc_co_u32_e32 v45, vcc, 0, v21, vcc
	v_add_co_u32_e32 v46, vcc, s88, v20
	s_nop 1
	v_addc_co_u32_e32 v47, vcc, 0, v21, vcc
	v_add_co_u32_e32 v48, vcc, s89, v20
	s_nop 1
	v_addc_co_u32_e32 v49, vcc, 0, v21, vcc
	v_add_co_u32_e32 v20, vcc, s90, v20
	s_nop 1
	v_addc_co_u32_e32 v21, vcc, 0, v21, vcc
	global_load_dword v34, v[34:35], off nt
	s_nop 0
	global_load_dword v35, v[38:39], off nt
	s_nop 0
	global_load_dword v38, v[40:41], off nt
	global_load_dword v39, v[42:43], off nt
	s_nop 0
	global_load_dword v40, v[44:45], off nt
	global_load_dword v41, v[46:47], off nt
	global_load_dword v42, v[48:49], off nt
	s_nop 0
	global_load_dword v20, v[20:21], off nt
	s_waitcnt vmcnt(30)
	ds_write2_b32 v3, v4, v53 offset1:66
	s_waitcnt vmcnt(28)
	ds_write2_b32 v3, v54, v55 offset0:132 offset1:198
	s_waitcnt vmcnt(26)
	ds_write2_b32 v31, v56, v57 offset0:8 offset1:74
	s_waitcnt vmcnt(24)
	ds_write2_b32 v31, v58, v59 offset0:140 offset1:206
	s_waitcnt vmcnt(22)
	ds_write2_b32 v32, v60, v61 offset0:16 offset1:82
	s_waitcnt vmcnt(20)
	ds_write2_b32 v32, v62, v63 offset0:148 offset1:214
	v_add_u32_e32 v4, 0xc00, v3
	s_waitcnt vmcnt(18)
	ds_write2_b32 v4, v64, v65 offset0:24 offset1:90
	s_waitcnt vmcnt(16)
	ds_write2_b32 v4, v66, v67 offset0:156 offset1:222
	v_add_u32_e32 v4, 0x1000, v3
	s_waitcnt vmcnt(14)
; #define LAS __attribute__((address_space(3)))
; #define LDS_WAIT() asm volatile("s_waitcnt lgkmcnt(0)" ::: "memory")
; __device__ __forceinline__ unsigned pk2(float lo, float hi) { return f2bf(lo) | (f2bf(hi) << 16); }
;     ...
;     for (int i = 0; i < 32; ++i) scr[(2 * i + (lane >> 5)) * 33 + (lane & 31)] = tv_[i];
;     LDS_WAIT(); asm volatile("" ::: "memory");
;     const int c = lane & 7;
; #pragma unroll
;     for (int j = 0; j < 4; ++j) { const int n = (lane >> 3) + 8 * j; const LAS float* s = scr + (8 * c) * 33 + n;
;         v4u o; o.x = pk2(s[0 * 33], s[1 * 33]); o.y = pk2(s[2 * 33], s[3 * 33]); o.z = pk2(s[4 * 33], s[5 * 33]); o.w = pk2(s[6 * 33], s[7 * 33]);
;         *(v4u*)(WT + (size_t)(n0 + n) * ldw + koff + k0 + 8 * c) = o; }
;     LDS_WAIT(); asm volatile("" ::: "memory");
	ds_write2_b32 v4, v68, v69 offset0:32 offset1:98
	s_waitcnt vmcnt(12)
	ds_write2_b32 v4, v70, v71 offset0:164 offset1:230
	v_add_u32_e32 v4, 0x1400, v3
	s_waitcnt vmcnt(10)
	ds_write2_b32 v4, v72, v73 offset0:40 offset1:106
	s_waitcnt vmcnt(8)
	ds_write2_b32 v4, v74, v50 offset0:172 offset1:238
	v_add_u32_e32 v4, 0x1800, v3
	s_waitcnt vmcnt(6)
	ds_write2_b32 v4, v34, v35 offset0:48 offset1:114
	s_waitcnt vmcnt(4)
	ds_write2_b32 v4, v38, v39 offset0:180 offset1:246
	v_add_u32_e32 v4, 0x1c00, v3
	s_waitcnt vmcnt(2)
	ds_write2_b32 v4, v40, v41 offset0:56 offset1:122
	s_waitcnt vmcnt(0)
	ds_write2_b32 v4, v42, v20 offset0:188 offset1:254
	s_waitcnt lgkmcnt(0)
	v_lshlrev_b32_e32 v4, 1, v33
	v_lshl_add_u64 v[20:21], v[36:37], 0, v[4:5]
	v_lshlrev_b32_e32 v4, 1, v6
	v_lshl_add_u64 v[20:21], v[20:21], 0, v[4:5]
	ds_read_b32 v4, v23
	ds_read_b32 v33, v23 offset:132
	ds_read_b32 v35, v23 offset:264
	ds_read_b32 v36, v23 offset:396
	ds_read_b32 v37, v23 offset:528
	ds_read_b32 v38, v23 offset:660
	ds_read_b32 v39, v23 offset:792
	ds_read_b32 v40, v23 offset:924
	s_waitcnt lgkmcnt(0)
	v_bfe_u32 v34, v4, 16, 1
	v_add3_u32 v4, v4, v34, s41
	v_bfe_u32 v34, v33, 16, 1
	v_lshrrev_b32_e32 v4, 16, v4
	v_add3_u32 v33, v33, v34, s41
	v_and_or_b32 v34, v33, s42, v4
	v_bfe_u32 v4, v35, 16, 1
	v_add3_u32 v4, v35, v4, s41
	v_bfe_u32 v33, v36, 16, 1
	v_lshrrev_b32_e32 v4, 16, v4
	v_add3_u32 v33, v36, v33, s41
	v_and_or_b32 v35, v33, s42, v4
	v_bfe_u32 v4, v37, 16, 1
	v_add3_u32 v4, v37, v4, s41
	v_bfe_u32 v33, v38, 16, 1
	v_lshrrev_b32_e32 v4, 16, v4
	v_add3_u32 v33, v38, v33, s41
	v_and_or_b32 v36, v33, s42, v4
	v_bfe_u32 v4, v39, 16, 1
	v_add3_u32 v4, v39, v4, s41
	v_bfe_u32 v33, v40, 16, 1
	v_lshrrev_b32_e32 v4, 16, v4
	v_add3_u32 v33, v40, v33, s41
	v_and_or_b32 v37, v33, s42, v4
	v_or_b32_e32 v4, v52, v7
	v_mul_u32_u24_e32 v4, 0xc00, v4
	v_lshl_add_u64 v[20:21], v[20:21], 0, s[30:31]
	v_lshlrev_b32_e32 v4, 1, v4
	v_lshl_add_u64 v[38:39], v[20:21], 0, v[4:5]
	global_store_dwordx4 v[38:39], v[34:37], off
	ds_read_b32 v4, v23 offset:32
	ds_read_b32 v33, v23 offset:164
	ds_read_b32 v35, v23 offset:296
	ds_read_b32 v36, v23 offset:428
	ds_read_b32 v37, v23 offset:560
	ds_read_b32 v38, v23 offset:692
	ds_read_b32 v39, v23 offset:824
	ds_read_b32 v40, v23 offset:956
	s_waitcnt lgkmcnt(0)
	v_bfe_u32 v34, v4, 16, 1
	v_add3_u32 v4, v4, v34, s41
	v_bfe_u32 v34, v33, 16, 1
	v_lshrrev_b32_e32 v4, 16, v4
	v_add3_u32 v33, v33, v34, s41
	v_and_or_b32 v34, v33, s42, v4
	v_bfe_u32 v4, v35, 16, 1
	v_add3_u32 v4, v35, v4, s41
	v_bfe_u32 v33, v36, 16, 1
	v_lshrrev_b32_e32 v4, 16, v4
	v_add3_u32 v33, v36, v33, s41
	v_and_or_b32 v35, v33, s42, v4
	v_bfe_u32 v4, v37, 16, 1
	v_add3_u32 v4, v37, v4, s41
	v_bfe_u32 v33, v38, 16, 1
	v_lshrrev_b32_e32 v4, 16, v4
	v_add3_u32 v33, v38, v33, s41
	v_and_or_b32 v36, v33, s42, v4
	v_bfe_u32 v4, v39, 16, 1
	v_add3_u32 v4, v39, v4, s41
	v_bfe_u32 v33, v40, 16, 1
	v_lshrrev_b32_e32 v4, 16, v4
	v_add3_u32 v33, v40, v33, s41
	v_and_or_b32 v37, v33, s42, v4
	v_or_b32_e32 v4, v52, v24
	v_mul_u32_u24_e32 v4, 0xc00, v4
	v_lshlrev_b32_e32 v4, 1, v4
	v_lshl_add_u64 v[38:39], v[20:21], 0, v[4:5]
	global_store_dwordx4 v[38:39], v[34:37], off
	ds_read_b32 v4, v23 offset:64
	ds_read_b32 v33, v23 offset:196
	ds_read_b32 v35, v23 offset:328
	ds_read_b32 v36, v23 offset:460
	ds_read_b32 v37, v23 offset:592
	ds_read_b32 v38, v23 offset:724
	ds_read_b32 v39, v23 offset:856
	ds_read_b32 v40, v23 offset:988
	s_waitcnt lgkmcnt(0)
	v_bfe_u32 v34, v4, 16, 1
	v_add3_u32 v4, v4, v34, s41
	v_bfe_u32 v34, v33, 16, 1
	v_lshrrev_b32_e32 v4, 16, v4
	v_add3_u32 v33, v33, v34, s41
	v_and_or_b32 v34, v33, s42, v4
	v_bfe_u32 v4, v35, 16, 1
	v_add3_u32 v4, v35, v4, s41
	v_bfe_u32 v33, v36, 16, 1
	v_lshrrev_b32_e32 v4, 16, v4
	v_add3_u32 v33, v36, v33, s41
	v_and_or_b32 v35, v33, s42, v4
	v_bfe_u32 v4, v37, 16, 1
	v_add3_u32 v4, v37, v4, s41
	v_bfe_u32 v33, v38, 16, 1
	v_lshrrev_b32_e32 v4, 16, v4
	v_add3_u32 v33, v38, v33, s41
	v_and_or_b32 v36, v33, s42, v4
	v_bfe_u32 v4, v39, 16, 1
	v_add3_u32 v4, v39, v4, s41
	v_bfe_u32 v33, v40, 16, 1
	v_lshrrev_b32_e32 v4, 16, v4
	v_add3_u32 v33, v40, v33, s41
	v_and_or_b32 v37, v33, s42, v4
	v_or_b32_e32 v4, v52, v25
	v_mul_u32_u24_e32 v4, 0xc00, v4
	v_lshlrev_b32_e32 v4, 1, v4
	v_lshl_add_u64 v[38:39], v[20:21], 0, v[4:5]
	global_store_dwordx4 v[38:39], v[34:37], off
	ds_read_b32 v4, v23 offset:96
	ds_read_b32 v33, v23 offset:228
	ds_read_b32 v35, v23 offset:360
	ds_read_b32 v36, v23 offset:492
	ds_read_b32 v37, v23 offset:624
	ds_read_b32 v38, v23 offset:756
	ds_read_b32 v39, v23 offset:888
	ds_read_b32 v40, v23 offset:1020
	s_waitcnt lgkmcnt(0)
	v_bfe_u32 v34, v4, 16, 1
	v_add3_u32 v4, v4, v34, s41
	v_bfe_u32 v34, v33, 16, 1
	v_lshrrev_b32_e32 v4, 16, v4
	v_add3_u32 v33, v33, v34, s41
	v_and_or_b32 v34, v33, s42, v4
	v_bfe_u32 v4, v35, 16, 1
	v_add3_u32 v4, v35, v4, s41
	v_bfe_u32 v33, v36, 16, 1
	v_lshrrev_b32_e32 v4, 16, v4
	v_add3_u32 v33, v36, v33, s41
	v_and_or_b32 v35, v33, s42, v4
	v_bfe_u32 v4, v37, 16, 1
	v_add3_u32 v4, v37, v4, s41
	v_bfe_u32 v33, v38, 16, 1
	v_lshrrev_b32_e32 v4, 16, v4
	v_add3_u32 v33, v38, v33, s41
	v_and_or_b32 v36, v33, s42, v4
	v_bfe_u32 v4, v39, 16, 1
	v_add3_u32 v4, v39, v4, s41
	v_bfe_u32 v33, v40, 16, 1
	v_lshrrev_b32_e32 v4, 16, v4
	v_add3_u32 v33, v40, v33, s41
	v_and_or_b32 v37, v33, s42, v4
	v_or_b32_e32 v4, v52, v26
	v_mul_u32_u24_e32 v4, 0xc00, v4
	v_lshlrev_b32_e32 v4, 1, v4
	v_lshl_add_u64 v[20:21], v[20:21], 0, v[4:5]
	global_store_dwordx4 v[20:21], v[34:37], off
	s_waitcnt lgkmcnt(0)

; #define LAS __attribute__((address_space(3)))
; #define LDS_WAIT() asm volatile("s_waitcnt lgkmcnt(0)" ::: "memory")
; __device__ __forceinline__ unsigned pk2(float lo, float hi) { return f2bf(lo) | (f2bf(hi) << 16); }
;     if (ldw == 0) ldw = K;
;     const int nblk = N / 32, kb = item / nblk, nb = item % nblk, k0 = 64 * kb, n0 = 32 * nb;
;     float tv_[32];
; #pragma unroll
;     for (int i = 0; i < 32; ++i) tv_[i] = W[(size_t)(k0 + 2 * i + (lane >> 5)) * N + n0 + (lane & 31)];
; #pragma unroll
;     for (int i = 0; i < 32; ++i) scr[(2 * i + (lane >> 5)) * 33 + (lane & 31)] = tv_[i];
;     LDS_WAIT(); asm volatile("" ::: "memory");
;     const int c = lane & 7;
; #pragma unroll
;     for (int j = 0; j < 4; ++j) { const int n = (lane >> 3) + 8 * j; const LAS float* s = scr + (8 * c) * 33 + n;
;         v4u o; o.x = pk2(s[0 * 33], s[1 * 33]); o.y = pk2(s[2 * 33], s[3 * 33]); o.z = pk2(s[4 * 33], s[5 * 33]); o.w = pk2(s[6 * 33], s[7 * 33]);
;         *(v4u*)(WT + (size_t)(n0 + n) * ldw + koff + k0 + 8 * c) = o; }
;     LDS_WAIT(); asm volatile("" ::: "memory");
; }
; __device__ __forceinline__ void convert_range(LAS unsigned char* lds, const Params& p, const int lo, const int hi, const int gw, const int NGW) {
;     ...
;         if (r < 2 * I_PA) { const int l = r / I_PA; r -= l * I_PA; p0_transpose_item(p.in[16] + (size_t)l * PW * DM, PW, DM, (bf16*)(ws + WS_WCAT + l * SZ_WCAT), scr, r, lane, KCAT, 0); continue; } r -= 2 * I_PA;
.LBB0_41:
	s_andn2_saveexec_b64 s[26:27], s[26:27]
	s_cbranch_execz .LBB0_43
	v_add_u32_e32 v4, 0x2a00, v27
	v_lshrrev_b32_e32 v4, 10, v4
	v_readlane_b32 s68, v251, 9
	v_lshlrev_b64 v[34:35], 23, v[4:5]
	v_readlane_b32 s69, v251, 10
	v_mov_b64_e32 v[36:37], s[20:21]
	v_and_b32_e32 v52, 0x7e0, v30
	v_lshl_add_u64 v[34:35], s[68:69], 0, v[34:35]
	v_mad_u64_u32 v[36:37], s[28:29], v4, s91, v[36:37]
	v_and_b32_e32 v33, 0x3c0, v20
	v_lshlrev_b32_e32 v4, 2, v52
	v_or_b32_e32 v38, v33, v1
	v_lshl_add_u64 v[20:21], v[34:35], 0, v[4:5]
	v_lshlrev_b32_e32 v4, 2, v2
	v_lshl_add_u64 v[20:21], v[20:21], 0, v[4:5]
	v_lshlrev_b32_e32 v4, 13, v38
	v_lshl_add_u64 v[20:21], v[20:21], 0, v[4:5]
	v_add_co_u32_e32 v34, vcc, s40, v20
	v_readlane_b32 s70, v251, 11
	s_nop 0
	v_addc_co_u32_e32 v35, vcc, 0, v21, vcc
	v_add_co_u32_e32 v38, vcc, s43, v20
	v_readlane_b32 s71, v251, 12
	s_nop 0
	v_addc_co_u32_e32 v39, vcc, 0, v21, vcc
	v_add_co_u32_e32 v40, vcc, s45, v20
	v_readlane_b32 s72, v251, 13
	s_nop 0
	v_addc_co_u32_e32 v41, vcc, 0, v21, vcc
	v_add_co_u32_e32 v42, vcc, s47, v20
	v_readlane_b32 s73, v251, 14
	s_nop 0
	v_addc_co_u32_e32 v43, vcc, 0, v21, vcc
	v_add_co_u32_e32 v44, vcc, s48, v20
	v_readlane_b32 s74, v251, 15
	s_nop 0
	v_addc_co_u32_e32 v45, vcc, 0, v21, vcc
	v_add_co_u32_e32 v46, vcc, s49, v20
	v_readlane_b32 s75, v251, 16
	s_nop 0
	v_addc_co_u32_e32 v47, vcc, 0, v21, vcc
	v_add_co_u32_e32 v48, vcc, s50, v20
	s_nop 1
	v_addc_co_u32_e32 v49, vcc, 0, v21, vcc
	global_load_dword v4, v[20:21], off nt
	global_load_dword v53, v[34:35], off nt
	global_load_dword v54, v[38:39], off nt
	global_load_dword v55, v[40:41], off nt
	global_load_dword v56, v[42:43], off nt
	global_load_dword v57, v[44:45], off nt
	global_load_dword v58, v[46:47], off nt
	global_load_dword v59, v[48:49], off nt
	v_add_co_u32_e32 v34, vcc, s51, v20
	s_nop 1
	v_addc_co_u32_e32 v35, vcc, 0, v21, vcc
	v_add_co_u32_e32 v38, vcc, s52, v20
	s_nop 1
	v_addc_co_u32_e32 v39, vcc, 0, v21, vcc
	v_add_co_u32_e32 v40, vcc, s53, v20
	s_nop 1
	v_addc_co_u32_e32 v41, vcc, 0, v21, vcc
	v_add_co_u32_e32 v42, vcc, s54, v20
	s_nop 1
	v_addc_co_u32_e32 v43, vcc, 0, v21, vcc
	v_add_co_u32_e32 v44, vcc, s55, v20
	s_nop 1
	v_addc_co_u32_e32 v45, vcc, 0, v21, vcc
	v_add_co_u32_e32 v46, vcc, s56, v20
	s_nop 1
	v_addc_co_u32_e32 v47, vcc, 0, v21, vcc
	v_add_co_u32_e32 v48, vcc, s57, v20
	s_nop 1
	v_addc_co_u32_e32 v49, vcc, 0, v21, vcc
	v_add_co_u32_e32 v50, vcc, s58, v20
	s_nop 1
	v_addc_co_u32_e32 v51, vcc, 0, v21, vcc
	global_load_dword v60, v[34:35], off nt
	global_load_dword v61, v[38:39], off nt
	global_load_dword v62, v[40:41], off nt
	global_load_dword v63, v[42:43], off nt
	global_load_dword v64, v[44:45], off nt
	global_load_dword v65, v[46:47], off nt
	global_load_dword v66, v[48:49], off nt
	global_load_dword v67, v[50:51], off nt
	v_add_co_u32_e32 v34, vcc, s59, v20
	s_nop 1
	v_addc_co_u32_e32 v35, vcc, 0, v21, vcc
	v_add_co_u32_e32 v38, vcc, s76, v20
	s_nop 1
	v_addc_co_u32_e32 v39, vcc, 0, v21, vcc
	v_add_co_u32_e32 v40, vcc, s77, v20
	s_nop 1
	v_addc_co_u32_e32 v41, vcc, 0, v21, vcc
	v_add_co_u32_e32 v42, vcc, s78, v20
	s_nop 1
	v_addc_co_u32_e32 v43, vcc, 0, v21, vcc
	v_add_co_u32_e32 v44, vcc, s79, v20
	s_nop 1
	v_addc_co_u32_e32 v45, vcc, 0, v21, vcc
	v_add_co_u32_e32 v46, vcc, s80, v20
	s_nop 1
	v_addc_co_u32_e32 v47, vcc, 0, v21, vcc
	v_add_co_u32_e32 v48, vcc, s81, v20
	s_nop 1
	v_addc_co_u32_e32 v49, vcc, 0, v21, vcc
	v_add_co_u32_e32 v50, vcc, s82, v20
	s_nop 1
	v_addc_co_u32_e32 v51, vcc, 0, v21, vcc
	global_load_dword v68, v[34:35], off nt
	global_load_dword v69, v[38:39], off nt
	global_load_dword v70, v[40:41], off nt
	global_load_dword v71, v[42:43], off nt
	global_load_dword v72, v[44:45], off nt
	global_load_dword v73, v[46:47], off nt
	global_load_dword v74, v[48:49], off nt
	s_nop 0
	global_load_dword v50, v[50:51], off nt
	v_add_co_u32_e32 v34, vcc, s83, v20
	s_nop 1
	v_addc_co_u32_e32 v35, vcc, 0, v21, vcc
	v_add_co_u32_e32 v38, vcc, s84, v20
	s_nop 1
	v_addc_co_u32_e32 v39, vcc, 0, v21, vcc
	v_add_co_u32_e32 v40, vcc, s85, v20
	s_nop 1
	v_addc_co_u32_e32 v41, vcc, 0, v21, vcc
	v_add_co_u32_e32 v42, vcc, s86, v20
	s_nop 1
	v_addc_co_u32_e32 v43, vcc, 0, v21, vcc
	v_add_co_u32_e32 v44, vcc, s87, v20
	s_nop 1
	v_addc_co_u32_e32 v45, vcc, 0, v21, vcc
	v_add_co_u32_e32 v46, vcc, s88, v20
	s_nop 1
	v_addc_co_u32_e32 v47, vcc, 0, v21, vcc
	v_add_co_u32_e32 v48, vcc, s89, v20
	s_nop 1
	v_addc_co_u32_e32 v49, vcc, 0, v21, vcc
	v_add_co_u32_e32 v20, vcc, s90, v20
	s_nop 1
	v_addc_co_u32_e32 v21, vcc, 0, v21, vcc
	global_load_dword v34, v[34:35], off nt
	s_nop 0
	global_load_dword v35, v[38:39], off nt
	s_nop 0
	global_load_dword v38, v[40:41], off nt
	global_load_dword v39, v[42:43], off nt
	s_nop 0
	global_load_dword v40, v[44:45], off nt
	global_load_dword v41, v[46:47], off nt
	global_load_dword v42, v[48:49], off nt
	s_nop 0
	global_load_dword v20, v[20:21], off nt
	s_waitcnt vmcnt(30)
	ds_write2_b32 v3, v4, v53 offset1:66
	s_waitcnt vmcnt(28)
	ds_write2_b32 v3, v54, v55 offset0:132 offset1:198
	s_waitcnt vmcnt(26)
	ds_write2_b32 v31, v56, v57 offset0:8 offset1:74
	s_waitcnt vmcnt(24)
	ds_write2_b32 v31, v58, v59 offset0:140 offset1:206
	s_waitcnt vmcnt(22)
	ds_write2_b32 v32, v60, v61 offset0:16 offset1:82
	s_waitcnt vmcnt(20)
	ds_write2_b32 v32, v62, v63 offset0:148 offset1:214
	v_add_u32_e32 v4, 0xc00, v3
	s_waitcnt vmcnt(18)
	ds_write2_b32 v4, v64, v65 offset0:24 offset1:90
	s_waitcnt vmcnt(16)
	ds_write2_b32 v4, v66, v67 offset0:156 offset1:222
	v_add_u32_e32 v4, 0x1000, v3
	s_waitcnt vmcnt(14)
; #define LAS __attribute__((address_space(3)))
; #define LDS_WAIT() asm volatile("s_waitcnt lgkmcnt(0)" ::: "memory")
; __device__ __forceinline__ unsigned pk2(float lo, float hi) { return f2bf(lo) | (f2bf(hi) << 16); }
;     ...
;     for (int i = 0; i < 32; ++i) scr[(2 * i + (lane >> 5)) * 33 + (lane & 31)] = tv_[i];
;     LDS_WAIT(); asm volatile("" ::: "memory");
;     const int c = lane & 7;
; #pragma unroll
;     for (int j = 0; j < 4; ++j) { const int n = (lane >> 3) + 8 * j; const LAS float* s = scr + (8 * c) * 33 + n;
;         v4u o; o.x = pk2(s[0 * 33], s[1 * 33]); o.y = pk2(s[2 * 33], s[3 * 33]); o.z = pk2(s[4 * 33], s[5 * 33]); o.w = pk2(s[6 * 33], s[7 * 33]);
;         *(v4u*)(WT + (size_t)(n0 + n) * ldw + koff + k0 + 8 * c) = o; }
;     LDS_WAIT(); asm volatile("" ::: "memory");
	ds_write2_b32 v4, v68, v69 offset0:32 offset1:98
	s_waitcnt vmcnt(12)
	ds_write2_b32 v4, v70, v71 offset0:164 offset1:230
	v_add_u32_e32 v4, 0x1400, v3
	s_waitcnt vmcnt(10)
	ds_write2_b32 v4, v72, v73 offset0:40 offset1:106
	s_waitcnt vmcnt(8)
	ds_write2_b32 v4, v74, v50 offset0:172 offset1:238
	v_add_u32_e32 v4, 0x1800, v3
	s_waitcnt vmcnt(6)
	ds_write2_b32 v4, v34, v35 offset0:48 offset1:114
	s_waitcnt vmcnt(4)
	ds_write2_b32 v4, v38, v39 offset0:180 offset1:246
	v_add_u32_e32 v4, 0x1c00, v3
	s_waitcnt vmcnt(2)
	ds_write2_b32 v4, v40, v41 offset0:56 offset1:122
	s_waitcnt vmcnt(0)
	ds_write2_b32 v4, v42, v20 offset0:188 offset1:254
	s_waitcnt lgkmcnt(0)
	v_lshlrev_b32_e32 v4, 1, v33
	v_lshl_add_u64 v[20:21], v[36:37], 0, v[4:5]
	v_lshlrev_b32_e32 v4, 1, v6
	v_lshl_add_u64 v[20:21], v[20:21], 0, v[4:5]
	ds_read_b32 v4, v23
	ds_read_b32 v33, v23 offset:132
	ds_read_b32 v35, v23 offset:264
	ds_read_b32 v36, v23 offset:396
	ds_read_b32 v37, v23 offset:528
	ds_read_b32 v38, v23 offset:660
	ds_read_b32 v39, v23 offset:792
	ds_read_b32 v40, v23 offset:924
	s_waitcnt lgkmcnt(0)
	v_bfe_u32 v34, v4, 16, 1
	v_add3_u32 v4, v4, v34, s41
	v_bfe_u32 v34, v33, 16, 1
	v_lshrrev_b32_e32 v4, 16, v4
	v_add3_u32 v33, v33, v34, s41
	v_and_or_b32 v34, v33, s42, v4
	v_bfe_u32 v4, v35, 16, 1
	v_add3_u32 v4, v35, v4, s41
	v_bfe_u32 v33, v36, 16, 1
	v_lshrrev_b32_e32 v4, 16, v4
	v_add3_u32 v33, v36, v33, s41
	v_and_or_b32 v35, v33, s42, v4
	v_bfe_u32 v4, v37, 16, 1
	v_add3_u32 v4, v37, v4, s41
	v_bfe_u32 v33, v38, 16, 1
	v_lshrrev_b32_e32 v4, 16, v4
	v_add3_u32 v33, v38, v33, s41
	v_and_or_b32 v36, v33, s42, v4
	v_bfe_u32 v4, v39, 16, 1
	v_add3_u32 v4, v39, v4, s41
	v_bfe_u32 v33, v40, 16, 1
	v_lshrrev_b32_e32 v4, 16, v4
	v_add3_u32 v33, v40, v33, s41
	v_and_or_b32 v37, v33, s42, v4
	v_or_b32_e32 v4, v52, v7
	v_mul_u32_u24_e32 v4, 0xc00, v4
	v_lshlrev_b32_e32 v4, 1, v4
	v_lshl_add_u64 v[38:39], v[20:21], 0, v[4:5]
	global_store_dwordx4 v[38:39], v[34:37], off
	ds_read_b32 v4, v23 offset:32
	ds_read_b32 v33, v23 offset:164
	ds_read_b32 v35, v23 offset:296
	ds_read_b32 v36, v23 offset:428
	ds_read_b32 v37, v23 offset:560
	ds_read_b32 v38, v23 offset:692
	ds_read_b32 v39, v23 offset:824
	ds_read_b32 v40, v23 offset:956
	s_waitcnt lgkmcnt(0)
	v_bfe_u32 v34, v4, 16, 1
	v_add3_u32 v4, v4, v34, s41
	v_bfe_u32 v34, v33, 16, 1
	v_lshrrev_b32_e32 v4, 16, v4
	v_add3_u32 v33, v33, v34, s41
	v_and_or_b32 v34, v33, s42, v4
	v_bfe_u32 v4, v35, 16, 1
	v_add3_u32 v4, v35, v4, s41
	v_bfe_u32 v33, v36, 16, 1
	v_lshrrev_b32_e32 v4, 16, v4
	v_add3_u32 v33, v36, v33, s41
	v_and_or_b32 v35, v33, s42, v4
	v_bfe_u32 v4, v37, 16, 1
	v_add3_u32 v4, v37, v4, s41
	v_bfe_u32 v33, v38, 16, 1
	v_lshrrev_b32_e32 v4, 16, v4
	v_add3_u32 v33, v38, v33, s41
	v_and_or_b32 v36, v33, s42, v4
	v_bfe_u32 v4, v39, 16, 1
	v_add3_u32 v4, v39, v4, s41
	v_bfe_u32 v33, v40, 16, 1
	v_lshrrev_b32_e32 v4, 16, v4
	v_add3_u32 v33, v40, v33, s41
	v_and_or_b32 v37, v33, s42, v4
	v_or_b32_e32 v4, v52, v24
	v_mul_u32_u24_e32 v4, 0xc00, v4
	v_lshlrev_b32_e32 v4, 1, v4
	v_lshl_add_u64 v[38:39], v[20:21], 0, v[4:5]
	global_store_dwordx4 v[38:39], v[34:37], off
	ds_read_b32 v4, v23 offset:64
	ds_read_b32 v33, v23 offset:196
	ds_read_b32 v35, v23 offset:328
	ds_read_b32 v36, v23 offset:460
	ds_read_b32 v37, v23 offset:592
	ds_read_b32 v38, v23 offset:724
	ds_read_b32 v39, v23 offset:856
	ds_read_b32 v40, v23 offset:988
	s_waitcnt lgkmcnt(0)
	v_bfe_u32 v34, v4, 16, 1
	v_add3_u32 v4, v4, v34, s41
	v_bfe_u32 v34, v33, 16, 1
	v_lshrrev_b32_e32 v4, 16, v4
	v_add3_u32 v33, v33, v34, s41
	v_and_or_b32 v34, v33, s42, v4
	v_bfe_u32 v4, v35, 16, 1
	v_add3_u32 v4, v35, v4, s41
	v_bfe_u32 v33, v36, 16, 1
	v_lshrrev_b32_e32 v4, 16, v4
	v_add3_u32 v33, v36, v33, s41
	v_and_or_b32 v35, v33, s42, v4
	v_bfe_u32 v4, v37, 16, 1
	v_add3_u32 v4, v37, v4, s41
	v_bfe_u32 v33, v38, 16, 1
	v_lshrrev_b32_e32 v4, 16, v4
	v_add3_u32 v33, v38, v33, s41
	v_and_or_b32 v36, v33, s42, v4
	v_bfe_u32 v4, v39, 16, 1
	v_add3_u32 v4, v39, v4, s41
	v_bfe_u32 v33, v40, 16, 1
	v_lshrrev_b32_e32 v4, 16, v4
	v_add3_u32 v33, v40, v33, s41
	v_and_or_b32 v37, v33, s42, v4
	v_or_b32_e32 v4, v52, v25
	v_mul_u32_u24_e32 v4, 0xc00, v4
	v_lshlrev_b32_e32 v4, 1, v4
	v_lshl_add_u64 v[38:39], v[20:21], 0, v[4:5]
	global_store_dwordx4 v[38:39], v[34:37], off
	ds_read_b32 v4, v23 offset:96
	ds_read_b32 v33, v23 offset:228
	ds_read_b32 v35, v23 offset:360
	ds_read_b32 v36, v23 offset:492
	ds_read_b32 v37, v23 offset:624
	ds_read_b32 v38, v23 offset:756
	ds_read_b32 v39, v23 offset:888
	ds_read_b32 v40, v23 offset:1020
	s_waitcnt lgkmcnt(0)
	v_bfe_u32 v34, v4, 16, 1
	v_add3_u32 v4, v4, v34, s41
	v_bfe_u32 v34, v33, 16, 1
	v_lshrrev_b32_e32 v4, 16, v4
	v_add3_u32 v33, v33, v34, s41
	v_and_or_b32 v34, v33, s42, v4
	v_bfe_u32 v4, v35, 16, 1
	v_add3_u32 v4, v35, v4, s41
	v_bfe_u32 v33, v36, 16, 1
	v_lshrrev_b32_e32 v4, 16, v4
	v_add3_u32 v33, v36, v33, s41
	v_and_or_b32 v35, v33, s42, v4
	v_bfe_u32 v4, v37, 16, 1
	v_add3_u32 v4, v37, v4, s41
	v_bfe_u32 v33, v38, 16, 1
	v_lshrrev_b32_e32 v4, 16, v4
	v_add3_u32 v33, v38, v33, s41
	v_and_or_b32 v36, v33, s42, v4
	v_bfe_u32 v4, v39, 16, 1
	v_add3_u32 v4, v39, v4, s41
	v_bfe_u32 v33, v40, 16, 1
	v_lshrrev_b32_e32 v4, 16, v4
	v_add3_u32 v33, v40, v33, s41
	v_and_or_b32 v37, v33, s42, v4
	v_or_b32_e32 v4, v52, v26
	v_mul_u32_u24_e32 v4, 0xc00, v4
	v_lshlrev_b32_e32 v4, 1, v4
	v_lshl_add_u64 v[20:21], v[20:21], 0, v[4:5]
	global_store_dwordx4 v[20:21], v[34:37], off
	s_waitcnt lgkmcnt(0)

; #define LAS __attribute__((address_space(3)))
; #define LDS_WAIT() asm volatile("s_waitcnt lgkmcnt(0)" ::: "memory")
; __device__ __forceinline__ unsigned pk2(float lo, float hi) { return f2bf(lo) | (f2bf(hi) << 16); }
;     if (ldw == 0) ldw = K;
;     const int nblk = N / 32, kb = item / nblk, nb = item % nblk, k0 = 64 * kb, n0 = 32 * nb;
;     float tv_[32];
; #pragma unroll
;     for (int i = 0; i < 32; ++i) tv_[i] = W[(size_t)(k0 + 2 * i + (lane >> 5)) * N + n0 + (lane & 31)];
; #pragma unroll
;     for (int i = 0; i < 32; ++i) scr[(2 * i + (lane >> 5)) * 33 + (lane & 31)] = tv_[i];
;     LDS_WAIT(); asm volatile("" ::: "memory");
;     const int c = lane & 7;
; #pragma unroll
;     for (int j = 0; j < 4; ++j) { const int n = (lane >> 3) + 8 * j; const LAS float* s = scr + (8 * c) * 33 + n;
;         v4u o; o.x = pk2(s[0 * 33], s[1 * 33]); o.y = pk2(s[2 * 33], s[3 * 33]); o.z = pk2(s[4 * 33], s[5 * 33]); o.w = pk2(s[6 * 33], s[7 * 33]);
;         *(v4u*)(WT + (size_t)(n0 + n) * ldw + koff + k0 + 8 * c) = o; }
;     LDS_WAIT(); asm volatile("" ::: "memory");
; }
; __device__ __forceinline__ void convert_range(LAS unsigned char* lds, const Params& p, const int lo, const int hi, const int gw, const int NGW) {
;     ...
;         if (r < 2 * I_IN) { const int l = r / I_IN; r -= l * I_IN; p0_transpose_item(p.in[5] + (size_t)l * DM * NC, DM, NC, (bf16*)(ws + WS_WIN + l * SZ_WIN), scr, r, lane); continue; } r -= 2 * I_IN;
.LBB0_44:
	s_andn2_saveexec_b64 s[24:25], s[24:25]
	s_cbranch_execz .LBB0_21
	v_mul_hi_i32 v4, v20, s92
	v_lshrrev_b32_e32 v20, 31, v4
	v_ashrrev_i32_e32 v4, 12, v4
	v_add_u32_e32 v33, v4, v20
	v_readlane_b32 s60, v251, 21
	v_mul_i32_i24_e32 v4, 0xffffd800, v33
	s_movk_i32 s26, 0x7a00
	v_readlane_b32 s70, v251, 31
	v_readlane_b32 s71, v251, 32
	v_add3_u32 v4, v4, v27, s26
	s_mov_b32 s26, 0x5000000
	v_mov_b64_e32 v[20:21], s[70:71]
	v_mad_i64_i32 v[34:35], s[26:27], v33, s26, v[20:21]
	v_mul_hi_i32 v20, v4, s92
	v_lshrrev_b32_e32 v21, 31, v20
	v_ashrrev_i32_e32 v20, 7, v20
	v_add_u32_e32 v20, v20, v21
	v_mul_i32_i24_e32 v21, 0x140, v20
	v_sub_u32_e32 v4, v4, v21
	v_lshlrev_b32_e32 v36, 6, v20
	v_lshlrev_b32_e32 v20, 5, v4
	v_ashrrev_i32_e32 v21, 31, v20
	v_or_b32_e32 v37, v36, v1
	v_lshl_add_u64 v[34:35], v[20:21], 2, v[34:35]
	v_lshlrev_b32_e32 v4, 2, v2
	v_lshl_add_u64 v[34:35], v[34:35], 0, v[4:5]
	v_or_b32_e32 v4, 2, v37
	v_mad_i64_i32 v[40:41], s[26:27], v4, s44, v[34:35]
	v_or_b32_e32 v4, 4, v37
	v_mad_i64_i32 v[42:43], s[26:27], v4, s44, v[34:35]
	v_or_b32_e32 v4, 6, v37
	v_mad_i64_i32 v[44:45], s[26:27], v4, s44, v[34:35]
	v_or_b32_e32 v4, 8, v37
	v_mad_i64_i32 v[46:47], s[26:27], v4, s44, v[34:35]
	v_or_b32_e32 v4, 10, v37
	v_mad_i64_i32 v[48:49], s[26:27], v4, s44, v[34:35]
	v_or_b32_e32 v4, 12, v37
	v_mad_i64_i32 v[50:51], s[26:27], v4, s44, v[34:35]
	v_or_b32_e32 v4, 14, v37
	v_mad_i64_i32 v[38:39], s[26:27], v37, s44, v[34:35]
	v_mad_i64_i32 v[52:53], s[26:27], v4, s44, v[34:35]
	global_load_dword v4, v[38:39], off nt
	global_load_dword v21, v[40:41], off nt
	global_load_dword v54, v[42:43], off nt
	global_load_dword v55, v[44:45], off nt
	global_load_dword v56, v[46:47], off nt
	global_load_dword v57, v[48:49], off nt
	global_load_dword v58, v[50:51], off nt
	global_load_dword v59, v[52:53], off nt
	v_or_b32_e32 v38, 16, v37
	v_or_b32_e32 v40, 18, v37
	v_or_b32_e32 v42, 20, v37
	v_or_b32_e32 v44, 22, v37
	v_or_b32_e32 v52, 30, v37
	v_mad_i64_i32 v[38:39], s[26:27], v38, s44, v[34:35]
	v_mad_i64_i32 v[40:41], s[26:27], v40, s44, v[34:35]
	v_mad_i64_i32 v[42:43], s[26:27], v42, s44, v[34:35]
	v_mad_i64_i32 v[44:45], s[26:27], v44, s44, v[34:35]
	v_or_b32_e32 v46, 24, v37
	v_or_b32_e32 v48, 26, v37
	v_or_b32_e32 v50, 28, v37
	v_mad_i64_i32 v[52:53], s[26:27], v52, s44, v[34:35]
	v_mad_i64_i32 v[46:47], s[26:27], v46, s44, v[34:35]
	v_mad_i64_i32 v[48:49], s[26:27], v48, s44, v[34:35]
	v_mad_i64_i32 v[50:51], s[26:27], v50, s44, v[34:35]
	global_load_dword v60, v[38:39], off nt
	global_load_dword v61, v[40:41], off nt
	global_load_dword v62, v[42:43], off nt
	global_load_dword v63, v[44:45], off nt
	global_load_dword v64, v[46:47], off nt
	global_load_dword v65, v[48:49], off nt
	global_load_dword v66, v[50:51], off nt
	global_load_dword v67, v[52:53], off nt
	v_or_b32_e32 v38, 32, v37
	v_or_b32_e32 v40, 34, v37
	v_or_b32_e32 v42, 36, v37
	v_or_b32_e32 v44, 38, v37
	v_or_b32_e32 v52, 46, v37
	v_mad_i64_i32 v[38:39], s[26:27], v38, s44, v[34:35]
	v_mad_i64_i32 v[40:41], s[26:27], v40, s44, v[34:35]
	v_mad_i64_i32 v[42:43], s[26:27], v42, s44, v[34:35]
	v_mad_i64_i32 v[44:45], s[26:27], v44, s44, v[34:35]
	v_or_b32_e32 v46, 40, v37
	v_or_b32_e32 v48, 42, v37
	v_or_b32_e32 v50, 44, v37
	v_mad_i64_i32 v[52:53], s[26:27], v52, s44, v[34:35]
	v_mad_i64_i32 v[46:47], s[26:27], v46, s44, v[34:35]
	v_mad_i64_i32 v[48:49], s[26:27], v48, s44, v[34:35]
	v_mad_i64_i32 v[50:51], s[26:27], v50, s44, v[34:35]
	global_load_dword v68, v[38:39], off nt
	global_load_dword v69, v[40:41], off nt
	global_load_dword v70, v[42:43], off nt
	global_load_dword v71, v[44:45], off nt
	global_load_dword v72, v[46:47], off nt
	global_load_dword v73, v[48:49], off nt
	global_load_dword v74, v[50:51], off nt
	s_nop 0
	global_load_dword v52, v[52:53], off nt
	v_or_b32_e32 v38, 48, v37
	v_or_b32_e32 v40, 50, v37
	v_or_b32_e32 v42, 52, v37
	v_or_b32_e32 v44, 54, v37
	v_mad_i64_i32 v[38:39], s[26:27], v38, s44, v[34:35]
	v_mad_i64_i32 v[40:41], s[26:27], v40, s44, v[34:35]
	v_mad_i64_i32 v[42:43], s[26:27], v42, s44, v[34:35]
	v_mad_i64_i32 v[44:45], s[26:27], v44, s44, v[34:35]
	v_or_b32_e32 v46, 56, v37
	v_or_b32_e32 v48, 58, v37
	v_or_b32_e32 v50, 60, v37
	v_or_b32_e32 v37, 62, v37
	v_mad_i64_i32 v[46:47], s[26:27], v46, s44, v[34:35]
	v_mad_i64_i32 v[48:49], s[26:27], v48, s44, v[34:35]
	v_mad_i64_i32 v[50:51], s[26:27], v50, s44, v[34:35]
	v_mad_i64_i32 v[34:35], s[26:27], v37, s44, v[34:35]
	global_load_dword v37, v[38:39], off nt
	s_nop 0
	global_load_dword v38, v[40:41], off nt
	global_load_dword v39, v[42:43], off nt
	s_nop 0
	global_load_dword v40, v[44:45], off nt
	global_load_dword v41, v[46:47], off nt
	global_load_dword v42, v[48:49], off nt
	global_load_dword v43, v[50:51], off nt
	s_nop 0
	global_load_dword v44, v[34:35], off nt
	s_waitcnt vmcnt(30)
	ds_write2_b32 v3, v4, v21 offset1:66
	s_waitcnt vmcnt(28)
	ds_write2_b32 v3, v54, v55 offset0:132 offset1:198
	s_waitcnt vmcnt(26)
	ds_write2_b32 v31, v56, v57 offset0:8 offset1:74
	s_waitcnt vmcnt(24)
	ds_write2_b32 v31, v58, v59 offset0:140 offset1:206
	s_waitcnt vmcnt(22)
	ds_write2_b32 v32, v60, v61 offset0:16 offset1:82
	s_waitcnt vmcnt(20)
	ds_write2_b32 v32, v62, v63 offset0:148 offset1:214
	v_add_u32_e32 v4, 0xc00, v3
	s_waitcnt vmcnt(18)
	ds_write2_b32 v4, v64, v65 offset0:24 offset1:90
	s_waitcnt vmcnt(16)
	ds_write2_b32 v4, v66, v67 offset0:156 offset1:222
	v_add_u32_e32 v4, 0x1000, v3
	s_waitcnt vmcnt(14)
	ds_write2_b32 v4, v68, v69 offset0:32 offset1:98
	s_waitcnt vmcnt(12)
	ds_write2_b32 v4, v70, v71 offset0:164 offset1:230
	v_add_u32_e32 v4, 0x1400, v3
	s_waitcnt vmcnt(10)
; #define LAS __attribute__((address_space(3)))
; #define LDS_WAIT() asm volatile("s_waitcnt lgkmcnt(0)" ::: "memory")
; __device__ __forceinline__ unsigned pk2(float lo, float hi) { return f2bf(lo) | (f2bf(hi) << 16); }
;     ...
;     for (int i = 0; i < 32; ++i) scr[(2 * i + (lane >> 5)) * 33 + (lane & 31)] = tv_[i];
;     LDS_WAIT(); asm volatile("" ::: "memory");
;     const int c = lane & 7;
; #pragma unroll
;     for (int j = 0; j < 4; ++j) { const int n = (lane >> 3) + 8 * j; const LAS float* s = scr + (8 * c) * 33 + n;
;         v4u o; o.x = pk2(s[0 * 33], s[1 * 33]); o.y = pk2(s[2 * 33], s[3 * 33]); o.z = pk2(s[4 * 33], s[5 * 33]); o.w = pk2(s[6 * 33], s[7 * 33]);
;         *(v4u*)(WT + (size_t)(n0 + n) * ldw + koff + k0 + 8 * c) = o; }
;     LDS_WAIT(); asm volatile("" ::: "memory");
; }
	ds_write2_b32 v4, v72, v73 offset0:40 offset1:106
	s_waitcnt vmcnt(8)
	ds_write2_b32 v4, v74, v52 offset0:172 offset1:238
	v_add_u32_e32 v4, 0x1800, v3
	s_waitcnt vmcnt(6)
	ds_write2_b32 v4, v37, v38 offset0:48 offset1:114
	s_waitcnt vmcnt(4)
	ds_write2_b32 v4, v39, v40 offset0:180 offset1:246
	v_add_u32_e32 v4, 0x1c00, v3
	v_mov_b64_e32 v[34:35], s[8:9]
	s_mov_b32 s26, 0x2800000
	s_waitcnt vmcnt(2)
	ds_write2_b32 v4, v41, v42 offset0:56 offset1:122
	s_waitcnt vmcnt(0)
	ds_write2_b32 v4, v43, v44 offset0:188 offset1:254
	v_mad_i64_i32 v[34:35], s[26:27], v33, s26, v[34:35]
	s_waitcnt lgkmcnt(0)
	v_ashrrev_i32_e32 v37, 31, v36
	v_lshl_add_u64 v[34:35], v[36:37], 1, v[34:35]
	v_lshlrev_b32_e32 v4, 1, v6
	v_lshl_add_u64 v[38:39], v[34:35], 0, v[4:5]
	ds_read_b32 v4, v23
	ds_read_b32 v21, v23 offset:132
	ds_read_b32 v33, v23 offset:264
	ds_read_b32 v35, v23 offset:396
	ds_read_b32 v36, v23 offset:528
	ds_read_b32 v37, v23 offset:660
	ds_read_b32 v40, v23 offset:792
	ds_read_b32 v41, v23 offset:924
	s_waitcnt lgkmcnt(0)
	v_bfe_u32 v34, v4, 16, 1
	v_add3_u32 v4, v4, v34, s41
	v_bfe_u32 v34, v21, 16, 1
	v_lshrrev_b32_e32 v4, 16, v4
	v_add3_u32 v21, v21, v34, s41
	v_and_or_b32 v34, v21, s42, v4
	v_bfe_u32 v4, v33, 16, 1
	v_add3_u32 v4, v33, v4, s41
	v_bfe_u32 v21, v35, 16, 1
	v_lshrrev_b32_e32 v4, 16, v4
	v_add3_u32 v21, v35, v21, s41
	v_and_or_b32 v35, v21, s42, v4
	v_bfe_u32 v4, v36, 16, 1
	v_add3_u32 v4, v36, v4, s41
	v_bfe_u32 v21, v37, 16, 1
	v_lshrrev_b32_e32 v4, 16, v4
	v_add3_u32 v21, v37, v21, s41
	v_and_or_b32 v36, v21, s42, v4
	v_bfe_u32 v4, v40, 16, 1
	v_add3_u32 v4, v40, v4, s41
	v_bfe_u32 v21, v41, 16, 1
	v_or_b32_e32 v40, v20, v7
	v_add3_u32 v21, v41, v21, s41
	v_ashrrev_i32_e32 v41, 31, v40
	v_lshrrev_b32_e32 v4, 16, v4
	v_lshlrev_b64 v[40:41], 12, v[40:41]
	v_and_or_b32 v37, v21, s42, v4
	v_lshl_add_u64 v[40:41], v[38:39], 0, v[40:41]
	global_store_dwordx4 v[40:41], v[34:37], off
	ds_read_b32 v4, v23 offset:32
	ds_read_b32 v21, v23 offset:164
	ds_read_b32 v33, v23 offset:296
	ds_read_b32 v35, v23 offset:428
	ds_read_b32 v36, v23 offset:560
	ds_read_b32 v37, v23 offset:692
	ds_read_b32 v40, v23 offset:824
	ds_read_b32 v41, v23 offset:956
	s_waitcnt lgkmcnt(0)
	v_bfe_u32 v34, v4, 16, 1
	v_add3_u32 v4, v4, v34, s41
	v_bfe_u32 v34, v21, 16, 1
	v_lshrrev_b32_e32 v4, 16, v4
	v_add3_u32 v21, v21, v34, s41
	v_and_or_b32 v34, v21, s42, v4
	v_bfe_u32 v4, v33, 16, 1
	v_add3_u32 v4, v33, v4, s41
	v_bfe_u32 v21, v35, 16, 1
	v_lshrrev_b32_e32 v4, 16, v4
	v_add3_u32 v21, v35, v21, s41
	v_and_or_b32 v35, v21, s42, v4
	v_bfe_u32 v4, v36, 16, 1
	v_add3_u32 v4, v36, v4, s41
	v_bfe_u32 v21, v37, 16, 1
	v_lshrrev_b32_e32 v4, 16, v4
	v_add3_u32 v21, v37, v21, s41
	v_and_or_b32 v36, v21, s42, v4
	v_bfe_u32 v4, v40, 16, 1
	v_add3_u32 v4, v40, v4, s41
	v_bfe_u32 v21, v41, 16, 1
	v_or_b32_e32 v40, v20, v24
	v_add3_u32 v21, v41, v21, s41
	v_ashrrev_i32_e32 v41, 31, v40
	v_lshrrev_b32_e32 v4, 16, v4
	v_lshlrev_b64 v[40:41], 12, v[40:41]
	v_and_or_b32 v37, v21, s42, v4
	v_lshl_add_u64 v[40:41], v[38:39], 0, v[40:41]
	global_store_dwordx4 v[40:41], v[34:37], off
	ds_read_b32 v4, v23 offset:64
	ds_read_b32 v21, v23 offset:196
	ds_read_b32 v33, v23 offset:328
	ds_read_b32 v35, v23 offset:460
	ds_read_b32 v36, v23 offset:592
	ds_read_b32 v37, v23 offset:724
	ds_read_b32 v40, v23 offset:856
	ds_read_b32 v41, v23 offset:988
	s_waitcnt lgkmcnt(0)
	v_bfe_u32 v34, v4, 16, 1
	v_add3_u32 v4, v4, v34, s41
	v_bfe_u32 v34, v21, 16, 1
	v_lshrrev_b32_e32 v4, 16, v4
	v_add3_u32 v21, v21, v34, s41
	v_and_or_b32 v34, v21, s42, v4
	v_bfe_u32 v4, v33, 16, 1
	v_add3_u32 v4, v33, v4, s41
	v_bfe_u32 v21, v35, 16, 1
	v_lshrrev_b32_e32 v4, 16, v4
	v_add3_u32 v21, v35, v21, s41
	v_and_or_b32 v35, v21, s42, v4
	v_bfe_u32 v4, v36, 16, 1
	v_add3_u32 v4, v36, v4, s41
	v_bfe_u32 v21, v37, 16, 1
	v_lshrrev_b32_e32 v4, 16, v4
	v_add3_u32 v21, v37, v21, s41
	v_and_or_b32 v36, v21, s42, v4
	v_bfe_u32 v4, v40, 16, 1
	v_add3_u32 v4, v40, v4, s41
	v_bfe_u32 v21, v41, 16, 1
	v_or_b32_e32 v40, v20, v25
	v_add3_u32 v21, v41, v21, s41
	v_ashrrev_i32_e32 v41, 31, v40
	v_lshrrev_b32_e32 v4, 16, v4
	v_lshlrev_b64 v[40:41], 12, v[40:41]
	v_and_or_b32 v37, v21, s42, v4
	v_lshl_add_u64 v[40:41], v[38:39], 0, v[40:41]
	global_store_dwordx4 v[40:41], v[34:37], off
	ds_read_b32 v4, v23 offset:96
	ds_read_b32 v21, v23 offset:228
	ds_read_b32 v33, v23 offset:360
	ds_read_b32 v35, v23 offset:492
	ds_read_b32 v36, v23 offset:624
	ds_read_b32 v37, v23 offset:756
	ds_read_b32 v40, v23 offset:888
	ds_read_b32 v41, v23 offset:1020
	s_waitcnt lgkmcnt(0)
	v_bfe_u32 v34, v4, 16, 1
	v_add3_u32 v4, v4, v34, s41
	v_bfe_u32 v34, v21, 16, 1
	v_lshrrev_b32_e32 v4, 16, v4
	v_add3_u32 v21, v21, v34, s41
	v_and_or_b32 v34, v21, s42, v4
	v_bfe_u32 v4, v33, 16, 1
	v_add3_u32 v4, v33, v4, s41
	v_bfe_u32 v21, v35, 16, 1
	v_lshrrev_b32_e32 v4, 16, v4
	v_add3_u32 v21, v35, v21, s41
	v_and_or_b32 v35, v21, s42, v4
	v_bfe_u32 v4, v36, 16, 1
	v_add3_u32 v4, v36, v4, s41
	v_bfe_u32 v21, v37, 16, 1
	v_lshrrev_b32_e32 v4, 16, v4
	v_add3_u32 v21, v37, v21, s41
	v_and_or_b32 v36, v21, s42, v4
	v_bfe_u32 v4, v40, 16, 1
	v_add3_u32 v4, v40, v4, s41
	v_bfe_u32 v21, v41, 16, 1
	v_lshrrev_b32_e32 v4, 16, v4
	v_add3_u32 v21, v41, v21, s41
	v_or_b32_e32 v20, v20, v26
	v_and_or_b32 v37, v21, s42, v4
	v_ashrrev_i32_e32 v21, 31, v20
	v_lshlrev_b64 v[20:21], 12, v[20:21]
	v_lshl_add_u64 v[20:21], v[38:39], 0, v[20:21]
	global_store_dwordx4 v[20:21], v[34:37], off
	s_waitcnt lgkmcnt(0)
	v_readlane_b32 s61, v251, 22
	v_readlane_b32 s62, v251, 23
	v_readlane_b32 s63, v251, 24
	v_readlane_b32 s64, v251, 25
	v_readlane_b32 s65, v251, 26
	v_readlane_b32 s66, v251, 27
	v_readlane_b32 s67, v251, 28
	v_readlane_b32 s68, v251, 29
	v_readlane_b32 s69, v251, 30
	v_readlane_b32 s72, v251, 33
	v_readlane_b32 s73, v251, 34
	v_readlane_b32 s74, v251, 35
	v_readlane_b32 s75, v251, 36
	s_branch .LBB0_21

; #define LAS __attribute__((address_space(3)))
; #define LDS_WAIT() asm volatile("s_waitcnt lgkmcnt(0)" ::: "memory")
; __device__ __forceinline__ unsigned pk2(float lo, float hi) { return f2bf(lo) | (f2bf(hi) << 16); }
;     if (ldw == 0) ldw = K;
;     const int nblk = N / 32, kb = item / nblk, nb = item % nblk, k0 = 64 * kb, n0 = 32 * nb;
;     float tv_[32];
; #pragma unroll
;     for (int i = 0; i < 32; ++i) tv_[i] = W[(size_t)(k0 + 2 * i + (lane >> 5)) * N + n0 + (lane & 31)];
; #pragma unroll
;     for (int i = 0; i < 32; ++i) scr[(2 * i + (lane >> 5)) * 33 + (lane & 31)] = tv_[i];
;     LDS_WAIT(); asm volatile("" ::: "memory");
;     const int c = lane & 7;
; #pragma unroll
;     for (int j = 0; j < 4; ++j) { const int n = (lane >> 3) + 8 * j; const LAS float* s = scr + (8 * c) * 33 + n;
;         v4u o; o.x = pk2(s[0 * 33], s[1 * 33]); o.y = pk2(s[2 * 33], s[3 * 33]); o.z = pk2(s[4 * 33], s[5 * 33]); o.w = pk2(s[6 * 33], s[7 * 33]);
;         *(v4u*)(WT + (size_t)(n0 + n) * ldw + koff + k0 + 8 * c) = o; }
;     LDS_WAIT(); asm volatile("" ::: "memory");
; }
; __device__ __forceinline__ void convert_range(LAS unsigned char* lds, const Params& p, const int lo, const int hi, const int gw, const int NGW) {
;     ...
;     for (int it = lo + gw; it < hi; it += NGW) {
;         int r = it;
;         if (r < 2 * I_IN) { const int l = r / I_IN; r -= l * I_IN; p0_transpose_item(p.in[5] + (size_t)l * DM * NC, DM, NC, (bf16*)(ws + WS_WIN + l * SZ_WIN), scr, r, lane); continue; } r -= 2 * I_IN;
.LBB0_49:
	v_mul_hi_i32 v10, v28, s7
	v_lshrrev_b32_e32 v11, 31, v10
	v_ashrrev_i32_e32 v10, 12, v10
	v_add_u32_e32 v12, v10, v11
	v_mul_i32_i24_e32 v29, 0xffffd800, v12
	v_add_u32_e32 v29, v29, v28
	v_mul_hi_i32 v30, v29, s7
	v_lshrrev_b32_e32 v31, 31, v30
	v_ashrrev_i32_e32 v30, 7, v30
	v_add_u32_e32 v30, v30, v31
	v_mul_i32_i24_e32 v31, 0x140, v30
	v_lshlrev_b32_e32 v30, 6, v30
	v_sub_u32_e32 v29, v29, v31
	v_mad_i64_i32 v[10:11], s[18:19], v12, s14, v[4:5]
	v_mad_i64_i32 v[12:13], s[18:19], v12, s15, v[6:7]
	v_ashrrev_i32_e32 v31, 31, v30
	v_lshlrev_b32_e32 v32, 5, v29
	v_or_b32_e32 v40, v30, v1
	v_lshl_add_u64 v[12:13], v[30:31], 1, v[12:13]
	v_ashrrev_i32_e32 v33, 31, v32
	v_or_b32_e32 v30, v32, v14
	v_or_b32_e32 v34, v32, v16
	v_or_b32_e32 v36, v32, v17
	v_or_b32_e32 v38, v32, v18
	v_lshl_add_u64 v[10:11], v[32:33], 2, v[10:11]
	v_ashrrev_i32_e32 v31, 31, v30
	v_ashrrev_i32_e32 v35, 31, v34
	v_ashrrev_i32_e32 v37, 31, v36
	v_ashrrev_i32_e32 v39, 31, v38
	v_or_b32_e32 v29, 2, v40
	v_or_b32_e32 v41, 4, v40
	v_or_b32_e32 v42, 6, v40
	v_or_b32_e32 v44, 8, v40
	v_or_b32_e32 v46, 10, v40
	v_or_b32_e32 v48, 12, v40
	v_or_b32_e32 v50, 14, v40
	v_or_b32_e32 v52, 16, v40
	v_or_b32_e32 v54, 18, v40
	v_or_b32_e32 v56, 20, v40
	v_or_b32_e32 v58, 22, v40
	v_or_b32_e32 v60, 24, v40
	v_or_b32_e32 v62, 26, v40
	v_or_b32_e32 v64, 28, v40
	v_or_b32_e32 v66, 30, v40
	v_or_b32_e32 v68, 32, v40
	v_or_b32_e32 v70, 34, v40
	v_or_b32_e32 v72, 36, v40
	v_or_b32_e32 v74, 38, v40
	v_or_b32_e32 v76, 40, v40
	v_or_b32_e32 v78, 42, v40
	v_or_b32_e32 v80, 44, v40
	v_or_b32_e32 v82, 46, v40
	v_or_b32_e32 v84, 48, v40
	v_or_b32_e32 v86, 50, v40
	v_or_b32_e32 v88, 52, v40
	v_or_b32_e32 v90, 54, v40
	v_or_b32_e32 v92, 56, v40
	v_or_b32_e32 v94, 58, v40
	v_or_b32_e32 v96, 60, v40
	v_or_b32_e32 v98, 62, v40
	v_lshl_add_u64 v[12:13], v[12:13], 0, v[8:9]
	v_lshl_add_u64 v[10:11], v[10:11], 0, v[2:3]
	v_lshlrev_b64 v[30:31], 12, v[30:31]
	v_lshlrev_b64 v[32:33], 12, v[34:35]
	v_lshlrev_b64 v[34:35], 12, v[36:37]
	v_lshlrev_b64 v[36:37], 12, v[38:39]
	v_lshl_add_u64 v[30:31], v[12:13], 0, v[30:31]
	v_lshl_add_u64 v[32:33], v[12:13], 0, v[32:33]
	v_lshl_add_u64 v[34:35], v[12:13], 0, v[34:35]
	v_lshl_add_u64 v[36:37], v[12:13], 0, v[36:37]
	v_mad_i64_i32 v[12:13], s[18:19], v40, s12, v[10:11]
	v_mad_i64_i32 v[38:39], s[18:19], v29, s12, v[10:11]
	v_mad_i64_i32 v[40:41], s[18:19], v41, s12, v[10:11]
	v_mad_i64_i32 v[42:43], s[18:19], v42, s12, v[10:11]
	v_mad_i64_i32 v[44:45], s[18:19], v44, s12, v[10:11]
	v_mad_i64_i32 v[46:47], s[18:19], v46, s12, v[10:11]
	v_mad_i64_i32 v[48:49], s[18:19], v48, s12, v[10:11]
	v_mad_i64_i32 v[50:51], s[18:19], v50, s12, v[10:11]
	v_mad_i64_i32 v[52:53], s[18:19], v52, s12, v[10:11]
	v_mad_i64_i32 v[54:55], s[18:19], v54, s12, v[10:11]
	v_mad_i64_i32 v[56:57], s[18:19], v56, s12, v[10:11]
	v_mad_i64_i32 v[58:59], s[18:19], v58, s12, v[10:11]
	v_mad_i64_i32 v[60:61], s[18:19], v60, s12, v[10:11]
	v_mad_i64_i32 v[62:63], s[18:19], v62, s12, v[10:11]
	v_mad_i64_i32 v[64:65], s[18:19], v64, s12, v[10:11]
	v_mad_i64_i32 v[66:67], s[18:19], v66, s12, v[10:11]
	v_mad_i64_i32 v[68:69], s[18:19], v68, s12, v[10:11]
	v_mad_i64_i32 v[70:71], s[18:19], v70, s12, v[10:11]
	v_mad_i64_i32 v[72:73], s[18:19], v72, s12, v[10:11]
	v_mad_i64_i32 v[74:75], s[18:19], v74, s12, v[10:11]
	v_mad_i64_i32 v[76:77], s[18:19], v76, s12, v[10:11]
	v_mad_i64_i32 v[78:79], s[18:19], v78, s12, v[10:11]
	v_mad_i64_i32 v[80:81], s[18:19], v80, s12, v[10:11]
	v_mad_i64_i32 v[82:83], s[18:19], v82, s12, v[10:11]
	v_mad_i64_i32 v[84:85], s[18:19], v84, s12, v[10:11]
	v_mad_i64_i32 v[86:87], s[18:19], v86, s12, v[10:11]
	v_mad_i64_i32 v[88:89], s[18:19], v88, s12, v[10:11]
	v_mad_i64_i32 v[90:91], s[18:19], v90, s12, v[10:11]
	v_mad_i64_i32 v[92:93], s[18:19], v92, s12, v[10:11]
	v_mad_i64_i32 v[94:95], s[18:19], v94, s12, v[10:11]
	v_mad_i64_i32 v[96:97], s[18:19], v96, s12, v[10:11]
	v_mad_i64_i32 v[10:11], s[18:19], v98, s12, v[10:11]
	global_load_dword v12, v[12:13], off nt
	s_nop 0
	global_load_dword v13, v[38:39], off nt
	global_load_dword v29, v[40:41], off nt
	s_nop 0
	global_load_dword v38, v[42:43], off nt
	global_load_dword v39, v[44:45], off nt
	global_load_dword v40, v[46:47], off nt
	global_load_dword v41, v[48:49], off nt
	s_nop 0
	global_load_dword v42, v[50:51], off nt
	global_load_dword v43, v[52:53], off nt
	global_load_dword v44, v[54:55], off nt
	global_load_dword v45, v[56:57], off nt
	global_load_dword v46, v[58:59], off nt
	global_load_dword v47, v[60:61], off nt
	global_load_dword v48, v[62:63], off nt
	global_load_dword v49, v[64:65], off nt
	global_load_dword v50, v[66:67], off nt
	global_load_dword v51, v[68:69], off nt
	global_load_dword v52, v[70:71], off nt
	global_load_dword v53, v[72:73], off nt
	global_load_dword v54, v[74:75], off nt
	global_load_dword v55, v[76:77], off nt
	global_load_dword v56, v[78:79], off nt
	global_load_dword v57, v[80:81], off nt
	global_load_dword v58, v[82:83], off nt
	global_load_dword v59, v[84:85], off nt
	global_load_dword v60, v[86:87], off nt
	global_load_dword v61, v[88:89], off nt
	global_load_dword v62, v[90:91], off nt
	global_load_dword v63, v[92:93], off nt
	global_load_dword v64, v[94:95], off nt
	global_load_dword v65, v[96:97], off nt
	s_nop 0
	global_load_dword v10, v[10:11], off nt
	s_waitcnt vmcnt(30)
	ds_write2_b32 v19, v12, v13 offset1:66
	s_waitcnt vmcnt(28)
	ds_write2_b32 v19, v29, v38 offset0:132 offset1:198
	s_waitcnt vmcnt(26)
; #define LAS __attribute__((address_space(3)))
; #define LDS_WAIT() asm volatile("s_waitcnt lgkmcnt(0)" ::: "memory")
; __device__ __forceinline__ unsigned pk2(float lo, float hi) { return f2bf(lo) | (f2bf(hi) << 16); }
;     ...
;     for (int i = 0; i < 32; ++i) scr[(2 * i + (lane >> 5)) * 33 + (lane & 31)] = tv_[i];
;     LDS_WAIT(); asm volatile("" ::: "memory");
;     const int c = lane & 7;
; #pragma unroll
;     for (int j = 0; j < 4; ++j) { const int n = (lane >> 3) + 8 * j; const LAS float* s = scr + (8 * c) * 33 + n;
;         v4u o; o.x = pk2(s[0 * 33], s[1 * 33]); o.y = pk2(s[2 * 33], s[3 * 33]); o.z = pk2(s[4 * 33], s[5 * 33]); o.w = pk2(s[6 * 33], s[7 * 33]);
;         *(v4u*)(WT + (size_t)(n0 + n) * ldw + koff + k0 + 8 * c) = o; }
;     LDS_WAIT(); asm volatile("" ::: "memory");
; }
; __device__ __forceinline__ void convert_range(LAS unsigned char* lds, const Params& p, const int lo, const int hi, const int gw, const int NGW) {
;     ...
;     for (int it = lo + gw; it < hi; it += NGW) {
	ds_write2_b32 v20, v39, v40 offset0:8 offset1:74
	s_waitcnt vmcnt(24)
	ds_write2_b32 v20, v41, v42 offset0:140 offset1:206
	s_waitcnt vmcnt(22)
	ds_write2_b32 v21, v43, v44 offset0:16 offset1:82
	s_waitcnt vmcnt(20)
	ds_write2_b32 v21, v45, v46 offset0:148 offset1:214
	s_waitcnt vmcnt(18)
	ds_write2_b32 v23, v47, v48 offset0:24 offset1:90
	s_waitcnt vmcnt(16)
	ds_write2_b32 v23, v49, v50 offset0:156 offset1:222
	s_waitcnt vmcnt(14)
	ds_write2_b32 v24, v51, v52 offset0:32 offset1:98
	s_waitcnt vmcnt(12)
	ds_write2_b32 v24, v53, v54 offset0:164 offset1:230
	s_waitcnt vmcnt(10)
	ds_write2_b32 v25, v55, v56 offset0:40 offset1:106
	s_waitcnt vmcnt(8)
	ds_write2_b32 v25, v57, v58 offset0:172 offset1:238
	s_waitcnt vmcnt(6)
	ds_write2_b32 v26, v59, v60 offset0:48 offset1:114
	s_waitcnt vmcnt(4)
	ds_write2_b32 v26, v61, v62 offset0:180 offset1:246
	s_waitcnt vmcnt(2)
	ds_write2_b32 v27, v63, v64 offset0:56 offset1:122
	s_waitcnt vmcnt(0)
	ds_write2_b32 v27, v65, v10 offset0:188 offset1:254
	s_waitcnt lgkmcnt(0)
	ds_read_b32 v10, v15
	ds_read_b32 v11, v15 offset:132
	ds_read_b32 v12, v15 offset:264
	ds_read_b32 v13, v15 offset:396
	ds_read_b32 v29, v15 offset:528
	ds_read_b32 v38, v15 offset:660
	ds_read_b32 v39, v15 offset:792
	ds_read_b32 v40, v15 offset:924
	s_waitcnt lgkmcnt(0)
	v_bfe_u32 v41, v10, 16, 1
	v_bfe_u32 v43, v12, 16, 1
	v_bfe_u32 v45, v29, 16, 1
	v_bfe_u32 v47, v39, 16, 1
	v_bfe_u32 v42, v11, 16, 1
	v_bfe_u32 v44, v13, 16, 1
	v_bfe_u32 v46, v38, 16, 1
	v_bfe_u32 v48, v40, 16, 1
	v_add3_u32 v10, v10, v41, s13
	v_add3_u32 v12, v12, v43, s13
	v_add3_u32 v29, v29, v45, s13
	v_add3_u32 v39, v39, v47, s13
	v_add3_u32 v11, v11, v42, s13
	v_add3_u32 v13, v13, v44, s13
	v_add3_u32 v38, v38, v46, s13
	v_add3_u32 v40, v40, v48, s13
	v_lshrrev_b32_e32 v10, 16, v10
	v_lshrrev_b32_e32 v12, 16, v12
	v_lshrrev_b32_e32 v29, 16, v29
	v_lshrrev_b32_e32 v39, 16, v39
	v_and_or_b32 v10, v11, s16, v10
	v_and_or_b32 v11, v13, s16, v12
	v_and_or_b32 v12, v38, s16, v29
	v_and_or_b32 v13, v40, s16, v39
	global_store_dwordx4 v[30:31], v[10:13], off
	ds_read_b32 v10, v15 offset:32
	ds_read_b32 v11, v15 offset:164
	ds_read_b32 v12, v15 offset:296
	ds_read_b32 v13, v15 offset:428
	ds_read_b32 v29, v15 offset:560
	ds_read_b32 v30, v15 offset:692
	ds_read_b32 v31, v15 offset:824
	ds_read_b32 v38, v15 offset:956
	s_waitcnt lgkmcnt(0)
	v_bfe_u32 v39, v10, 16, 1
	v_bfe_u32 v41, v12, 16, 1
	v_bfe_u32 v43, v29, 16, 1
	v_bfe_u32 v45, v31, 16, 1
	v_bfe_u32 v40, v11, 16, 1
	v_bfe_u32 v42, v13, 16, 1
	v_bfe_u32 v44, v30, 16, 1
	v_bfe_u32 v46, v38, 16, 1
	v_add3_u32 v10, v10, v39, s13
	v_add3_u32 v12, v12, v41, s13
	v_add3_u32 v29, v29, v43, s13
	v_add3_u32 v31, v31, v45, s13
	v_add3_u32 v11, v11, v40, s13
	v_add3_u32 v13, v13, v42, s13
	v_add3_u32 v30, v30, v44, s13
	v_add3_u32 v38, v38, v46, s13
	v_lshrrev_b32_e32 v10, 16, v10
	v_lshrrev_b32_e32 v12, 16, v12
	v_lshrrev_b32_e32 v29, 16, v29
	v_lshrrev_b32_e32 v31, 16, v31
	v_and_or_b32 v10, v11, s16, v10
	v_and_or_b32 v11, v13, s16, v12
	v_and_or_b32 v12, v30, s16, v29
	v_and_or_b32 v13, v38, s16, v31
	global_store_dwordx4 v[32:33], v[10:13], off
	ds_read_b32 v10, v15 offset:64
	ds_read_b32 v11, v15 offset:196
	ds_read_b32 v12, v15 offset:328
	ds_read_b32 v13, v15 offset:460
	ds_read_b32 v29, v15 offset:592
	ds_read_b32 v30, v15 offset:724
	ds_read_b32 v31, v15 offset:856
	ds_read_b32 v32, v15 offset:988
	s_waitcnt lgkmcnt(0)
	v_bfe_u32 v33, v10, 16, 1
	v_bfe_u32 v39, v12, 16, 1
	v_bfe_u32 v41, v29, 16, 1
	v_bfe_u32 v43, v31, 16, 1
	v_bfe_u32 v38, v11, 16, 1
	v_bfe_u32 v40, v13, 16, 1
	v_bfe_u32 v42, v30, 16, 1
	v_bfe_u32 v44, v32, 16, 1
	v_add3_u32 v10, v10, v33, s13
	v_add3_u32 v12, v12, v39, s13
	v_add3_u32 v29, v29, v41, s13
	v_add3_u32 v31, v31, v43, s13
	v_add3_u32 v11, v11, v38, s13
	v_add3_u32 v13, v13, v40, s13
	v_add3_u32 v30, v30, v42, s13
	v_add3_u32 v32, v32, v44, s13
	v_lshrrev_b32_e32 v10, 16, v10
	v_lshrrev_b32_e32 v12, 16, v12
	v_lshrrev_b32_e32 v29, 16, v29
	v_lshrrev_b32_e32 v31, 16, v31
	v_and_or_b32 v10, v11, s16, v10
	v_and_or_b32 v11, v13, s16, v12
	v_and_or_b32 v12, v30, s16, v29
	v_and_or_b32 v13, v32, s16, v31
	global_store_dwordx4 v[34:35], v[10:13], off
	ds_read_b32 v10, v15 offset:96
	ds_read_b32 v11, v15 offset:228
	ds_read_b32 v12, v15 offset:360
	ds_read_b32 v13, v15 offset:492
	ds_read_b32 v29, v15 offset:624
	ds_read_b32 v30, v15 offset:756
	ds_read_b32 v31, v15 offset:888
	ds_read_b32 v32, v15 offset:1020
	s_waitcnt lgkmcnt(0)
	v_bfe_u32 v33, v10, 16, 1
	v_bfe_u32 v35, v12, 16, 1
	v_bfe_u32 v39, v29, 16, 1
	v_bfe_u32 v41, v31, 16, 1
	v_bfe_u32 v34, v11, 16, 1
	v_bfe_u32 v38, v13, 16, 1
	v_bfe_u32 v40, v30, 16, 1
	v_bfe_u32 v42, v32, 16, 1
	v_add3_u32 v10, v10, v33, s13
	v_add3_u32 v12, v12, v35, s13
	v_add3_u32 v29, v29, v39, s13
	v_add3_u32 v31, v31, v41, s13
	v_add3_u32 v11, v11, v34, s13
	v_add3_u32 v13, v13, v38, s13
	v_add3_u32 v30, v30, v40, s13
	v_add3_u32 v32, v32, v42, s13
	v_lshrrev_b32_e32 v10, 16, v10
	v_lshrrev_b32_e32 v12, 16, v12
	v_lshrrev_b32_e32 v29, 16, v29
	v_lshrrev_b32_e32 v31, 16, v31
	v_and_or_b32 v10, v11, s16, v10
	v_and_or_b32 v11, v13, s16, v12
	v_and_or_b32 v12, v30, s16, v29
	v_and_or_b32 v13, v32, s16, v31
	global_store_dwordx4 v[36:37], v[10:13], off
	s_waitcnt lgkmcnt(0)
	v_add_u32_e32 v28, s6, v28
	v_cmp_lt_i32_e32 vcc, s17, v28
	s_or_b64 s[10:11], vcc, s[10:11]
	s_andn2_b64 exec, exec, s[10:11]
	s_cbranch_execnz .LBB0_49

; #define LAS __attribute__((address_space(3)))
;     if (ldw == 0) ldw = K;
;     const int nblk = N / 32, kb = item / nblk, nb = item % nblk, k0 = 64 * kb, n0 = 32 * nb;
;     float tv_[32];
; #pragma unroll
;     for (int i = 0; i < 32; ++i) tv_[i] = W[(size_t)(k0 + 2 * i + (lane >> 5)) * N + n0 + (lane & 31)];
; #pragma unroll
;     for (int i = 0; i < 32; ++i) scr[(2 * i + (lane >> 5)) * 33 + (lane & 31)] = tv_[i];
;     LDS_WAIT(); asm volatile("" ::: "memory");
;     const int c = lane & 7;
; #pragma unroll
;     for (int j = 0; j < 4; ++j) { const int n = (lane >> 3) + 8 * j; const LAS float* s = scr + (8 * c) * 33 + n;
;         v4u o; o.x = pk2(s[0 * 33], s[1 * 33]); o.y = pk2(s[2 * 33], s[3 * 33]); o.z = pk2(s[4 * 33], s[5 * 33]); o.w = pk2(s[6 * 33], s[7 * 33]);
;         *(v4u*)(WT + (size_t)(n0 + n) * ldw + koff + k0 + 8 * c) = o; }
;     LDS_WAIT(); asm volatile("" ::: "memory");
; }
; __device__ __forceinline__ void convert_range(LAS unsigned char* lds, const Params& p, const int lo, const int hi, const int gw, const int NGW) {
;     ...
;     for (int it = lo + gw; it < hi; it += NGW) {
;         int r = it;
;         if (r < 2 * I_IN) { const int l = r / I_IN; r -= l * I_IN; p0_transpose_item(p.in[5] + (size_t)l * DM * NC, DM, NC, (bf16*)(ws + WS_WIN + l * SZ_WIN), scr, r, lane); continue; } r -= 2 * I_IN;
;         if (r < 2 * I_PA) { const int l = r / I_PA; r -= l * I_PA; p0_transpose_item(p.in[16] + (size_t)l * PW * DM, PW, DM, (bf16*)(ws + WS_WCAT + l * SZ_WCAT), scr, r, lane, KCAT, 0); continue; } r -= 2 * I_PA;
;         if (r < 2 * I_PB) { const int l = r / I_PB; r -= l * I_PB; p0_transpose_item(p.in[17] + (size_t)l * LW * DM, LW, DM, (bf16*)(ws + WS_WCAT + l * SZ_WCAT), scr, r, lane, KCAT, PW); continue; } r -= 2 * I_PB;
;         if (r < 2 * I_OUT) { const int l = r / I_OUT; r -= l * I_OUT; p0_transpose_item(p.in[18] + (size_t)l * DM * DM, DM, DM, (bf16*)(ws + WS_WOUT + l * SZ_WOUT), scr, r, lane); continue; } r -= 2 * I_OUT;
;         if (r < I_PL) { const int mi = r / 32; r -= mi * 32; p0_transpose_item(p.in[7] + (size_t)mi * 65536, 256, 256, (bf16*)(ws + WS_POOLW) + (size_t)mi * 65536, scr, r, lane); continue; } r -= I_PL;
;         if (r < I_LR) { const int mi = r / 8; r -= mi * 8; p0_transpose_item(p.in[11] + (size_t)mi * 16384, 128, 128, (bf16*)(ws + WS_WA) + (size_t)mi * 16384, scr, r, lane); continue; } r -= I_LR;
.LBB0_53:
	v_add_u32_e32 v20, 0x7a00, v27
	s_movk_i32 s24, 0x4fff
	v_cmp_lt_i32_e32 vcc, s24, v20
	s_and_saveexec_b64 s[24:25], vcc
	s_xor_b64 s[24:25], exec, s[24:25]
	s_cbranch_execz .LBB0_75
	s_movk_i32 s26, 0x57ff
	v_cmp_lt_u32_e32 vcc, s26, v20
	s_and_saveexec_b64 s[26:27], vcc
	s_xor_b64 s[26:27], exec, s[26:27]
	s_cbranch_execz .LBB0_72
	s_movk_i32 s28, 0x67ff
	v_cmp_lt_u32_e32 vcc, s28, v20
	s_and_saveexec_b64 s[28:29], vcc
	s_xor_b64 s[28:29], exec, s[28:29]
	s_cbranch_execz .LBB0_69
	s_movk_i32 s30, 0x77ff
	v_cmp_lt_u32_e32 vcc, s30, v20
	s_and_saveexec_b64 s[30:31], vcc
	s_xor_b64 s[30:31], exec, s[30:31]
	s_cbranch_execz .LBB0_66
	s_movk_i32 s34, 0x78ff
	v_cmp_lt_u32_e32 vcc, s34, v20
	s_and_saveexec_b64 s[34:35], vcc
	s_xor_b64 s[34:35], exec, s[34:35]
	s_cbranch_execz .LBB0_63
	s_movk_i32 s36, 0x79ff
	v_cmp_lt_u32_e32 vcc, s36, v20
	v_and_b32_e32 v20, 64, v28
	v_or_b32_e32 v4, v20, v1
	v_lshlrev_b32_e32 v21, 7, v4
	s_and_saveexec_b64 s[36:37], vcc
	s_xor_b64 s[36:37], exec, s[36:37]
	s_cbranch_execz .LBB0_60
	v_lshrrev_b32_e32 v4, 3, v27
	v_lshlrev_b64 v[36:37], 16, v[4:5]
	v_lshlrev_b64 v[34:35], 15, v[4:5]
	v_lshl_add_u64 v[36:37], v[16:17], 0, v[36:37]
	v_lshlrev_b32_e32 v4, 2, v21
	v_lshl_add_u64 v[36:37], v[36:37], 0, v[4:5]
	v_add_co_u32_e32 v38, vcc, 0x1000, v36
	v_add_u32_e32 v66, 0x1000, v3
	s_nop 0
	v_addc_co_u32_e32 v39, vcc, 0, v37, vcc
	global_load_dword v4, v[36:37], off nt
	global_load_dword v21, v[36:37], off offset:1024 nt
	global_load_dword v33, v[36:37], off offset:2048 nt
	global_load_dword v42, v[36:37], off offset:3072 nt
	global_load_dword v43, v[38:39], off nt
	global_load_dword v44, v[38:39], off offset:1024 nt
	global_load_dword v45, v[38:39], off offset:2048 nt
	global_load_dword v46, v[38:39], off offset:3072 nt
	v_add_co_u32_e32 v38, vcc, 0x2000, v36
	v_add_u32_e32 v67, 0x1400, v3
	s_nop 0
	v_addc_co_u32_e32 v39, vcc, 0, v37, vcc
	v_add_co_u32_e32 v40, vcc, 0x3000, v36
	v_add_u32_e32 v68, 0x1800, v3
	s_nop 0
	v_addc_co_u32_e32 v41, vcc, 0, v37, vcc
	global_load_dword v47, v[38:39], off nt
	global_load_dword v48, v[38:39], off offset:1024 nt
	global_load_dword v49, v[38:39], off offset:2048 nt
	global_load_dword v50, v[38:39], off offset:3072 nt
	global_load_dword v51, v[40:41], off nt
	global_load_dword v52, v[40:41], off offset:1024 nt
	global_load_dword v53, v[40:41], off offset:2048 nt
	global_load_dword v54, v[40:41], off offset:3072 nt
	v_add_co_u32_e32 v38, vcc, 0x4000, v36
	v_add_u32_e32 v69, 0x1c00, v3
	s_nop 0
	v_addc_co_u32_e32 v39, vcc, 0, v37, vcc
	v_add_co_u32_e32 v40, vcc, 0x5000, v36
	v_lshl_add_u64 v[34:35], s[12:13], 0, v[34:35]
	s_nop 0
	v_addc_co_u32_e32 v41, vcc, 0, v37, vcc
	global_load_dword v55, v[38:39], off nt
	global_load_dword v56, v[38:39], off offset:1024 nt
	global_load_dword v57, v[38:39], off offset:2048 nt
	global_load_dword v58, v[38:39], off offset:3072 nt
	global_load_dword v59, v[40:41], off nt
	global_load_dword v60, v[40:41], off offset:1024 nt
	global_load_dword v61, v[40:41], off offset:2048 nt
	s_nop 0
	global_load_dword v40, v[40:41], off offset:3072 nt
	v_add_co_u32_e32 v38, vcc, 0x6000, v36
	s_nop 1
	v_addc_co_u32_e32 v39, vcc, 0, v37, vcc
	v_add_co_u32_e32 v36, vcc, 0x7000, v36
	s_nop 1
	v_addc_co_u32_e32 v37, vcc, 0, v37, vcc
	global_load_dword v41, v[38:39], off nt
	global_load_dword v62, v[38:39], off offset:1024 nt
	global_load_dword v63, v[38:39], off offset:2048 nt
	s_nop 0
	global_load_dword v38, v[38:39], off offset:3072 nt
	s_nop 0
	global_load_dword v39, v[36:37], off nt
	global_load_dword v64, v[36:37], off offset:1024 nt
	global_load_dword v65, v[36:37], off offset:2048 nt
	s_nop 0
	global_load_dword v36, v[36:37], off offset:3072 nt
	v_add_u32_e32 v37, 0xc00, v3
	s_waitcnt vmcnt(30)
	ds_write2_b32 v3, v4, v21 offset1:66
	s_waitcnt vmcnt(28)
	ds_write2_b32 v3, v33, v42 offset0:132 offset1:198
	s_waitcnt vmcnt(26)
	ds_write2_b32 v31, v43, v44 offset0:8 offset1:74
	s_waitcnt vmcnt(24)
	ds_write2_b32 v31, v45, v46 offset0:140 offset1:206
	s_waitcnt vmcnt(22)
	ds_write2_b32 v32, v47, v48 offset0:16 offset1:82
	s_waitcnt vmcnt(20)
	ds_write2_b32 v32, v49, v50 offset0:148 offset1:214
	s_waitcnt vmcnt(18)
	ds_write2_b32 v37, v51, v52 offset0:24 offset1:90
	s_waitcnt vmcnt(16)
	ds_write2_b32 v37, v53, v54 offset0:156 offset1:222
	s_waitcnt vmcnt(14)
	ds_write2_b32 v66, v55, v56 offset0:32 offset1:98
	s_waitcnt vmcnt(12)
	ds_write2_b32 v66, v57, v58 offset0:164 offset1:230
	s_waitcnt vmcnt(10)
	ds_write2_b32 v67, v59, v60 offset0:40 offset1:106
	s_waitcnt vmcnt(8)
	ds_write2_b32 v67, v61, v40 offset0:172 offset1:238
	s_waitcnt vmcnt(6)
	ds_write2_b32 v68, v41, v62 offset0:48 offset1:114
	s_waitcnt vmcnt(4)
	ds_write2_b32 v68, v63, v38 offset0:180 offset1:246
	s_waitcnt vmcnt(2)
	ds_write2_b32 v69, v39, v64 offset0:56 offset1:122
	s_waitcnt vmcnt(0)
	ds_write2_b32 v69, v65, v36 offset0:188 offset1:254
	s_waitcnt lgkmcnt(0)
	v_lshlrev_b32_e32 v4, 1, v20
	v_lshl_add_u64 v[20:21], v[34:35], 0, v[4:5]
	v_lshlrev_b32_e32 v4, 1, v6
	v_lshl_add_u64 v[20:21], v[20:21], 0, v[4:5]
	ds_read_b32 v4, v23
	ds_read_b32 v33, v23 offset:132
	ds_read_b32 v35, v23 offset:264
	ds_read_b32 v36, v23 offset:396
	ds_read_b32 v37, v23 offset:528
	ds_read_b32 v38, v23 offset:660
	ds_read_b32 v39, v23 offset:792
	ds_read_b32 v40, v23 offset:924
	s_waitcnt lgkmcnt(0)
; #define LAS __attribute__((address_space(3)))
; #define LDS_WAIT() asm volatile("s_waitcnt lgkmcnt(0)" ::: "memory")
; __device__ __forceinline__ unsigned pk2(float lo, float hi) { return f2bf(lo) | (f2bf(hi) << 16); }
;     ...
;     for (int i = 0; i < 32; ++i) scr[(2 * i + (lane >> 5)) * 33 + (lane & 31)] = tv_[i];
;     LDS_WAIT(); asm volatile("" ::: "memory");
;     const int c = lane & 7;
; #pragma unroll
;     for (int j = 0; j < 4; ++j) { const int n = (lane >> 3) + 8 * j; const LAS float* s = scr + (8 * c) * 33 + n;
;         v4u o; o.x = pk2(s[0 * 33], s[1 * 33]); o.y = pk2(s[2 * 33], s[3 * 33]); o.z = pk2(s[4 * 33], s[5 * 33]); o.w = pk2(s[6 * 33], s[7 * 33]);
;         *(v4u*)(WT + (size_t)(n0 + n) * ldw + koff + k0 + 8 * c) = o; }
;     LDS_WAIT(); asm volatile("" ::: "memory");
; __device__ __forceinline__ void convert_range(LAS unsigned char* lds, const Params& p, const int lo, const int hi, const int gw, const int NGW) {
;     ...
;         if (r < I_LR) { const int mi = r / 8; r -= mi * 8; p0_transpose_item(p.in[11] + (size_t)mi * 16384, 128, 128, (bf16*)(ws + WS_WA) + (size_t)mi * 16384, scr, r, lane); continue; } r -= I_LR;
;         { const int mi = r / 8; r -= mi * 8; p0_transpose_item(p.in[13] + (size_t)mi * 16384, 128, 128, (bf16*)(ws + WS_WX) + (size_t)mi * 16384, scr, r, lane); }
	v_bfe_u32 v34, v4, 16, 1
	v_add3_u32 v4, v4, v34, s38
	v_bfe_u32 v34, v33, 16, 1
	v_lshrrev_b32_e32 v4, 16, v4
	v_add3_u32 v33, v33, v34, s38
	v_and_or_b32 v34, v33, s39, v4
	v_bfe_u32 v4, v35, 16, 1
	v_add3_u32 v4, v35, v4, s38
	v_bfe_u32 v33, v36, 16, 1
	v_lshrrev_b32_e32 v4, 16, v4
	v_add3_u32 v33, v36, v33, s38
	v_and_or_b32 v35, v33, s39, v4
	v_bfe_u32 v4, v37, 16, 1
	v_add3_u32 v4, v37, v4, s38
	v_bfe_u32 v33, v38, 16, 1
	v_lshrrev_b32_e32 v4, 16, v4
	v_add3_u32 v33, v38, v33, s38
	v_and_or_b32 v36, v33, s39, v4
	v_bfe_u32 v4, v39, 16, 1
	v_add3_u32 v4, v39, v4, s38
	v_bfe_u32 v33, v40, 16, 1
	v_lshrrev_b32_e32 v4, 16, v4
	v_add3_u32 v33, v40, v33, s38
	v_and_or_b32 v37, v33, s39, v4
	v_lshl_add_u64 v[38:39], v[20:21], 0, v[8:9]
	global_store_dwordx4 v[38:39], v[34:37], off
	ds_read_b32 v4, v23 offset:32
	ds_read_b32 v33, v23 offset:164
	ds_read_b32 v35, v23 offset:296
	ds_read_b32 v36, v23 offset:428
	ds_read_b32 v37, v23 offset:560
	ds_read_b32 v38, v23 offset:692
	ds_read_b32 v39, v23 offset:824
	ds_read_b32 v40, v23 offset:956
	s_waitcnt lgkmcnt(0)
	v_bfe_u32 v34, v4, 16, 1
	v_add3_u32 v4, v4, v34, s38
	v_bfe_u32 v34, v33, 16, 1
	v_lshrrev_b32_e32 v4, 16, v4
	v_add3_u32 v33, v33, v34, s38
	v_and_or_b32 v34, v33, s39, v4
	v_bfe_u32 v4, v35, 16, 1
	v_add3_u32 v4, v35, v4, s38
	v_bfe_u32 v33, v36, 16, 1
	v_lshrrev_b32_e32 v4, 16, v4
	v_add3_u32 v33, v36, v33, s38
	v_and_or_b32 v35, v33, s39, v4
	v_bfe_u32 v4, v37, 16, 1
	v_add3_u32 v4, v37, v4, s38
	v_bfe_u32 v33, v38, 16, 1
	v_lshrrev_b32_e32 v4, 16, v4
	v_add3_u32 v33, v38, v33, s38
	v_and_or_b32 v36, v33, s39, v4
	v_bfe_u32 v4, v39, 16, 1
	v_add3_u32 v4, v39, v4, s38
	v_bfe_u32 v33, v40, 16, 1
	v_lshrrev_b32_e32 v4, 16, v4
	v_add3_u32 v33, v40, v33, s38
	v_and_or_b32 v37, v33, s39, v4
	v_lshl_add_u64 v[38:39], v[20:21], 0, v[10:11]
	global_store_dwordx4 v[38:39], v[34:37], off
	ds_read_b32 v4, v23 offset:64
	ds_read_b32 v33, v23 offset:196
	ds_read_b32 v35, v23 offset:328
	ds_read_b32 v36, v23 offset:460
	ds_read_b32 v37, v23 offset:592
	ds_read_b32 v38, v23 offset:724
	ds_read_b32 v39, v23 offset:856
	ds_read_b32 v40, v23 offset:988
	s_waitcnt lgkmcnt(0)
	v_bfe_u32 v34, v4, 16, 1
	v_add3_u32 v4, v4, v34, s38
	v_bfe_u32 v34, v33, 16, 1
	v_lshrrev_b32_e32 v4, 16, v4
	v_add3_u32 v33, v33, v34, s38
	v_and_or_b32 v34, v33, s39, v4
	v_bfe_u32 v4, v35, 16, 1
	v_add3_u32 v4, v35, v4, s38
	v_bfe_u32 v33, v36, 16, 1
	v_lshrrev_b32_e32 v4, 16, v4
	v_add3_u32 v33, v36, v33, s38
	v_and_or_b32 v35, v33, s39, v4
	v_bfe_u32 v4, v37, 16, 1
	v_add3_u32 v4, v37, v4, s38
	v_bfe_u32 v33, v38, 16, 1
	v_lshrrev_b32_e32 v4, 16, v4
	v_add3_u32 v33, v38, v33, s38
	v_and_or_b32 v36, v33, s39, v4
	v_bfe_u32 v4, v39, 16, 1
	v_add3_u32 v4, v39, v4, s38
	v_bfe_u32 v33, v40, 16, 1
	v_lshrrev_b32_e32 v4, 16, v4
	v_add3_u32 v33, v40, v33, s38
	v_and_or_b32 v37, v33, s39, v4
	v_lshl_add_u64 v[38:39], v[20:21], 0, v[12:13]
	global_store_dwordx4 v[38:39], v[34:37], off
	ds_read_b32 v4, v23 offset:96
	ds_read_b32 v33, v23 offset:228
	ds_read_b32 v35, v23 offset:360
	ds_read_b32 v36, v23 offset:492
	ds_read_b32 v37, v23 offset:624
	ds_read_b32 v38, v23 offset:756
	ds_read_b32 v39, v23 offset:888
	ds_read_b32 v40, v23 offset:1020
	s_waitcnt lgkmcnt(0)
	v_bfe_u32 v34, v4, 16, 1
	v_add3_u32 v4, v4, v34, s38
	v_bfe_u32 v34, v33, 16, 1
	v_lshrrev_b32_e32 v4, 16, v4
	v_add3_u32 v33, v33, v34, s38
	v_and_or_b32 v34, v33, s39, v4
	v_bfe_u32 v4, v35, 16, 1
	v_add3_u32 v4, v35, v4, s38
	v_bfe_u32 v33, v36, 16, 1
	v_lshrrev_b32_e32 v4, 16, v4
	v_add3_u32 v33, v36, v33, s38
	v_and_or_b32 v35, v33, s39, v4
	v_bfe_u32 v4, v37, 16, 1
	v_add3_u32 v4, v37, v4, s38
	v_bfe_u32 v33, v38, 16, 1
	v_lshrrev_b32_e32 v4, 16, v4
	v_add3_u32 v33, v38, v33, s38
	v_and_or_b32 v36, v33, s39, v4
	v_bfe_u32 v4, v39, 16, 1
	v_add3_u32 v4, v39, v4, s38
	v_bfe_u32 v33, v40, 16, 1
	v_lshrrev_b32_e32 v4, 16, v4
	v_add3_u32 v33, v40, v33, s38
	v_and_or_b32 v37, v33, s39, v4
	v_lshl_add_u64 v[20:21], v[20:21], 0, v[14:15]
	global_store_dwordx4 v[20:21], v[34:37], off
	s_waitcnt lgkmcnt(0)
.LBB0_60:
	s_andn2_saveexec_b64 s[36:37], s[36:37]
	s_cbranch_execz .LBB0_62
	v_add_u32_e32 v4, 0x100, v27
	v_lshrrev_b32_e32 v4, 3, v4
	v_lshlrev_b64 v[36:37], 16, v[4:5]
	v_lshlrev_b64 v[34:35], 15, v[4:5]
	v_lshl_add_u64 v[36:37], v[18:19], 0, v[36:37]
	v_lshlrev_b32_e32 v4, 2, v21
	v_lshl_add_u64 v[36:37], v[36:37], 0, v[4:5]
	v_add_co_u32_e32 v38, vcc, 0x1000, v36
	v_add_u32_e32 v66, 0x1000, v3
	s_nop 0
	v_addc_co_u32_e32 v39, vcc, 0, v37, vcc
	global_load_dword v4, v[36:37], off nt
	global_load_dword v21, v[36:37], off offset:1024 nt
	global_load_dword v33, v[36:37], off offset:2048 nt
	global_load_dword v42, v[36:37], off offset:3072 nt
	global_load_dword v43, v[38:39], off nt
	global_load_dword v44, v[38:39], off offset:1024 nt
	global_load_dword v45, v[38:39], off offset:2048 nt
	global_load_dword v46, v[38:39], off offset:3072 nt
	v_add_co_u32_e32 v38, vcc, 0x2000, v36
	v_add_u32_e32 v67, 0x1400, v3
	s_nop 0
	v_addc_co_u32_e32 v39, vcc, 0, v37, vcc
	v_add_co_u32_e32 v40, vcc, 0x3000, v36
	v_add_u32_e32 v68, 0x1800, v3
	s_nop 0
	v_addc_co_u32_e32 v41, vcc, 0, v37, vcc
	global_load_dword v47, v[38:39], off nt
	global_load_dword v48, v[38:39], off offset:1024 nt
	global_load_dword v49, v[38:39], off offset:2048 nt
	global_load_dword v50, v[38:39], off offset:3072 nt
	global_load_dword v51, v[40:41], off nt
	global_load_dword v52, v[40:41], off offset:1024 nt
	global_load_dword v53, v[40:41], off offset:2048 nt
	global_load_dword v54, v[40:41], off offset:3072 nt
	v_add_co_u32_e32 v38, vcc, 0x4000, v36
	v_add_u32_e32 v69, 0x1c00, v3
	s_nop 0
	v_addc_co_u32_e32 v39, vcc, 0, v37, vcc
	v_add_co_u32_e32 v40, vcc, 0x5000, v36
	v_lshl_add_u64 v[34:35], s[14:15], 0, v[34:35]
	s_nop 0
	v_addc_co_u32_e32 v41, vcc, 0, v37, vcc
	global_load_dword v55, v[38:39], off nt
	global_load_dword v56, v[38:39], off offset:1024 nt
	global_load_dword v57, v[38:39], off offset:2048 nt
	global_load_dword v58, v[38:39], off offset:3072 nt
	global_load_dword v59, v[40:41], off nt
	global_load_dword v60, v[40:41], off offset:1024 nt
	global_load_dword v61, v[40:41], off offset:2048 nt
	s_nop 0
	global_load_dword v40, v[40:41], off offset:3072 nt
	v_add_co_u32_e32 v38, vcc, 0x6000, v36
	s_nop 1
	v_addc_co_u32_e32 v39, vcc, 0, v37, vcc
	v_add_co_u32_e32 v36, vcc, 0x7000, v36
	s_nop 1
	v_addc_co_u32_e32 v37, vcc, 0, v37, vcc
	global_load_dword v41, v[38:39], off nt
	global_load_dword v62, v[38:39], off offset:1024 nt
	global_load_dword v63, v[38:39], off offset:2048 nt
	s_nop 0
	global_load_dword v38, v[38:39], off offset:3072 nt
	s_nop 0
	global_load_dword v39, v[36:37], off nt
	global_load_dword v64, v[36:37], off offset:1024 nt
	global_load_dword v65, v[36:37], off offset:2048 nt
	s_nop 0
	global_load_dword v36, v[36:37], off offset:3072 nt
	v_add_u32_e32 v37, 0xc00, v3
	s_waitcnt vmcnt(30)
; #define LAS __attribute__((address_space(3)))
; #define LDS_WAIT() asm volatile("s_waitcnt lgkmcnt(0)" ::: "memory")
; __device__ __forceinline__ unsigned pk2(float lo, float hi) { return f2bf(lo) | (f2bf(hi) << 16); }
;     ...
;     for (int i = 0; i < 32; ++i) scr[(2 * i + (lane >> 5)) * 33 + (lane & 31)] = tv_[i];
;     LDS_WAIT(); asm volatile("" ::: "memory");
;     const int c = lane & 7;
; #pragma unroll
;     for (int j = 0; j < 4; ++j) { const int n = (lane >> 3) + 8 * j; const LAS float* s = scr + (8 * c) * 33 + n;
;         v4u o; o.x = pk2(s[0 * 33], s[1 * 33]); o.y = pk2(s[2 * 33], s[3 * 33]); o.z = pk2(s[4 * 33], s[5 * 33]); o.w = pk2(s[6 * 33], s[7 * 33]);
;         *(v4u*)(WT + (size_t)(n0 + n) * ldw + koff + k0 + 8 * c) = o; }
;     LDS_WAIT(); asm volatile("" ::: "memory");
	ds_write2_b32 v3, v4, v21 offset1:66
	s_waitcnt vmcnt(28)
	ds_write2_b32 v3, v33, v42 offset0:132 offset1:198
	s_waitcnt vmcnt(26)
	ds_write2_b32 v31, v43, v44 offset0:8 offset1:74
	s_waitcnt vmcnt(24)
	ds_write2_b32 v31, v45, v46 offset0:140 offset1:206
	s_waitcnt vmcnt(22)
	ds_write2_b32 v32, v47, v48 offset0:16 offset1:82
	s_waitcnt vmcnt(20)
	ds_write2_b32 v32, v49, v50 offset0:148 offset1:214
	s_waitcnt vmcnt(18)
	ds_write2_b32 v37, v51, v52 offset0:24 offset1:90
	s_waitcnt vmcnt(16)
	ds_write2_b32 v37, v53, v54 offset0:156 offset1:222
	s_waitcnt vmcnt(14)
	ds_write2_b32 v66, v55, v56 offset0:32 offset1:98
	s_waitcnt vmcnt(12)
	ds_write2_b32 v66, v57, v58 offset0:164 offset1:230
	s_waitcnt vmcnt(10)
	ds_write2_b32 v67, v59, v60 offset0:40 offset1:106
	s_waitcnt vmcnt(8)
	ds_write2_b32 v67, v61, v40 offset0:172 offset1:238
	s_waitcnt vmcnt(6)
	ds_write2_b32 v68, v41, v62 offset0:48 offset1:114
	s_waitcnt vmcnt(4)
	ds_write2_b32 v68, v63, v38 offset0:180 offset1:246
	s_waitcnt vmcnt(2)
	ds_write2_b32 v69, v39, v64 offset0:56 offset1:122
	s_waitcnt vmcnt(0)
	ds_write2_b32 v69, v65, v36 offset0:188 offset1:254
	s_waitcnt lgkmcnt(0)
	v_lshlrev_b32_e32 v4, 1, v20
	v_lshl_add_u64 v[20:21], v[34:35], 0, v[4:5]
	v_lshlrev_b32_e32 v4, 1, v6
	v_lshl_add_u64 v[20:21], v[20:21], 0, v[4:5]
	ds_read_b32 v4, v23
	ds_read_b32 v33, v23 offset:132
	ds_read_b32 v35, v23 offset:264
	ds_read_b32 v36, v23 offset:396
	ds_read_b32 v37, v23 offset:528
	ds_read_b32 v38, v23 offset:660
	ds_read_b32 v39, v23 offset:792
	ds_read_b32 v40, v23 offset:924
	s_waitcnt lgkmcnt(0)
	v_bfe_u32 v34, v4, 16, 1
	v_add3_u32 v4, v4, v34, s38
	v_bfe_u32 v34, v33, 16, 1
	v_lshrrev_b32_e32 v4, 16, v4
	v_add3_u32 v33, v33, v34, s38
	v_and_or_b32 v34, v33, s39, v4
	v_bfe_u32 v4, v35, 16, 1
	v_add3_u32 v4, v35, v4, s38
	v_bfe_u32 v33, v36, 16, 1
	v_lshrrev_b32_e32 v4, 16, v4
	v_add3_u32 v33, v36, v33, s38
	v_and_or_b32 v35, v33, s39, v4
	v_bfe_u32 v4, v37, 16, 1
	v_add3_u32 v4, v37, v4, s38
	v_bfe_u32 v33, v38, 16, 1
	v_lshrrev_b32_e32 v4, 16, v4
	v_add3_u32 v33, v38, v33, s38
	v_and_or_b32 v36, v33, s39, v4
	v_bfe_u32 v4, v39, 16, 1
	v_add3_u32 v4, v39, v4, s38
	v_bfe_u32 v33, v40, 16, 1
	v_lshrrev_b32_e32 v4, 16, v4
	v_add3_u32 v33, v40, v33, s38
	v_and_or_b32 v37, v33, s39, v4
	v_lshl_add_u64 v[38:39], v[20:21], 0, v[8:9]
	global_store_dwordx4 v[38:39], v[34:37], off
	ds_read_b32 v4, v23 offset:32
	ds_read_b32 v33, v23 offset:164
	ds_read_b32 v35, v23 offset:296
	ds_read_b32 v36, v23 offset:428
	ds_read_b32 v37, v23 offset:560
	ds_read_b32 v38, v23 offset:692
	ds_read_b32 v39, v23 offset:824
	ds_read_b32 v40, v23 offset:956
	s_waitcnt lgkmcnt(0)
	v_bfe_u32 v34, v4, 16, 1
	v_add3_u32 v4, v4, v34, s38
	v_bfe_u32 v34, v33, 16, 1
	v_lshrrev_b32_e32 v4, 16, v4
	v_add3_u32 v33, v33, v34, s38
	v_and_or_b32 v34, v33, s39, v4
	v_bfe_u32 v4, v35, 16, 1
	v_add3_u32 v4, v35, v4, s38
	v_bfe_u32 v33, v36, 16, 1
	v_lshrrev_b32_e32 v4, 16, v4
	v_add3_u32 v33, v36, v33, s38
	v_and_or_b32 v35, v33, s39, v4
	v_bfe_u32 v4, v37, 16, 1
	v_add3_u32 v4, v37, v4, s38
	v_bfe_u32 v33, v38, 16, 1
	v_lshrrev_b32_e32 v4, 16, v4
	v_add3_u32 v33, v38, v33, s38
	v_and_or_b32 v36, v33, s39, v4
	v_bfe_u32 v4, v39, 16, 1
	v_add3_u32 v4, v39, v4, s38
	v_bfe_u32 v33, v40, 16, 1
	v_lshrrev_b32_e32 v4, 16, v4
	v_add3_u32 v33, v40, v33, s38
	v_and_or_b32 v37, v33, s39, v4
	v_lshl_add_u64 v[38:39], v[20:21], 0, v[10:11]
	global_store_dwordx4 v[38:39], v[34:37], off
	ds_read_b32 v4, v23 offset:64
	ds_read_b32 v33, v23 offset:196
	ds_read_b32 v35, v23 offset:328
	ds_read_b32 v36, v23 offset:460
	ds_read_b32 v37, v23 offset:592
	ds_read_b32 v38, v23 offset:724
	ds_read_b32 v39, v23 offset:856
	ds_read_b32 v40, v23 offset:988
	s_waitcnt lgkmcnt(0)
	v_bfe_u32 v34, v4, 16, 1
	v_add3_u32 v4, v4, v34, s38
	v_bfe_u32 v34, v33, 16, 1
	v_lshrrev_b32_e32 v4, 16, v4
	v_add3_u32 v33, v33, v34, s38
	v_and_or_b32 v34, v33, s39, v4
	v_bfe_u32 v4, v35, 16, 1
	v_add3_u32 v4, v35, v4, s38
	v_bfe_u32 v33, v36, 16, 1
	v_lshrrev_b32_e32 v4, 16, v4
	v_add3_u32 v33, v36, v33, s38
	v_and_or_b32 v35, v33, s39, v4
	v_bfe_u32 v4, v37, 16, 1
	v_add3_u32 v4, v37, v4, s38
	v_bfe_u32 v33, v38, 16, 1
	v_lshrrev_b32_e32 v4, 16, v4
	v_add3_u32 v33, v38, v33, s38
	v_and_or_b32 v36, v33, s39, v4
	v_bfe_u32 v4, v39, 16, 1
	v_add3_u32 v4, v39, v4, s38
	v_bfe_u32 v33, v40, 16, 1
	v_lshrrev_b32_e32 v4, 16, v4
	v_add3_u32 v33, v40, v33, s38
	v_and_or_b32 v37, v33, s39, v4
	v_lshl_add_u64 v[38:39], v[20:21], 0, v[12:13]
	global_store_dwordx4 v[38:39], v[34:37], off
	ds_read_b32 v4, v23 offset:96
	ds_read_b32 v33, v23 offset:228
	ds_read_b32 v35, v23 offset:360
	ds_read_b32 v36, v23 offset:492
	ds_read_b32 v37, v23 offset:624
	ds_read_b32 v38, v23 offset:756
	ds_read_b32 v39, v23 offset:888
	ds_read_b32 v40, v23 offset:1020
	s_waitcnt lgkmcnt(0)
	v_bfe_u32 v34, v4, 16, 1
	v_add3_u32 v4, v4, v34, s38
	v_bfe_u32 v34, v33, 16, 1
	v_lshrrev_b32_e32 v4, 16, v4
	v_add3_u32 v33, v33, v34, s38
	v_and_or_b32 v34, v33, s39, v4
	v_bfe_u32 v4, v35, 16, 1
	v_add3_u32 v4, v35, v4, s38
	v_bfe_u32 v33, v36, 16, 1
	v_lshrrev_b32_e32 v4, 16, v4
	v_add3_u32 v33, v36, v33, s38
	v_and_or_b32 v35, v33, s39, v4
	v_bfe_u32 v4, v37, 16, 1
	v_add3_u32 v4, v37, v4, s38
	v_bfe_u32 v33, v38, 16, 1
	v_lshrrev_b32_e32 v4, 16, v4
	v_add3_u32 v33, v38, v33, s38
	v_and_or_b32 v36, v33, s39, v4
	v_bfe_u32 v4, v39, 16, 1
	v_add3_u32 v4, v39, v4, s38
	v_bfe_u32 v33, v40, 16, 1
	v_lshrrev_b32_e32 v4, 16, v4
	v_add3_u32 v33, v40, v33, s38
	v_and_or_b32 v37, v33, s39, v4
	v_lshl_add_u64 v[20:21], v[20:21], 0, v[14:15]
	global_store_dwordx4 v[20:21], v[34:37], off
	s_waitcnt lgkmcnt(0)

;     if (ldw == 0) ldw = K;
;     const int nblk = N / 32, kb = item / nblk, nb = item % nblk, k0 = 64 * kb, n0 = 32 * nb;
;     float tv_[32];
; #pragma unroll
;     for (int i = 0; i < 32; ++i) tv_[i] = W[(size_t)(k0 + 2 * i + (lane >> 5)) * N + n0 + (lane & 31)];
; #pragma unroll
;     for (int i = 0; i < 32; ++i) scr[(2 * i + (lane >> 5)) * 33 + (lane & 31)] = tv_[i];
; __device__ __forceinline__ void convert_range(LAS unsigned char* lds, const Params& p, const int lo, const int hi, const int gw, const int NGW) {
;     ...
;         if (r < I_PL) { const int mi = r / 32; r -= mi * 32; p0_transpose_item(p.in[7] + (size_t)mi * 65536, 256, 256, (bf16*)(ws + WS_POOLW) + (size_t)mi * 65536, scr, r, lane); continue; } r -= I_PL;
.LBB0_63:
	s_andn2_saveexec_b64 s[34:35], s[34:35]
	s_cbranch_execz .LBB0_65
	v_add_u32_e32 v4, 0x200, v27
	v_lshrrev_b32_e32 v4, 5, v4
	v_readlane_b32 s60, v251, 21
	v_lshlrev_b64 v[20:21], 18, v[4:5]
	v_readlane_b32 s74, v251, 35
	v_readlane_b32 s75, v251, 36
	v_and_b32_e32 v54, 0xe0, v30
	v_lshlrev_b64 v[34:35], 17, v[4:5]
	v_lshl_add_u64 v[20:21], s[74:75], 0, v[20:21]
	v_and_b32_e32 v33, 0xc0, v29
	v_lshlrev_b32_e32 v4, 2, v54
	v_or_b32_e32 v36, v33, v1
	v_lshl_add_u64 v[20:21], v[20:21], 0, v[4:5]
	v_lshlrev_b32_e32 v4, 2, v2
	v_lshl_add_u64 v[20:21], v[20:21], 0, v[4:5]
	v_lshlrev_b32_e32 v4, 10, v36
	v_lshl_add_u64 v[20:21], v[20:21], 0, v[4:5]
	s_movk_i32 s36, 0x1000
	v_add_co_u32_e32 v36, vcc, s36, v20
	s_movk_i32 s36, 0x2000
	s_nop 0
	v_addc_co_u32_e32 v37, vcc, 0, v21, vcc
	v_add_co_u32_e32 v38, vcc, s36, v20
	s_movk_i32 s36, 0x3000
	s_nop 0
	v_addc_co_u32_e32 v39, vcc, 0, v21, vcc
	v_add_co_u32_e32 v40, vcc, s36, v20
	s_movk_i32 s36, 0x5000
	s_nop 0
	v_addc_co_u32_e32 v41, vcc, 0, v21, vcc
	v_add_co_u32_e32 v42, vcc, s7, v20
	v_readlane_b32 s61, v251, 22
	s_nop 0
	v_addc_co_u32_e32 v43, vcc, 0, v21, vcc
	global_load_dword v4, v[38:39], off offset:-4096 nt
	global_load_dword v55, v[38:39], off nt
	global_load_dword v56, v[38:39], off offset:2048 nt
	global_load_dword v57, v[42:43], off offset:-4096 nt
	global_load_dword v58, v[42:43], off nt
	v_add_co_u32_e32 v38, vcc, s36, v20
	s_movk_i32 s36, 0x6000
	s_nop 0
	v_addc_co_u32_e32 v39, vcc, 0, v21, vcc
	v_add_co_u32_e32 v44, vcc, s36, v20
	s_movk_i32 s36, 0x7000
	s_nop 0
	v_addc_co_u32_e32 v45, vcc, 0, v21, vcc
	v_add_co_u32_e32 v46, vcc, s36, v20
	s_mov_b32 s36, 0x9000
	s_nop 0
	v_addc_co_u32_e32 v47, vcc, 0, v21, vcc
	v_add_co_u32_e32 v48, vcc, s40, v20
	v_readlane_b32 s62, v251, 23
	s_nop 0
	v_addc_co_u32_e32 v49, vcc, 0, v21, vcc
	v_add_co_u32_e32 v50, vcc, s36, v20
	s_mov_b32 s36, 0xb000
	s_nop 0
	v_addc_co_u32_e32 v51, vcc, 0, v21, vcc
	v_add_co_u32_e32 v52, vcc, s41, v20
	v_readlane_b32 s63, v251, 24
	s_nop 0
	v_addc_co_u32_e32 v53, vcc, 0, v21, vcc
	global_load_dword v59, v[42:43], off offset:2048 nt
	global_load_dword v60, v[44:45], off offset:-4096 nt
	global_load_dword v61, v[44:45], off nt
	global_load_dword v62, v[44:45], off offset:2048 nt
	global_load_dword v63, v[48:49], off offset:-4096 nt
	global_load_dword v64, v[48:49], off nt
	s_nop 0
	global_load_dword v48, v[48:49], off offset:2048 nt
	s_nop 0
	global_load_dword v49, v[52:53], off offset:-4096 nt
	v_add_co_u32_e32 v42, vcc, s36, v20
	s_mov_b32 s36, 0xd000
	s_nop 0
	v_addc_co_u32_e32 v43, vcc, 0, v21, vcc
	v_add_co_u32_e32 v44, vcc, s42, v20
	global_load_dword v65, v[20:21], off nt
	global_load_dword v66, v[20:21], off offset:2048 nt
	global_load_dword v67, v[36:37], off offset:2048 nt
	s_nop 0
	global_load_dword v40, v[40:41], off offset:2048 nt
	s_nop 0
	global_load_dword v41, v[38:39], off offset:2048 nt
	s_nop 0
	global_load_dword v46, v[46:47], off offset:2048 nt
	s_nop 0
	global_load_dword v47, v[50:51], off offset:2048 nt
	s_nop 0
	global_load_dword v42, v[42:43], off offset:2048 nt
	v_addc_co_u32_e32 v45, vcc, 0, v21, vcc
	v_add_co_u32_e32 v36, vcc, s36, v20
	s_mov_b32 s36, 0xe000
	s_nop 0
	v_addc_co_u32_e32 v37, vcc, 0, v21, vcc
	v_add_co_u32_e32 v38, vcc, s36, v20
	s_mov_b32 s36, 0xf000
	s_nop 0
	v_addc_co_u32_e32 v39, vcc, 0, v21, vcc
	v_add_co_u32_e32 v20, vcc, s36, v20
	global_load_dword v36, v[36:37], off offset:2048 nt
	s_nop 0
	global_load_dword v37, v[52:53], off nt
	global_load_dword v43, v[52:53], off offset:2048 nt
	global_load_dword v50, v[44:45], off offset:-4096 nt
	global_load_dword v51, v[44:45], off nt
	s_nop 0
	global_load_dword v44, v[44:45], off offset:2048 nt
	s_nop 0
	global_load_dword v45, v[38:39], off offset:-4096 nt
	global_load_dword v52, v[38:39], off nt
	s_nop 0
	global_load_dword v38, v[38:39], off offset:2048 nt
	v_addc_co_u32_e32 v21, vcc, 0, v21, vcc
	global_load_dword v39, v[20:21], off nt
	global_load_dword v53, v[20:21], off offset:2048 nt
	v_lshl_add_u64 v[20:21], s[16:17], 0, v[34:35]
	v_readlane_b32 s64, v251, 25
	v_readlane_b32 s65, v251, 26
	v_readlane_b32 s66, v251, 27
	v_readlane_b32 s67, v251, 28
	v_readlane_b32 s68, v251, 29
	v_readlane_b32 s69, v251, 30
	v_readlane_b32 s70, v251, 31
	v_readlane_b32 s71, v251, 32
	s_waitcnt vmcnt(17)
	ds_write2_b32 v3, v65, v66 offset1:66
	s_waitcnt vmcnt(16)
	ds_write2_b32 v3, v4, v67 offset0:132 offset1:198
	ds_write2_b32 v31, v55, v56 offset0:8 offset1:74
	s_waitcnt vmcnt(15)
	ds_write2_b32 v31, v57, v40 offset0:140 offset1:206
	ds_write2_b32 v32, v58, v59 offset0:16 offset1:82
	s_waitcnt vmcnt(14)
	ds_write2_b32 v32, v60, v41 offset0:148 offset1:214
	v_add_u32_e32 v4, 0xc00, v3
	ds_write2_b32 v4, v61, v62 offset0:24 offset1:90
	s_waitcnt vmcnt(13)
	ds_write2_b32 v4, v63, v46 offset0:156 offset1:222
	v_add_u32_e32 v4, 0x1000, v3
	ds_write2_b32 v4, v64, v48 offset0:32 offset1:98
	s_waitcnt vmcnt(12)
	ds_write2_b32 v4, v49, v47 offset0:164 offset1:230
	v_add_u32_e32 v4, 0x1400, v3
	s_waitcnt vmcnt(8)
	ds_write2_b32 v4, v37, v43 offset0:40 offset1:106
	s_waitcnt vmcnt(7)
; #define LAS __attribute__((address_space(3)))
; #define LDS_WAIT() asm volatile("s_waitcnt lgkmcnt(0)" ::: "memory")
; __device__ __forceinline__ unsigned pk2(float lo, float hi) { return f2bf(lo) | (f2bf(hi) << 16); }
;     ...
;     for (int i = 0; i < 32; ++i) scr[(2 * i + (lane >> 5)) * 33 + (lane & 31)] = tv_[i];
;     LDS_WAIT(); asm volatile("" ::: "memory");
;     const int c = lane & 7;
; #pragma unroll
;     for (int j = 0; j < 4; ++j) { const int n = (lane >> 3) + 8 * j; const LAS float* s = scr + (8 * c) * 33 + n;
;         v4u o; o.x = pk2(s[0 * 33], s[1 * 33]); o.y = pk2(s[2 * 33], s[3 * 33]); o.z = pk2(s[4 * 33], s[5 * 33]); o.w = pk2(s[6 * 33], s[7 * 33]);
;         *(v4u*)(WT + (size_t)(n0 + n) * ldw + koff + k0 + 8 * c) = o; }
;     LDS_WAIT(); asm volatile("" ::: "memory");
	ds_write2_b32 v4, v50, v42 offset0:172 offset1:238
	v_add_u32_e32 v4, 0x1800, v3
	s_waitcnt vmcnt(5)
	ds_write2_b32 v4, v51, v44 offset0:48 offset1:114
	s_waitcnt vmcnt(4)
	ds_write2_b32 v4, v45, v36 offset0:180 offset1:246
	v_add_u32_e32 v4, 0x1c00, v3
	s_waitcnt vmcnt(2)
	ds_write2_b32 v4, v52, v38 offset0:56 offset1:122
	s_waitcnt vmcnt(0)
	ds_write2_b32 v4, v39, v53 offset0:188 offset1:254
	s_waitcnt lgkmcnt(0)
	v_lshlrev_b32_e32 v4, 1, v33
	v_lshl_add_u64 v[20:21], v[20:21], 0, v[4:5]
	v_lshlrev_b32_e32 v4, 1, v6
	v_lshl_add_u64 v[20:21], v[20:21], 0, v[4:5]
	ds_read_b32 v4, v23
	ds_read_b32 v33, v23 offset:132
	ds_read_b32 v35, v23 offset:264
	ds_read_b32 v36, v23 offset:396
	ds_read_b32 v37, v23 offset:528
	ds_read_b32 v38, v23 offset:660
	ds_read_b32 v39, v23 offset:792
	ds_read_b32 v40, v23 offset:924
	s_waitcnt lgkmcnt(0)
	v_bfe_u32 v34, v4, 16, 1
	v_add3_u32 v4, v4, v34, s38
	v_bfe_u32 v34, v33, 16, 1
	v_lshrrev_b32_e32 v4, 16, v4
	v_add3_u32 v33, v33, v34, s38
	v_and_or_b32 v34, v33, s39, v4
	v_bfe_u32 v4, v35, 16, 1
	v_add3_u32 v4, v35, v4, s38
	v_bfe_u32 v33, v36, 16, 1
	v_lshrrev_b32_e32 v4, 16, v4
	v_add3_u32 v33, v36, v33, s38
	v_and_or_b32 v35, v33, s39, v4
	v_bfe_u32 v4, v37, 16, 1
	v_add3_u32 v4, v37, v4, s38
	v_bfe_u32 v33, v38, 16, 1
	v_lshrrev_b32_e32 v4, 16, v4
	v_add3_u32 v33, v38, v33, s38
	v_and_or_b32 v36, v33, s39, v4
	v_bfe_u32 v4, v39, 16, 1
	v_add3_u32 v4, v39, v4, s38
	v_bfe_u32 v33, v40, 16, 1
	v_lshrrev_b32_e32 v4, 16, v4
	v_add3_u32 v33, v40, v33, s38
	v_and_or_b32 v37, v33, s39, v4
	v_or_b32_e32 v4, v54, v7
	v_lshlrev_b32_e32 v4, 9, v4
	v_lshl_add_u64 v[38:39], v[20:21], 0, v[4:5]
	global_store_dwordx4 v[38:39], v[34:37], off
	ds_read_b32 v4, v23 offset:32
	ds_read_b32 v33, v23 offset:164
	ds_read_b32 v35, v23 offset:296
	ds_read_b32 v36, v23 offset:428
	ds_read_b32 v37, v23 offset:560
	ds_read_b32 v38, v23 offset:692
	ds_read_b32 v39, v23 offset:824
	ds_read_b32 v40, v23 offset:956
	s_waitcnt lgkmcnt(0)
	v_bfe_u32 v34, v4, 16, 1
	v_add3_u32 v4, v4, v34, s38
	v_bfe_u32 v34, v33, 16, 1
	v_lshrrev_b32_e32 v4, 16, v4
	v_add3_u32 v33, v33, v34, s38
	v_and_or_b32 v34, v33, s39, v4
	v_bfe_u32 v4, v35, 16, 1
	v_add3_u32 v4, v35, v4, s38
	v_bfe_u32 v33, v36, 16, 1
	v_lshrrev_b32_e32 v4, 16, v4
	v_add3_u32 v33, v36, v33, s38
	v_and_or_b32 v35, v33, s39, v4
	v_bfe_u32 v4, v37, 16, 1
	v_add3_u32 v4, v37, v4, s38
	v_bfe_u32 v33, v38, 16, 1
	v_lshrrev_b32_e32 v4, 16, v4
	v_add3_u32 v33, v38, v33, s38
	v_and_or_b32 v36, v33, s39, v4
	v_bfe_u32 v4, v39, 16, 1
	v_add3_u32 v4, v39, v4, s38
	v_bfe_u32 v33, v40, 16, 1
	v_lshrrev_b32_e32 v4, 16, v4
	v_add3_u32 v33, v40, v33, s38
	v_and_or_b32 v37, v33, s39, v4
	v_or_b32_e32 v4, v54, v24
	v_lshlrev_b32_e32 v4, 9, v4
	v_lshl_add_u64 v[38:39], v[20:21], 0, v[4:5]
	global_store_dwordx4 v[38:39], v[34:37], off
	ds_read_b32 v4, v23 offset:64
	ds_read_b32 v33, v23 offset:196
	ds_read_b32 v35, v23 offset:328
	ds_read_b32 v36, v23 offset:460
	ds_read_b32 v37, v23 offset:592
	ds_read_b32 v38, v23 offset:724
	ds_read_b32 v39, v23 offset:856
	ds_read_b32 v40, v23 offset:988
	s_waitcnt lgkmcnt(0)
	v_bfe_u32 v34, v4, 16, 1
	v_add3_u32 v4, v4, v34, s38
	v_bfe_u32 v34, v33, 16, 1
	v_lshrrev_b32_e32 v4, 16, v4
	v_add3_u32 v33, v33, v34, s38
	v_and_or_b32 v34, v33, s39, v4
	v_bfe_u32 v4, v35, 16, 1
	v_add3_u32 v4, v35, v4, s38
	v_bfe_u32 v33, v36, 16, 1
	v_lshrrev_b32_e32 v4, 16, v4
	v_add3_u32 v33, v36, v33, s38
	v_and_or_b32 v35, v33, s39, v4
	v_bfe_u32 v4, v37, 16, 1
	v_add3_u32 v4, v37, v4, s38
	v_bfe_u32 v33, v38, 16, 1
	v_lshrrev_b32_e32 v4, 16, v4
	v_add3_u32 v33, v38, v33, s38
	v_and_or_b32 v36, v33, s39, v4
	v_bfe_u32 v4, v39, 16, 1
	v_add3_u32 v4, v39, v4, s38
	v_bfe_u32 v33, v40, 16, 1
	v_lshrrev_b32_e32 v4, 16, v4
	v_add3_u32 v33, v40, v33, s38
	v_and_or_b32 v37, v33, s39, v4
	v_or_b32_e32 v4, v54, v25
	v_lshlrev_b32_e32 v4, 9, v4
	v_lshl_add_u64 v[38:39], v[20:21], 0, v[4:5]
	global_store_dwordx4 v[38:39], v[34:37], off
	ds_read_b32 v4, v23 offset:96
	ds_read_b32 v33, v23 offset:228
	ds_read_b32 v35, v23 offset:360
	ds_read_b32 v36, v23 offset:492
	ds_read_b32 v37, v23 offset:624
	ds_read_b32 v38, v23 offset:756
	ds_read_b32 v39, v23 offset:888
	ds_read_b32 v40, v23 offset:1020
	s_waitcnt lgkmcnt(0)
	v_bfe_u32 v34, v4, 16, 1
	v_add3_u32 v4, v4, v34, s38
	v_bfe_u32 v34, v33, 16, 1
	v_lshrrev_b32_e32 v4, 16, v4
	v_add3_u32 v33, v33, v34, s38
	v_and_or_b32 v34, v33, s39, v4
	v_bfe_u32 v4, v35, 16, 1
	v_add3_u32 v4, v35, v4, s38
	v_bfe_u32 v33, v36, 16, 1
	v_lshrrev_b32_e32 v4, 16, v4
	v_add3_u32 v33, v36, v33, s38
	v_and_or_b32 v35, v33, s39, v4
	v_bfe_u32 v4, v37, 16, 1
	v_add3_u32 v4, v37, v4, s38
	v_bfe_u32 v33, v38, 16, 1
	v_lshrrev_b32_e32 v4, 16, v4
	v_add3_u32 v33, v38, v33, s38
	v_and_or_b32 v36, v33, s39, v4
	v_bfe_u32 v4, v39, 16, 1
	v_add3_u32 v4, v39, v4, s38
	v_bfe_u32 v33, v40, 16, 1
	v_lshrrev_b32_e32 v4, 16, v4
	v_add3_u32 v33, v40, v33, s38
	v_and_or_b32 v37, v33, s39, v4
	v_or_b32_e32 v4, v54, v26
	v_lshlrev_b32_e32 v4, 9, v4
	v_lshl_add_u64 v[20:21], v[20:21], 0, v[4:5]
	global_store_dwordx4 v[20:21], v[34:37], off
	s_waitcnt lgkmcnt(0)
	v_readlane_b32 s72, v251, 33
	v_readlane_b32 s73, v251, 34

;     if (ldw == 0) ldw = K;
;     const int nblk = N / 32, kb = item / nblk, nb = item % nblk, k0 = 64 * kb, n0 = 32 * nb;
;     float tv_[32];
; #pragma unroll
;     for (int i = 0; i < 32; ++i) tv_[i] = W[(size_t)(k0 + 2 * i + (lane >> 5)) * N + n0 + (lane & 31)];
; #pragma unroll
;     for (int i = 0; i < 32; ++i) scr[(2 * i + (lane >> 5)) * 33 + (lane & 31)] = tv_[i];
; __device__ __forceinline__ void convert_range(LAS unsigned char* lds, const Params& p, const int lo, const int hi, const int gw, const int NGW) {
;     ...
;         if (r < 2 * I_OUT) { const int l = r / I_OUT; r -= l * I_OUT; p0_transpose_item(p.in[18] + (size_t)l * DM * DM, DM, DM, (bf16*)(ws + WS_WOUT + l * SZ_WOUT), scr, r, lane); continue; } r -= 2 * I_OUT;
.LBB0_66:
	s_andn2_saveexec_b64 s[30:31], s[30:31]
	s_cbranch_execz .LBB0_68
	v_add_u32_e32 v4, 0x1200, v27
	v_lshrrev_b32_e32 v4, 11, v4
	v_readlane_b32 s68, v251, 9
	v_lshlrev_b64 v[34:35], 24, v[4:5]
	v_readlane_b32 s72, v251, 13
	v_readlane_b32 s73, v251, 14
	v_and_b32_e32 v52, 0x7e0, v30
	v_lshlrev_b64 v[36:37], 23, v[4:5]
	v_lshl_add_u64 v[34:35], s[72:73], 0, v[34:35]
	v_and_b32_e32 v33, 0x7c0, v20
	v_lshlrev_b32_e32 v4, 2, v52
	v_or_b32_e32 v38, v33, v1
	v_lshl_add_u64 v[20:21], v[34:35], 0, v[4:5]
	v_lshlrev_b32_e32 v4, 2, v2
	v_lshl_add_u64 v[20:21], v[20:21], 0, v[4:5]
	v_lshlrev_b32_e32 v4, 13, v38
	v_lshl_add_u64 v[20:21], v[20:21], 0, v[4:5]
	v_add_co_u32_e32 v34, vcc, s7, v20
	v_readlane_b32 s69, v251, 10
	s_nop 0
	v_addc_co_u32_e32 v35, vcc, 0, v21, vcc
	v_add_co_u32_e32 v38, vcc, s40, v20
	v_readlane_b32 s70, v251, 11
	s_nop 0
	v_addc_co_u32_e32 v39, vcc, 0, v21, vcc
	v_add_co_u32_e32 v40, vcc, s42, v20
	v_readlane_b32 s71, v251, 12
	s_nop 0
	v_addc_co_u32_e32 v41, vcc, 0, v21, vcc
	v_add_co_u32_e32 v42, vcc, s43, v20
	v_readlane_b32 s74, v251, 15
	s_nop 0
	v_addc_co_u32_e32 v43, vcc, 0, v21, vcc
	v_add_co_u32_e32 v44, vcc, s44, v20
	v_readlane_b32 s75, v251, 16
	s_nop 0
	v_addc_co_u32_e32 v45, vcc, 0, v21, vcc
	v_add_co_u32_e32 v46, vcc, s45, v20
	s_nop 1
	v_addc_co_u32_e32 v47, vcc, 0, v21, vcc
	v_add_co_u32_e32 v48, vcc, s47, v20
	s_nop 1
	v_addc_co_u32_e32 v49, vcc, 0, v21, vcc
	global_load_dword v4, v[20:21], off nt
	global_load_dword v53, v[34:35], off nt
	global_load_dword v54, v[38:39], off nt
	global_load_dword v55, v[40:41], off nt
	global_load_dword v56, v[42:43], off nt
	global_load_dword v57, v[44:45], off nt
	global_load_dword v58, v[46:47], off nt
	global_load_dword v59, v[48:49], off nt
	v_add_co_u32_e32 v34, vcc, s48, v20
	s_nop 1
	v_addc_co_u32_e32 v35, vcc, 0, v21, vcc
	v_add_co_u32_e32 v38, vcc, s49, v20
	s_nop 1
	v_addc_co_u32_e32 v39, vcc, 0, v21, vcc
	v_add_co_u32_e32 v40, vcc, s50, v20
	s_nop 1
	v_addc_co_u32_e32 v41, vcc, 0, v21, vcc
	v_add_co_u32_e32 v42, vcc, s51, v20
	s_nop 1
	v_addc_co_u32_e32 v43, vcc, 0, v21, vcc
	v_add_co_u32_e32 v44, vcc, s52, v20
	s_nop 1
	v_addc_co_u32_e32 v45, vcc, 0, v21, vcc
	v_add_co_u32_e32 v46, vcc, s53, v20
	s_nop 1
	v_addc_co_u32_e32 v47, vcc, 0, v21, vcc
	v_add_co_u32_e32 v48, vcc, s54, v20
	s_nop 1
	v_addc_co_u32_e32 v49, vcc, 0, v21, vcc
	v_add_co_u32_e32 v50, vcc, s55, v20
	s_nop 1
	v_addc_co_u32_e32 v51, vcc, 0, v21, vcc
	global_load_dword v60, v[34:35], off nt
	global_load_dword v61, v[38:39], off nt
	global_load_dword v62, v[40:41], off nt
	global_load_dword v63, v[42:43], off nt
	global_load_dword v64, v[44:45], off nt
	global_load_dword v65, v[46:47], off nt
	global_load_dword v66, v[48:49], off nt
	global_load_dword v67, v[50:51], off nt
	v_add_co_u32_e32 v34, vcc, s56, v20
	s_nop 1
	v_addc_co_u32_e32 v35, vcc, 0, v21, vcc
	v_add_co_u32_e32 v38, vcc, s57, v20
	s_nop 1
	v_addc_co_u32_e32 v39, vcc, 0, v21, vcc
	v_add_co_u32_e32 v40, vcc, s58, v20
	s_nop 1
	v_addc_co_u32_e32 v41, vcc, 0, v21, vcc
	v_add_co_u32_e32 v42, vcc, s59, v20
	s_nop 1
	v_addc_co_u32_e32 v43, vcc, 0, v21, vcc
	v_add_co_u32_e32 v44, vcc, s76, v20
	s_nop 1
	v_addc_co_u32_e32 v45, vcc, 0, v21, vcc
	v_add_co_u32_e32 v46, vcc, s77, v20
	s_nop 1
	v_addc_co_u32_e32 v47, vcc, 0, v21, vcc
	v_add_co_u32_e32 v48, vcc, s78, v20
	s_nop 1
	v_addc_co_u32_e32 v49, vcc, 0, v21, vcc
	v_add_co_u32_e32 v50, vcc, s79, v20
	s_nop 1
	v_addc_co_u32_e32 v51, vcc, 0, v21, vcc
	global_load_dword v68, v[34:35], off nt
	global_load_dword v69, v[38:39], off nt
	global_load_dword v70, v[40:41], off nt
	global_load_dword v71, v[42:43], off nt
	global_load_dword v72, v[44:45], off nt
	global_load_dword v73, v[46:47], off nt
	global_load_dword v74, v[48:49], off nt
	s_nop 0
	global_load_dword v50, v[50:51], off nt
	v_add_co_u32_e32 v34, vcc, s80, v20
	s_nop 1
	v_addc_co_u32_e32 v35, vcc, 0, v21, vcc
	v_add_co_u32_e32 v38, vcc, s81, v20
	s_nop 1
	v_addc_co_u32_e32 v39, vcc, 0, v21, vcc
	v_add_co_u32_e32 v40, vcc, s82, v20
	s_nop 1
	v_addc_co_u32_e32 v41, vcc, 0, v21, vcc
	v_add_co_u32_e32 v42, vcc, s83, v20
	s_nop 1
	v_addc_co_u32_e32 v43, vcc, 0, v21, vcc
	v_add_co_u32_e32 v44, vcc, s84, v20
	s_nop 1
	v_addc_co_u32_e32 v45, vcc, 0, v21, vcc
	v_add_co_u32_e32 v46, vcc, s85, v20
	s_nop 1
	v_addc_co_u32_e32 v47, vcc, 0, v21, vcc
	v_add_co_u32_e32 v48, vcc, s86, v20
	s_nop 1
	v_addc_co_u32_e32 v49, vcc, 0, v21, vcc
	v_add_co_u32_e32 v20, vcc, s87, v20
	s_nop 1
	v_addc_co_u32_e32 v21, vcc, 0, v21, vcc
	global_load_dword v34, v[34:35], off nt
	s_nop 0
	global_load_dword v35, v[38:39], off nt
	s_nop 0
	global_load_dword v38, v[40:41], off nt
	global_load_dword v39, v[42:43], off nt
	s_nop 0
	global_load_dword v40, v[44:45], off nt
	global_load_dword v41, v[46:47], off nt
	global_load_dword v42, v[48:49], off nt
	global_load_dword v43, v[20:21], off nt
	s_waitcnt vmcnt(30)
	ds_write2_b32 v3, v4, v53 offset1:66
	s_waitcnt vmcnt(28)
	ds_write2_b32 v3, v54, v55 offset0:132 offset1:198
	s_waitcnt vmcnt(26)
	ds_write2_b32 v31, v56, v57 offset0:8 offset1:74
	s_waitcnt vmcnt(24)
	ds_write2_b32 v31, v58, v59 offset0:140 offset1:206
	s_waitcnt vmcnt(22)
	ds_write2_b32 v32, v60, v61 offset0:16 offset1:82
	s_waitcnt vmcnt(20)
	ds_write2_b32 v32, v62, v63 offset0:148 offset1:214
	v_add_u32_e32 v4, 0xc00, v3
	s_waitcnt vmcnt(18)
	ds_write2_b32 v4, v64, v65 offset0:24 offset1:90
	s_waitcnt vmcnt(16)
	ds_write2_b32 v4, v66, v67 offset0:156 offset1:222
	v_add_u32_e32 v4, 0x1000, v3
	s_waitcnt vmcnt(14)
; #define LAS __attribute__((address_space(3)))
; #define LDS_WAIT() asm volatile("s_waitcnt lgkmcnt(0)" ::: "memory")
; __device__ __forceinline__ unsigned pk2(float lo, float hi) { return f2bf(lo) | (f2bf(hi) << 16); }
;     ...
;     for (int i = 0; i < 32; ++i) scr[(2 * i + (lane >> 5)) * 33 + (lane & 31)] = tv_[i];
;     LDS_WAIT(); asm volatile("" ::: "memory");
;     const int c = lane & 7;
; #pragma unroll
;     for (int j = 0; j < 4; ++j) { const int n = (lane >> 3) + 8 * j; const LAS float* s = scr + (8 * c) * 33 + n;
;         v4u o; o.x = pk2(s[0 * 33], s[1 * 33]); o.y = pk2(s[2 * 33], s[3 * 33]); o.z = pk2(s[4 * 33], s[5 * 33]); o.w = pk2(s[6 * 33], s[7 * 33]);
;         *(v4u*)(WT + (size_t)(n0 + n) * ldw + koff + k0 + 8 * c) = o; }
;     LDS_WAIT(); asm volatile("" ::: "memory");
	ds_write2_b32 v4, v68, v69 offset0:32 offset1:98
	s_waitcnt vmcnt(12)
	ds_write2_b32 v4, v70, v71 offset0:164 offset1:230
	v_add_u32_e32 v4, 0x1400, v3
	s_waitcnt vmcnt(10)
	ds_write2_b32 v4, v72, v73 offset0:40 offset1:106
	s_waitcnt vmcnt(8)
	ds_write2_b32 v4, v74, v50 offset0:172 offset1:238
	v_add_u32_e32 v4, 0x1800, v3
	s_waitcnt vmcnt(6)
	ds_write2_b32 v4, v34, v35 offset0:48 offset1:114
	s_waitcnt vmcnt(4)
	ds_write2_b32 v4, v38, v39 offset0:180 offset1:246
	v_add_u32_e32 v4, 0x1c00, v3
	s_waitcnt vmcnt(2)
	ds_write2_b32 v4, v40, v41 offset0:56 offset1:122
	s_waitcnt vmcnt(0)
	ds_write2_b32 v4, v42, v43 offset0:188 offset1:254
	v_lshl_add_u64 v[20:21], s[18:19], 0, v[36:37]
	s_waitcnt lgkmcnt(0)
	v_lshlrev_b32_e32 v4, 1, v33
	v_lshl_add_u64 v[20:21], v[20:21], 0, v[4:5]
	v_lshlrev_b32_e32 v4, 1, v6
	v_lshl_add_u64 v[20:21], v[20:21], 0, v[4:5]
	ds_read_b32 v4, v23
	ds_read_b32 v33, v23 offset:132
	ds_read_b32 v35, v23 offset:264
	ds_read_b32 v36, v23 offset:396
	ds_read_b32 v37, v23 offset:528
	ds_read_b32 v38, v23 offset:660
	ds_read_b32 v39, v23 offset:792
	ds_read_b32 v40, v23 offset:924
	s_waitcnt lgkmcnt(0)
	v_bfe_u32 v34, v4, 16, 1
	v_add3_u32 v4, v4, v34, s38
	v_bfe_u32 v34, v33, 16, 1
	v_lshrrev_b32_e32 v4, 16, v4
	v_add3_u32 v33, v33, v34, s38
	v_and_or_b32 v34, v33, s39, v4
	v_bfe_u32 v4, v35, 16, 1
	v_add3_u32 v4, v35, v4, s38
	v_bfe_u32 v33, v36, 16, 1
	v_lshrrev_b32_e32 v4, 16, v4
	v_add3_u32 v33, v36, v33, s38
	v_and_or_b32 v35, v33, s39, v4
	v_bfe_u32 v4, v37, 16, 1
	v_add3_u32 v4, v37, v4, s38
	v_bfe_u32 v33, v38, 16, 1
	v_lshrrev_b32_e32 v4, 16, v4
	v_add3_u32 v33, v38, v33, s38
	v_and_or_b32 v36, v33, s39, v4
	v_bfe_u32 v4, v39, 16, 1
	v_add3_u32 v4, v39, v4, s38
	v_bfe_u32 v33, v40, 16, 1
	v_lshrrev_b32_e32 v4, 16, v4
	v_add3_u32 v33, v40, v33, s38
	v_and_or_b32 v37, v33, s39, v4
	v_or_b32_e32 v4, v52, v7
	v_lshlrev_b32_e32 v4, 12, v4
	v_lshl_add_u64 v[38:39], v[20:21], 0, v[4:5]
	global_store_dwordx4 v[38:39], v[34:37], off
	ds_read_b32 v4, v23 offset:32
	ds_read_b32 v33, v23 offset:164
	ds_read_b32 v35, v23 offset:296
	ds_read_b32 v36, v23 offset:428
	ds_read_b32 v37, v23 offset:560
	ds_read_b32 v38, v23 offset:692
	ds_read_b32 v39, v23 offset:824
	ds_read_b32 v40, v23 offset:956
	s_waitcnt lgkmcnt(0)
	v_bfe_u32 v34, v4, 16, 1
	v_add3_u32 v4, v4, v34, s38
	v_bfe_u32 v34, v33, 16, 1
	v_lshrrev_b32_e32 v4, 16, v4
	v_add3_u32 v33, v33, v34, s38
	v_and_or_b32 v34, v33, s39, v4
	v_bfe_u32 v4, v35, 16, 1
	v_add3_u32 v4, v35, v4, s38
	v_bfe_u32 v33, v36, 16, 1
	v_lshrrev_b32_e32 v4, 16, v4
	v_add3_u32 v33, v36, v33, s38
	v_and_or_b32 v35, v33, s39, v4
	v_bfe_u32 v4, v37, 16, 1
	v_add3_u32 v4, v37, v4, s38
	v_bfe_u32 v33, v38, 16, 1
	v_lshrrev_b32_e32 v4, 16, v4
	v_add3_u32 v33, v38, v33, s38
	v_and_or_b32 v36, v33, s39, v4
	v_bfe_u32 v4, v39, 16, 1
	v_add3_u32 v4, v39, v4, s38
	v_bfe_u32 v33, v40, 16, 1
	v_lshrrev_b32_e32 v4, 16, v4
	v_add3_u32 v33, v40, v33, s38
	v_and_or_b32 v37, v33, s39, v4
	v_or_b32_e32 v4, v52, v24
	v_lshlrev_b32_e32 v4, 12, v4
	v_lshl_add_u64 v[38:39], v[20:21], 0, v[4:5]
	global_store_dwordx4 v[38:39], v[34:37], off
	ds_read_b32 v4, v23 offset:64
	ds_read_b32 v33, v23 offset:196
	ds_read_b32 v35, v23 offset:328
	ds_read_b32 v36, v23 offset:460
	ds_read_b32 v37, v23 offset:592
	ds_read_b32 v38, v23 offset:724
	ds_read_b32 v39, v23 offset:856
	ds_read_b32 v40, v23 offset:988
	s_waitcnt lgkmcnt(0)
	v_bfe_u32 v34, v4, 16, 1
	v_add3_u32 v4, v4, v34, s38
	v_bfe_u32 v34, v33, 16, 1
	v_lshrrev_b32_e32 v4, 16, v4
	v_add3_u32 v33, v33, v34, s38
	v_and_or_b32 v34, v33, s39, v4
	v_bfe_u32 v4, v35, 16, 1
	v_add3_u32 v4, v35, v4, s38
	v_bfe_u32 v33, v36, 16, 1
	v_lshrrev_b32_e32 v4, 16, v4
	v_add3_u32 v33, v36, v33, s38
	v_and_or_b32 v35, v33, s39, v4
	v_bfe_u32 v4, v37, 16, 1
	v_add3_u32 v4, v37, v4, s38
	v_bfe_u32 v33, v38, 16, 1
	v_lshrrev_b32_e32 v4, 16, v4
	v_add3_u32 v33, v38, v33, s38
	v_and_or_b32 v36, v33, s39, v4
	v_bfe_u32 v4, v39, 16, 1
	v_add3_u32 v4, v39, v4, s38
	v_bfe_u32 v33, v40, 16, 1
	v_lshrrev_b32_e32 v4, 16, v4
	v_add3_u32 v33, v40, v33, s38
	v_and_or_b32 v37, v33, s39, v4
	v_or_b32_e32 v4, v52, v25
	v_lshlrev_b32_e32 v4, 12, v4
	v_lshl_add_u64 v[38:39], v[20:21], 0, v[4:5]
	global_store_dwordx4 v[38:39], v[34:37], off
	ds_read_b32 v4, v23 offset:96
	ds_read_b32 v33, v23 offset:228
	ds_read_b32 v35, v23 offset:360
	ds_read_b32 v36, v23 offset:492
	ds_read_b32 v37, v23 offset:624
	ds_read_b32 v38, v23 offset:756
	ds_read_b32 v39, v23 offset:888
	ds_read_b32 v40, v23 offset:1020
	s_waitcnt lgkmcnt(0)
	v_bfe_u32 v34, v4, 16, 1
	v_add3_u32 v4, v4, v34, s38
	v_bfe_u32 v34, v33, 16, 1
	v_lshrrev_b32_e32 v4, 16, v4
	v_add3_u32 v33, v33, v34, s38
	v_and_or_b32 v34, v33, s39, v4
	v_bfe_u32 v4, v35, 16, 1
	v_add3_u32 v4, v35, v4, s38
	v_bfe_u32 v33, v36, 16, 1
	v_lshrrev_b32_e32 v4, 16, v4
	v_add3_u32 v33, v36, v33, s38
	v_and_or_b32 v35, v33, s39, v4
	v_bfe_u32 v4, v37, 16, 1
	v_add3_u32 v4, v37, v4, s38
	v_bfe_u32 v33, v38, 16, 1
	v_lshrrev_b32_e32 v4, 16, v4
	v_add3_u32 v33, v38, v33, s38
	v_and_or_b32 v36, v33, s39, v4
	v_bfe_u32 v4, v39, 16, 1
	v_add3_u32 v4, v39, v4, s38
	v_bfe_u32 v33, v40, 16, 1
	v_lshrrev_b32_e32 v4, 16, v4
	v_add3_u32 v33, v40, v33, s38
	v_and_or_b32 v37, v33, s39, v4
	v_or_b32_e32 v4, v52, v26
	v_lshlrev_b32_e32 v4, 12, v4
	v_lshl_add_u64 v[20:21], v[20:21], 0, v[4:5]
	global_store_dwordx4 v[20:21], v[34:37], off
	s_waitcnt lgkmcnt(0)

;     if (ldw == 0) ldw = K;
;     const int nblk = N / 32, kb = item / nblk, nb = item % nblk, k0 = 64 * kb, n0 = 32 * nb;
;     float tv_[32];
; #pragma unroll
;     for (int i = 0; i < 32; ++i) tv_[i] = W[(size_t)(k0 + 2 * i + (lane >> 5)) * N + n0 + (lane & 31)];
; #pragma unroll
;     for (int i = 0; i < 32; ++i) scr[(2 * i + (lane >> 5)) * 33 + (lane & 31)] = tv_[i];
; __device__ __forceinline__ void convert_range(LAS unsigned char* lds, const Params& p, const int lo, const int hi, const int gw, const int NGW) {
;     ...
;         if (r < 2 * I_PB) { const int l = r / I_PB; r -= l * I_PB; p0_transpose_item(p.in[17] + (size_t)l * LW * DM, LW, DM, (bf16*)(ws + WS_WCAT + l * SZ_WCAT), scr, r, lane, KCAT, PW); continue; } r -= 2 * I_PB;
.LBB0_69:
	s_andn2_saveexec_b64 s[28:29], s[28:29]
	s_cbranch_execz .LBB0_71
	v_add_u32_e32 v4, 0x2200, v27
	v_lshrrev_b32_e32 v4, 11, v4
	v_readlane_b32 s68, v251, 9
	v_lshlrev_b64 v[34:35], 24, v[4:5]
	v_readlane_b32 s70, v251, 11
	v_readlane_b32 s71, v251, 12
	v_mov_b64_e32 v[36:37], s[8:9]
	v_and_b32_e32 v52, 0x7e0, v30
	v_lshl_add_u64 v[34:35], s[70:71], 0, v[34:35]
	v_mad_u64_u32 v[36:37], s[30:31], v4, s88, v[36:37]
	v_and_b32_e32 v33, 0x7c0, v20
	v_lshlrev_b32_e32 v4, 2, v52
	v_or_b32_e32 v38, v33, v1
	v_lshl_add_u64 v[20:21], v[34:35], 0, v[4:5]
	v_lshlrev_b32_e32 v4, 2, v2
	v_lshl_add_u64 v[20:21], v[20:21], 0, v[4:5]
	v_lshlrev_b32_e32 v4, 13, v38
	v_lshl_add_u64 v[20:21], v[20:21], 0, v[4:5]
	v_add_co_u32_e32 v34, vcc, s7, v20
	s_mov_b64 s[30:31], 0x5000800
	s_nop 0
	v_addc_co_u32_e32 v35, vcc, 0, v21, vcc
	v_add_co_u32_e32 v38, vcc, s40, v20
	v_readlane_b32 s69, v251, 10
	s_nop 0
	v_addc_co_u32_e32 v39, vcc, 0, v21, vcc
	v_add_co_u32_e32 v40, vcc, s42, v20
	v_readlane_b32 s72, v251, 13
	s_nop 0
	v_addc_co_u32_e32 v41, vcc, 0, v21, vcc
	v_add_co_u32_e32 v42, vcc, s43, v20
	v_readlane_b32 s73, v251, 14
	s_nop 0
	v_addc_co_u32_e32 v43, vcc, 0, v21, vcc
	v_add_co_u32_e32 v44, vcc, s44, v20
	v_readlane_b32 s74, v251, 15
	s_nop 0
	v_addc_co_u32_e32 v45, vcc, 0, v21, vcc
	v_add_co_u32_e32 v46, vcc, s45, v20
	v_readlane_b32 s75, v251, 16
	s_nop 0
	v_addc_co_u32_e32 v47, vcc, 0, v21, vcc
	v_add_co_u32_e32 v48, vcc, s47, v20
	s_nop 1
	v_addc_co_u32_e32 v49, vcc, 0, v21, vcc
	global_load_dword v4, v[20:21], off nt
	global_load_dword v53, v[34:35], off nt
	global_load_dword v54, v[38:39], off nt
	global_load_dword v55, v[40:41], off nt
	global_load_dword v56, v[42:43], off nt
	global_load_dword v57, v[44:45], off nt
	global_load_dword v58, v[46:47], off nt
	global_load_dword v59, v[48:49], off nt
	v_add_co_u32_e32 v34, vcc, s48, v20
	s_nop 1
	v_addc_co_u32_e32 v35, vcc, 0, v21, vcc
	v_add_co_u32_e32 v38, vcc, s49, v20
	s_nop 1
	v_addc_co_u32_e32 v39, vcc, 0, v21, vcc
	v_add_co_u32_e32 v40, vcc, s50, v20
	s_nop 1
	v_addc_co_u32_e32 v41, vcc, 0, v21, vcc
	v_add_co_u32_e32 v42, vcc, s51, v20
	s_nop 1
	v_addc_co_u32_e32 v43, vcc, 0, v21, vcc
	v_add_co_u32_e32 v44, vcc, s52, v20
	s_nop 1
	v_addc_co_u32_e32 v45, vcc, 0, v21, vcc
	v_add_co_u32_e32 v46, vcc, s53, v20
	s_nop 1
	v_addc_co_u32_e32 v47, vcc, 0, v21, vcc
	v_add_co_u32_e32 v48, vcc, s54, v20
	s_nop 1
	v_addc_co_u32_e32 v49, vcc, 0, v21, vcc
	v_add_co_u32_e32 v50, vcc, s55, v20
	s_nop 1
	v_addc_co_u32_e32 v51, vcc, 0, v21, vcc
	global_load_dword v60, v[34:35], off nt
	global_load_dword v61, v[38:39], off nt
	global_load_dword v62, v[40:41], off nt
	global_load_dword v63, v[42:43], off nt
	global_load_dword v64, v[44:45], off nt
	global_load_dword v65, v[46:47], off nt
	global_load_dword v66, v[48:49], off nt
	global_load_dword v67, v[50:51], off nt
	v_add_co_u32_e32 v34, vcc, s56, v20
	s_nop 1
	v_addc_co_u32_e32 v35, vcc, 0, v21, vcc
	v_add_co_u32_e32 v38, vcc, s57, v20
	s_nop 1
	v_addc_co_u32_e32 v39, vcc, 0, v21, vcc
	v_add_co_u32_e32 v40, vcc, s58, v20
	s_nop 1
	v_addc_co_u32_e32 v41, vcc, 0, v21, vcc
	v_add_co_u32_e32 v42, vcc, s59, v20
	s_nop 1
	v_addc_co_u32_e32 v43, vcc, 0, v21, vcc
	v_add_co_u32_e32 v44, vcc, s76, v20
	s_nop 1
	v_addc_co_u32_e32 v45, vcc, 0, v21, vcc
	v_add_co_u32_e32 v46, vcc, s77, v20
	s_nop 1
	v_addc_co_u32_e32 v47, vcc, 0, v21, vcc
	v_add_co_u32_e32 v48, vcc, s78, v20
	s_nop 1
	v_addc_co_u32_e32 v49, vcc, 0, v21, vcc
	v_add_co_u32_e32 v50, vcc, s79, v20
	s_nop 1
	v_addc_co_u32_e32 v51, vcc, 0, v21, vcc
	global_load_dword v68, v[34:35], off nt
	global_load_dword v69, v[38:39], off nt
	global_load_dword v70, v[40:41], off nt
	global_load_dword v71, v[42:43], off nt
	global_load_dword v72, v[44:45], off nt
	global_load_dword v73, v[46:47], off nt
	global_load_dword v74, v[48:49], off nt
	s_nop 0
	global_load_dword v50, v[50:51], off nt
	v_add_co_u32_e32 v34, vcc, s80, v20
	s_nop 1
	v_addc_co_u32_e32 v35, vcc, 0, v21, vcc
	v_add_co_u32_e32 v38, vcc, s81, v20
	s_nop 1
	v_addc_co_u32_e32 v39, vcc, 0, v21, vcc
	v_add_co_u32_e32 v40, vcc, s82, v20
	s_nop 1
	v_addc_co_u32_e32 v41, vcc, 0, v21, vcc
	v_add_co_u32_e32 v42, vcc, s83, v20
	s_nop 1
	v_addc_co_u32_e32 v43, vcc, 0, v21, vcc
	v_add_co_u32_e32 v44, vcc, s84, v20
	s_nop 1
	v_addc_co_u32_e32 v45, vcc, 0, v21, vcc
	v_add_co_u32_e32 v46, vcc, s85, v20
	s_nop 1
	v_addc_co_u32_e32 v47, vcc, 0, v21, vcc
	v_add_co_u32_e32 v48, vcc, s86, v20
	s_nop 1
	v_addc_co_u32_e32 v49, vcc, 0, v21, vcc
	v_add_co_u32_e32 v20, vcc, s87, v20
	s_nop 1
	v_addc_co_u32_e32 v21, vcc, 0, v21, vcc
	global_load_dword v34, v[34:35], off nt
	s_nop 0
	global_load_dword v35, v[38:39], off nt
	s_nop 0
	global_load_dword v38, v[40:41], off nt
	global_load_dword v39, v[42:43], off nt
	s_nop 0
	global_load_dword v40, v[44:45], off nt
	global_load_dword v41, v[46:47], off nt
	global_load_dword v42, v[48:49], off nt
	s_nop 0
	global_load_dword v20, v[20:21], off nt
	s_waitcnt vmcnt(30)
	ds_write2_b32 v3, v4, v53 offset1:66
	s_waitcnt vmcnt(28)
	ds_write2_b32 v3, v54, v55 offset0:132 offset1:198
	s_waitcnt vmcnt(26)
	ds_write2_b32 v31, v56, v57 offset0:8 offset1:74
	s_waitcnt vmcnt(24)
	ds_write2_b32 v31, v58, v59 offset0:140 offset1:206
	s_waitcnt vmcnt(22)
	ds_write2_b32 v32, v60, v61 offset0:16 offset1:82
	s_waitcnt vmcnt(20)
	ds_write2_b32 v32, v62, v63 offset0:148 offset1:214
	v_add_u32_e32 v4, 0xc00, v3
	s_waitcnt vmcnt(18)
	ds_write2_b32 v4, v64, v65 offset0:24 offset1:90
	s_waitcnt vmcnt(16)
	ds_write2_b32 v4, v66, v67 offset0:156 offset1:222
	v_add_u32_e32 v4, 0x1000, v3
	s_waitcnt vmcnt(14)
; #define LAS __attribute__((address_space(3)))
; #define LDS_WAIT() asm volatile("s_waitcnt lgkmcnt(0)" ::: "memory")
; __device__ __forceinline__ unsigned pk2(float lo, float hi) { return f2bf(lo) | (f2bf(hi) << 16); }
;     ...
;     for (int i = 0; i < 32; ++i) scr[(2 * i + (lane >> 5)) * 33 + (lane & 31)] = tv_[i];
;     LDS_WAIT(); asm volatile("" ::: "memory");
;     const int c = lane & 7;
; #pragma unroll
;     for (int j = 0; j < 4; ++j) { const int n = (lane >> 3) + 8 * j; const LAS float* s = scr + (8 * c) * 33 + n;
;         v4u o; o.x = pk2(s[0 * 33], s[1 * 33]); o.y = pk2(s[2 * 33], s[3 * 33]); o.z = pk2(s[4 * 33], s[5 * 33]); o.w = pk2(s[6 * 33], s[7 * 33]);
;         *(v4u*)(WT + (size_t)(n0 + n) * ldw + koff + k0 + 8 * c) = o; }
;     LDS_WAIT(); asm volatile("" ::: "memory");
	ds_write2_b32 v4, v68, v69 offset0:32 offset1:98
	s_waitcnt vmcnt(12)
	ds_write2_b32 v4, v70, v71 offset0:164 offset1:230
	v_add_u32_e32 v4, 0x1400, v3
	s_waitcnt vmcnt(10)
	ds_write2_b32 v4, v72, v73 offset0:40 offset1:106
	s_waitcnt vmcnt(8)
	ds_write2_b32 v4, v74, v50 offset0:172 offset1:238
	v_add_u32_e32 v4, 0x1800, v3
	s_waitcnt vmcnt(6)
	ds_write2_b32 v4, v34, v35 offset0:48 offset1:114
	s_waitcnt vmcnt(4)
	ds_write2_b32 v4, v38, v39 offset0:180 offset1:246
	v_add_u32_e32 v4, 0x1c00, v3
	s_waitcnt vmcnt(2)
	ds_write2_b32 v4, v40, v41 offset0:56 offset1:122
	s_waitcnt vmcnt(0)
	ds_write2_b32 v4, v42, v20 offset0:188 offset1:254
	s_waitcnt lgkmcnt(0)
	v_lshlrev_b32_e32 v4, 1, v33
	v_lshl_add_u64 v[20:21], v[36:37], 0, v[4:5]
	v_lshlrev_b32_e32 v4, 1, v6
	v_lshl_add_u64 v[20:21], v[20:21], 0, v[4:5]
	ds_read_b32 v4, v23
	ds_read_b32 v33, v23 offset:132
	ds_read_b32 v35, v23 offset:264
	ds_read_b32 v36, v23 offset:396
	ds_read_b32 v37, v23 offset:528
	ds_read_b32 v38, v23 offset:660
	ds_read_b32 v39, v23 offset:792
	ds_read_b32 v40, v23 offset:924
	s_waitcnt lgkmcnt(0)
	v_bfe_u32 v34, v4, 16, 1
	v_add3_u32 v4, v4, v34, s38
	v_bfe_u32 v34, v33, 16, 1
	v_lshrrev_b32_e32 v4, 16, v4
	v_add3_u32 v33, v33, v34, s38
	v_and_or_b32 v34, v33, s39, v4
	v_bfe_u32 v4, v35, 16, 1
	v_add3_u32 v4, v35, v4, s38
	v_bfe_u32 v33, v36, 16, 1
	v_lshrrev_b32_e32 v4, 16, v4
	v_add3_u32 v33, v36, v33, s38
	v_and_or_b32 v35, v33, s39, v4
	v_bfe_u32 v4, v37, 16, 1
	v_add3_u32 v4, v37, v4, s38
	v_bfe_u32 v33, v38, 16, 1
	v_lshrrev_b32_e32 v4, 16, v4
	v_add3_u32 v33, v38, v33, s38
	v_and_or_b32 v36, v33, s39, v4
	v_bfe_u32 v4, v39, 16, 1
	v_add3_u32 v4, v39, v4, s38
	v_bfe_u32 v33, v40, 16, 1
	v_lshrrev_b32_e32 v4, 16, v4
	v_add3_u32 v33, v40, v33, s38
	v_and_or_b32 v37, v33, s39, v4
	v_or_b32_e32 v4, v52, v7
	v_mul_u32_u24_e32 v4, 0xc00, v4
	v_lshl_add_u64 v[20:21], v[20:21], 0, s[30:31]
	v_lshlrev_b32_e32 v4, 1, v4
	v_lshl_add_u64 v[38:39], v[20:21], 0, v[4:5]
	global_store_dwordx4 v[38:39], v[34:37], off
	ds_read_b32 v4, v23 offset:32
	ds_read_b32 v33, v23 offset:164
	ds_read_b32 v35, v23 offset:296
	ds_read_b32 v36, v23 offset:428
	ds_read_b32 v37, v23 offset:560
	ds_read_b32 v38, v23 offset:692
	ds_read_b32 v39, v23 offset:824
	ds_read_b32 v40, v23 offset:956
	s_waitcnt lgkmcnt(0)
	v_bfe_u32 v34, v4, 16, 1
	v_add3_u32 v4, v4, v34, s38
	v_bfe_u32 v34, v33, 16, 1
	v_lshrrev_b32_e32 v4, 16, v4
	v_add3_u32 v33, v33, v34, s38
	v_and_or_b32 v34, v33, s39, v4
	v_bfe_u32 v4, v35, 16, 1
	v_add3_u32 v4, v35, v4, s38
	v_bfe_u32 v33, v36, 16, 1
	v_lshrrev_b32_e32 v4, 16, v4
	v_add3_u32 v33, v36, v33, s38
	v_and_or_b32 v35, v33, s39, v4
	v_bfe_u32 v4, v37, 16, 1
	v_add3_u32 v4, v37, v4, s38
	v_bfe_u32 v33, v38, 16, 1
	v_lshrrev_b32_e32 v4, 16, v4
	v_add3_u32 v33, v38, v33, s38
	v_and_or_b32 v36, v33, s39, v4
	v_bfe_u32 v4, v39, 16, 1
	v_add3_u32 v4, v39, v4, s38
	v_bfe_u32 v33, v40, 16, 1
	v_lshrrev_b32_e32 v4, 16, v4
	v_add3_u32 v33, v40, v33, s38
	v_and_or_b32 v37, v33, s39, v4
	v_or_b32_e32 v4, v52, v24
	v_mul_u32_u24_e32 v4, 0xc00, v4
	v_lshlrev_b32_e32 v4, 1, v4
	v_lshl_add_u64 v[38:39], v[20:21], 0, v[4:5]
	global_store_dwordx4 v[38:39], v[34:37], off
	ds_read_b32 v4, v23 offset:64
	ds_read_b32 v33, v23 offset:196
	ds_read_b32 v35, v23 offset:328
	ds_read_b32 v36, v23 offset:460
	ds_read_b32 v37, v23 offset:592
	ds_read_b32 v38, v23 offset:724
	ds_read_b32 v39, v23 offset:856
	ds_read_b32 v40, v23 offset:988
	s_waitcnt lgkmcnt(0)
	v_bfe_u32 v34, v4, 16, 1
	v_add3_u32 v4, v4, v34, s38
	v_bfe_u32 v34, v33, 16, 1
	v_lshrrev_b32_e32 v4, 16, v4
	v_add3_u32 v33, v33, v34, s38
	v_and_or_b32 v34, v33, s39, v4
	v_bfe_u32 v4, v35, 16, 1
	v_add3_u32 v4, v35, v4, s38
	v_bfe_u32 v33, v36, 16, 1
	v_lshrrev_b32_e32 v4, 16, v4
	v_add3_u32 v33, v36, v33, s38
	v_and_or_b32 v35, v33, s39, v4
	v_bfe_u32 v4, v37, 16, 1
	v_add3_u32 v4, v37, v4, s38
	v_bfe_u32 v33, v38, 16, 1
	v_lshrrev_b32_e32 v4, 16, v4
	v_add3_u32 v33, v38, v33, s38
	v_and_or_b32 v36, v33, s39, v4
	v_bfe_u32 v4, v39, 16, 1
	v_add3_u32 v4, v39, v4, s38
	v_bfe_u32 v33, v40, 16, 1
	v_lshrrev_b32_e32 v4, 16, v4
	v_add3_u32 v33, v40, v33, s38
	v_and_or_b32 v37, v33, s39, v4
	v_or_b32_e32 v4, v52, v25
	v_mul_u32_u24_e32 v4, 0xc00, v4
	v_lshlrev_b32_e32 v4, 1, v4
	v_lshl_add_u64 v[38:39], v[20:21], 0, v[4:5]
	global_store_dwordx4 v[38:39], v[34:37], off
	ds_read_b32 v4, v23 offset:96
	ds_read_b32 v33, v23 offset:228
	ds_read_b32 v35, v23 offset:360
	ds_read_b32 v36, v23 offset:492
	ds_read_b32 v37, v23 offset:624
	ds_read_b32 v38, v23 offset:756
	ds_read_b32 v39, v23 offset:888
	ds_read_b32 v40, v23 offset:1020
	s_waitcnt lgkmcnt(0)
	v_bfe_u32 v34, v4, 16, 1
	v_add3_u32 v4, v4, v34, s38
	v_bfe_u32 v34, v33, 16, 1
	v_lshrrev_b32_e32 v4, 16, v4
	v_add3_u32 v33, v33, v34, s38
	v_and_or_b32 v34, v33, s39, v4
	v_bfe_u32 v4, v35, 16, 1
	v_add3_u32 v4, v35, v4, s38
	v_bfe_u32 v33, v36, 16, 1
	v_lshrrev_b32_e32 v4, 16, v4
	v_add3_u32 v33, v36, v33, s38
	v_and_or_b32 v35, v33, s39, v4
	v_bfe_u32 v4, v37, 16, 1
	v_add3_u32 v4, v37, v4, s38
	v_bfe_u32 v33, v38, 16, 1
	v_lshrrev_b32_e32 v4, 16, v4
	v_add3_u32 v33, v38, v33, s38
	v_and_or_b32 v36, v33, s39, v4
	v_bfe_u32 v4, v39, 16, 1
	v_add3_u32 v4, v39, v4, s38
	v_bfe_u32 v33, v40, 16, 1
	v_lshrrev_b32_e32 v4, 16, v4
	v_add3_u32 v33, v40, v33, s38
	v_and_or_b32 v37, v33, s39, v4
	v_or_b32_e32 v4, v52, v26
	v_mul_u32_u24_e32 v4, 0xc00, v4
	v_lshlrev_b32_e32 v4, 1, v4
	v_lshl_add_u64 v[20:21], v[20:21], 0, v[4:5]
	global_store_dwordx4 v[20:21], v[34:37], off
	s_waitcnt lgkmcnt(0)

;     if (ldw == 0) ldw = K;
;     const int nblk = N / 32, kb = item / nblk, nb = item % nblk, k0 = 64 * kb, n0 = 32 * nb;
;     float tv_[32];
; #pragma unroll
;     for (int i = 0; i < 32; ++i) tv_[i] = W[(size_t)(k0 + 2 * i + (lane >> 5)) * N + n0 + (lane & 31)];
; #pragma unroll
;     for (int i = 0; i < 32; ++i) scr[(2 * i + (lane >> 5)) * 33 + (lane & 31)] = tv_[i];
; __device__ __forceinline__ void convert_range(LAS unsigned char* lds, const Params& p, const int lo, const int hi, const int gw, const int NGW) {
;     ...
;         if (r < 2 * I_PA) { const int l = r / I_PA; r -= l * I_PA; p0_transpose_item(p.in[16] + (size_t)l * PW * DM, PW, DM, (bf16*)(ws + WS_WCAT + l * SZ_WCAT), scr, r, lane, KCAT, 0); continue; } r -= 2 * I_PA;
.LBB0_72:
	s_andn2_saveexec_b64 s[26:27], s[26:27]
	s_cbranch_execz .LBB0_74
	v_add_u32_e32 v4, 0x2a00, v27
	v_lshrrev_b32_e32 v4, 10, v4
	v_readlane_b32 s68, v251, 9
	v_lshlrev_b64 v[34:35], 23, v[4:5]
	v_readlane_b32 s69, v251, 10
	v_mov_b64_e32 v[36:37], s[20:21]
	v_and_b32_e32 v52, 0x7e0, v30
	v_lshl_add_u64 v[34:35], s[68:69], 0, v[34:35]
	v_mad_u64_u32 v[36:37], s[28:29], v4, s88, v[36:37]
	v_and_b32_e32 v33, 0x3c0, v20
	v_lshlrev_b32_e32 v4, 2, v52
	v_or_b32_e32 v38, v33, v1
	v_lshl_add_u64 v[20:21], v[34:35], 0, v[4:5]
	v_lshlrev_b32_e32 v4, 2, v2
	v_lshl_add_u64 v[20:21], v[20:21], 0, v[4:5]
	v_lshlrev_b32_e32 v4, 13, v38
	v_lshl_add_u64 v[20:21], v[20:21], 0, v[4:5]
	v_add_co_u32_e32 v34, vcc, s7, v20
	v_readlane_b32 s70, v251, 11
	s_nop 0
	v_addc_co_u32_e32 v35, vcc, 0, v21, vcc
	v_add_co_u32_e32 v38, vcc, s40, v20
	v_readlane_b32 s71, v251, 12
	s_nop 0
	v_addc_co_u32_e32 v39, vcc, 0, v21, vcc
	v_add_co_u32_e32 v40, vcc, s42, v20
	v_readlane_b32 s72, v251, 13
	s_nop 0
	v_addc_co_u32_e32 v41, vcc, 0, v21, vcc
	v_add_co_u32_e32 v42, vcc, s43, v20
	v_readlane_b32 s73, v251, 14
	s_nop 0
	v_addc_co_u32_e32 v43, vcc, 0, v21, vcc
	v_add_co_u32_e32 v44, vcc, s44, v20
	v_readlane_b32 s74, v251, 15
	s_nop 0
	v_addc_co_u32_e32 v45, vcc, 0, v21, vcc
	v_add_co_u32_e32 v46, vcc, s45, v20
	v_readlane_b32 s75, v251, 16
	s_nop 0
	v_addc_co_u32_e32 v47, vcc, 0, v21, vcc
	v_add_co_u32_e32 v48, vcc, s47, v20
	s_nop 1
	v_addc_co_u32_e32 v49, vcc, 0, v21, vcc
	global_load_dword v4, v[20:21], off nt
	global_load_dword v53, v[34:35], off nt
	global_load_dword v54, v[38:39], off nt
	global_load_dword v55, v[40:41], off nt
	global_load_dword v56, v[42:43], off nt
	global_load_dword v57, v[44:45], off nt
	global_load_dword v58, v[46:47], off nt
	global_load_dword v59, v[48:49], off nt
	v_add_co_u32_e32 v34, vcc, s48, v20
	s_nop 1
	v_addc_co_u32_e32 v35, vcc, 0, v21, vcc
	v_add_co_u32_e32 v38, vcc, s49, v20
	s_nop 1
	v_addc_co_u32_e32 v39, vcc, 0, v21, vcc
	v_add_co_u32_e32 v40, vcc, s50, v20
	s_nop 1
	v_addc_co_u32_e32 v41, vcc, 0, v21, vcc
	v_add_co_u32_e32 v42, vcc, s51, v20
	s_nop 1
	v_addc_co_u32_e32 v43, vcc, 0, v21, vcc
	v_add_co_u32_e32 v44, vcc, s52, v20
	s_nop 1
	v_addc_co_u32_e32 v45, vcc, 0, v21, vcc
	v_add_co_u32_e32 v46, vcc, s53, v20
	s_nop 1
	v_addc_co_u32_e32 v47, vcc, 0, v21, vcc
	v_add_co_u32_e32 v48, vcc, s54, v20
	s_nop 1
	v_addc_co_u32_e32 v49, vcc, 0, v21, vcc
	v_add_co_u32_e32 v50, vcc, s55, v20
	s_nop 1
	v_addc_co_u32_e32 v51, vcc, 0, v21, vcc
	global_load_dword v60, v[34:35], off nt
	global_load_dword v61, v[38:39], off nt
	global_load_dword v62, v[40:41], off nt
	global_load_dword v63, v[42:43], off nt
	global_load_dword v64, v[44:45], off nt
	global_load_dword v65, v[46:47], off nt
	global_load_dword v66, v[48:49], off nt
	global_load_dword v67, v[50:51], off nt
	v_add_co_u32_e32 v34, vcc, s56, v20
	s_nop 1
	v_addc_co_u32_e32 v35, vcc, 0, v21, vcc
	v_add_co_u32_e32 v38, vcc, s57, v20
	s_nop 1
	v_addc_co_u32_e32 v39, vcc, 0, v21, vcc
	v_add_co_u32_e32 v40, vcc, s58, v20
	s_nop 1
	v_addc_co_u32_e32 v41, vcc, 0, v21, vcc
	v_add_co_u32_e32 v42, vcc, s59, v20
	s_nop 1
	v_addc_co_u32_e32 v43, vcc, 0, v21, vcc
	v_add_co_u32_e32 v44, vcc, s76, v20
	s_nop 1
	v_addc_co_u32_e32 v45, vcc, 0, v21, vcc
	v_add_co_u32_e32 v46, vcc, s77, v20
	s_nop 1
	v_addc_co_u32_e32 v47, vcc, 0, v21, vcc
	v_add_co_u32_e32 v48, vcc, s78, v20
	s_nop 1
	v_addc_co_u32_e32 v49, vcc, 0, v21, vcc
	v_add_co_u32_e32 v50, vcc, s79, v20
	s_nop 1
	v_addc_co_u32_e32 v51, vcc, 0, v21, vcc
	global_load_dword v68, v[34:35], off nt
	global_load_dword v69, v[38:39], off nt
	global_load_dword v70, v[40:41], off nt
	global_load_dword v71, v[42:43], off nt
	global_load_dword v72, v[44:45], off nt
	global_load_dword v73, v[46:47], off nt
	global_load_dword v74, v[48:49], off nt
	s_nop 0
	global_load_dword v50, v[50:51], off nt
	v_add_co_u32_e32 v34, vcc, s80, v20
	s_nop 1
	v_addc_co_u32_e32 v35, vcc, 0, v21, vcc
	v_add_co_u32_e32 v38, vcc, s81, v20
	s_nop 1
	v_addc_co_u32_e32 v39, vcc, 0, v21, vcc
	v_add_co_u32_e32 v40, vcc, s82, v20
	s_nop 1
	v_addc_co_u32_e32 v41, vcc, 0, v21, vcc
	v_add_co_u32_e32 v42, vcc, s83, v20
	s_nop 1
	v_addc_co_u32_e32 v43, vcc, 0, v21, vcc
	v_add_co_u32_e32 v44, vcc, s84, v20
	s_nop 1
	v_addc_co_u32_e32 v45, vcc, 0, v21, vcc
	v_add_co_u32_e32 v46, vcc, s85, v20
	s_nop 1
	v_addc_co_u32_e32 v47, vcc, 0, v21, vcc
	v_add_co_u32_e32 v48, vcc, s86, v20
	s_nop 1
	v_addc_co_u32_e32 v49, vcc, 0, v21, vcc
	v_add_co_u32_e32 v20, vcc, s87, v20
	s_nop 1
	v_addc_co_u32_e32 v21, vcc, 0, v21, vcc
	global_load_dword v34, v[34:35], off nt
	s_nop 0
	global_load_dword v35, v[38:39], off nt
	s_nop 0
	global_load_dword v38, v[40:41], off nt
	global_load_dword v39, v[42:43], off nt
	s_nop 0
	global_load_dword v40, v[44:45], off nt
	global_load_dword v41, v[46:47], off nt
	global_load_dword v42, v[48:49], off nt
	s_nop 0
	global_load_dword v20, v[20:21], off nt
	s_waitcnt vmcnt(30)
	ds_write2_b32 v3, v4, v53 offset1:66
	s_waitcnt vmcnt(28)
	ds_write2_b32 v3, v54, v55 offset0:132 offset1:198
	s_waitcnt vmcnt(26)
	ds_write2_b32 v31, v56, v57 offset0:8 offset1:74
	s_waitcnt vmcnt(24)
	ds_write2_b32 v31, v58, v59 offset0:140 offset1:206
	s_waitcnt vmcnt(22)
	ds_write2_b32 v32, v60, v61 offset0:16 offset1:82
	s_waitcnt vmcnt(20)
	ds_write2_b32 v32, v62, v63 offset0:148 offset1:214
	v_add_u32_e32 v4, 0xc00, v3
	s_waitcnt vmcnt(18)
	ds_write2_b32 v4, v64, v65 offset0:24 offset1:90
	s_waitcnt vmcnt(16)
	ds_write2_b32 v4, v66, v67 offset0:156 offset1:222
	v_add_u32_e32 v4, 0x1000, v3
	s_waitcnt vmcnt(14)
; #define LAS __attribute__((address_space(3)))
; #define LDS_WAIT() asm volatile("s_waitcnt lgkmcnt(0)" ::: "memory")
; __device__ __forceinline__ unsigned pk2(float lo, float hi) { return f2bf(lo) | (f2bf(hi) << 16); }
;     ...
;     for (int i = 0; i < 32; ++i) scr[(2 * i + (lane >> 5)) * 33 + (lane & 31)] = tv_[i];
;     LDS_WAIT(); asm volatile("" ::: "memory");
;     const int c = lane & 7;
; #pragma unroll
;     for (int j = 0; j < 4; ++j) { const int n = (lane >> 3) + 8 * j; const LAS float* s = scr + (8 * c) * 33 + n;
;         v4u o; o.x = pk2(s[0 * 33], s[1 * 33]); o.y = pk2(s[2 * 33], s[3 * 33]); o.z = pk2(s[4 * 33], s[5 * 33]); o.w = pk2(s[6 * 33], s[7 * 33]);
;         *(v4u*)(WT + (size_t)(n0 + n) * ldw + koff + k0 + 8 * c) = o; }
;     LDS_WAIT(); asm volatile("" ::: "memory");
	ds_write2_b32 v4, v68, v69 offset0:32 offset1:98
	s_waitcnt vmcnt(12)
	ds_write2_b32 v4, v70, v71 offset0:164 offset1:230
	v_add_u32_e32 v4, 0x1400, v3
	s_waitcnt vmcnt(10)
	ds_write2_b32 v4, v72, v73 offset0:40 offset1:106
	s_waitcnt vmcnt(8)
	ds_write2_b32 v4, v74, v50 offset0:172 offset1:238
	v_add_u32_e32 v4, 0x1800, v3
	s_waitcnt vmcnt(6)
	ds_write2_b32 v4, v34, v35 offset0:48 offset1:114
	s_waitcnt vmcnt(4)
	ds_write2_b32 v4, v38, v39 offset0:180 offset1:246
	v_add_u32_e32 v4, 0x1c00, v3
	s_waitcnt vmcnt(2)
	ds_write2_b32 v4, v40, v41 offset0:56 offset1:122
	s_waitcnt vmcnt(0)
	ds_write2_b32 v4, v42, v20 offset0:188 offset1:254
	s_waitcnt lgkmcnt(0)
	v_lshlrev_b32_e32 v4, 1, v33
	v_lshl_add_u64 v[20:21], v[36:37], 0, v[4:5]
	v_lshlrev_b32_e32 v4, 1, v6
	v_lshl_add_u64 v[20:21], v[20:21], 0, v[4:5]
	ds_read_b32 v4, v23
	ds_read_b32 v33, v23 offset:132
	ds_read_b32 v35, v23 offset:264
	ds_read_b32 v36, v23 offset:396
	ds_read_b32 v37, v23 offset:528
	ds_read_b32 v38, v23 offset:660
	ds_read_b32 v39, v23 offset:792
	ds_read_b32 v40, v23 offset:924
	s_waitcnt lgkmcnt(0)
	v_bfe_u32 v34, v4, 16, 1
	v_add3_u32 v4, v4, v34, s38
	v_bfe_u32 v34, v33, 16, 1
	v_lshrrev_b32_e32 v4, 16, v4
	v_add3_u32 v33, v33, v34, s38
	v_and_or_b32 v34, v33, s39, v4
	v_bfe_u32 v4, v35, 16, 1
	v_add3_u32 v4, v35, v4, s38
	v_bfe_u32 v33, v36, 16, 1
	v_lshrrev_b32_e32 v4, 16, v4
	v_add3_u32 v33, v36, v33, s38
	v_and_or_b32 v35, v33, s39, v4
	v_bfe_u32 v4, v37, 16, 1
	v_add3_u32 v4, v37, v4, s38
	v_bfe_u32 v33, v38, 16, 1
	v_lshrrev_b32_e32 v4, 16, v4
	v_add3_u32 v33, v38, v33, s38
	v_and_or_b32 v36, v33, s39, v4
	v_bfe_u32 v4, v39, 16, 1
	v_add3_u32 v4, v39, v4, s38
	v_bfe_u32 v33, v40, 16, 1
	v_lshrrev_b32_e32 v4, 16, v4
	v_add3_u32 v33, v40, v33, s38
	v_and_or_b32 v37, v33, s39, v4
	v_or_b32_e32 v4, v52, v7
	v_mul_u32_u24_e32 v4, 0xc00, v4
	v_lshlrev_b32_e32 v4, 1, v4
	v_lshl_add_u64 v[38:39], v[20:21], 0, v[4:5]
	global_store_dwordx4 v[38:39], v[34:37], off
	ds_read_b32 v4, v23 offset:32
	ds_read_b32 v33, v23 offset:164
	ds_read_b32 v35, v23 offset:296
	ds_read_b32 v36, v23 offset:428
	ds_read_b32 v37, v23 offset:560
	ds_read_b32 v38, v23 offset:692
	ds_read_b32 v39, v23 offset:824
	ds_read_b32 v40, v23 offset:956
	s_waitcnt lgkmcnt(0)
	v_bfe_u32 v34, v4, 16, 1
	v_add3_u32 v4, v4, v34, s38
	v_bfe_u32 v34, v33, 16, 1
	v_lshrrev_b32_e32 v4, 16, v4
	v_add3_u32 v33, v33, v34, s38
	v_and_or_b32 v34, v33, s39, v4
	v_bfe_u32 v4, v35, 16, 1
	v_add3_u32 v4, v35, v4, s38
	v_bfe_u32 v33, v36, 16, 1
	v_lshrrev_b32_e32 v4, 16, v4
	v_add3_u32 v33, v36, v33, s38
	v_and_or_b32 v35, v33, s39, v4
	v_bfe_u32 v4, v37, 16, 1
	v_add3_u32 v4, v37, v4, s38
	v_bfe_u32 v33, v38, 16, 1
	v_lshrrev_b32_e32 v4, 16, v4
	v_add3_u32 v33, v38, v33, s38
	v_and_or_b32 v36, v33, s39, v4
	v_bfe_u32 v4, v39, 16, 1
	v_add3_u32 v4, v39, v4, s38
	v_bfe_u32 v33, v40, 16, 1
	v_lshrrev_b32_e32 v4, 16, v4
	v_add3_u32 v33, v40, v33, s38
	v_and_or_b32 v37, v33, s39, v4
	v_or_b32_e32 v4, v52, v24
	v_mul_u32_u24_e32 v4, 0xc00, v4
	v_lshlrev_b32_e32 v4, 1, v4
	v_lshl_add_u64 v[38:39], v[20:21], 0, v[4:5]
	global_store_dwordx4 v[38:39], v[34:37], off
	ds_read_b32 v4, v23 offset:64
	ds_read_b32 v33, v23 offset:196
	ds_read_b32 v35, v23 offset:328
	ds_read_b32 v36, v23 offset:460
	ds_read_b32 v37, v23 offset:592
	ds_read_b32 v38, v23 offset:724
	ds_read_b32 v39, v23 offset:856
	ds_read_b32 v40, v23 offset:988
	s_waitcnt lgkmcnt(0)
	v_bfe_u32 v34, v4, 16, 1
	v_add3_u32 v4, v4, v34, s38
	v_bfe_u32 v34, v33, 16, 1
	v_lshrrev_b32_e32 v4, 16, v4
	v_add3_u32 v33, v33, v34, s38
	v_and_or_b32 v34, v33, s39, v4
	v_bfe_u32 v4, v35, 16, 1
	v_add3_u32 v4, v35, v4, s38
	v_bfe_u32 v33, v36, 16, 1
	v_lshrrev_b32_e32 v4, 16, v4
	v_add3_u32 v33, v36, v33, s38
	v_and_or_b32 v35, v33, s39, v4
	v_bfe_u32 v4, v37, 16, 1
	v_add3_u32 v4, v37, v4, s38
	v_bfe_u32 v33, v38, 16, 1
	v_lshrrev_b32_e32 v4, 16, v4
	v_add3_u32 v33, v38, v33, s38
	v_and_or_b32 v36, v33, s39, v4
	v_bfe_u32 v4, v39, 16, 1
	v_add3_u32 v4, v39, v4, s38
	v_bfe_u32 v33, v40, 16, 1
	v_lshrrev_b32_e32 v4, 16, v4
	v_add3_u32 v33, v40, v33, s38
	v_and_or_b32 v37, v33, s39, v4
	v_or_b32_e32 v4, v52, v25
	v_mul_u32_u24_e32 v4, 0xc00, v4
	v_lshlrev_b32_e32 v4, 1, v4
	v_lshl_add_u64 v[38:39], v[20:21], 0, v[4:5]
	global_store_dwordx4 v[38:39], v[34:37], off
	ds_read_b32 v4, v23 offset:96
	ds_read_b32 v33, v23 offset:228
	ds_read_b32 v35, v23 offset:360
	ds_read_b32 v36, v23 offset:492
	ds_read_b32 v37, v23 offset:624
	ds_read_b32 v38, v23 offset:756
	ds_read_b32 v39, v23 offset:888
	ds_read_b32 v40, v23 offset:1020
	s_waitcnt lgkmcnt(0)
	v_bfe_u32 v34, v4, 16, 1
	v_add3_u32 v4, v4, v34, s38
	v_bfe_u32 v34, v33, 16, 1
	v_lshrrev_b32_e32 v4, 16, v4
	v_add3_u32 v33, v33, v34, s38
	v_and_or_b32 v34, v33, s39, v4
	v_bfe_u32 v4, v35, 16, 1
	v_add3_u32 v4, v35, v4, s38
	v_bfe_u32 v33, v36, 16, 1
	v_lshrrev_b32_e32 v4, 16, v4
	v_add3_u32 v33, v36, v33, s38
	v_and_or_b32 v35, v33, s39, v4
	v_bfe_u32 v4, v37, 16, 1
	v_add3_u32 v4, v37, v4, s38
	v_bfe_u32 v33, v38, 16, 1
	v_lshrrev_b32_e32 v4, 16, v4
	v_add3_u32 v33, v38, v33, s38
	v_and_or_b32 v36, v33, s39, v4
	v_bfe_u32 v4, v39, 16, 1
	v_add3_u32 v4, v39, v4, s38
	v_bfe_u32 v33, v40, 16, 1
	v_lshrrev_b32_e32 v4, 16, v4
	v_add3_u32 v33, v40, v33, s38
	v_and_or_b32 v37, v33, s39, v4
	v_or_b32_e32 v4, v52, v26
	v_mul_u32_u24_e32 v4, 0xc00, v4
	v_lshlrev_b32_e32 v4, 1, v4
	v_lshl_add_u64 v[20:21], v[20:21], 0, v[4:5]
	global_store_dwordx4 v[20:21], v[34:37], off
	s_waitcnt lgkmcnt(0)

;     if (ldw == 0) ldw = K;
;     const int nblk = N / 32, kb = item / nblk, nb = item % nblk, k0 = 64 * kb, n0 = 32 * nb;
;     float tv_[32];
; #pragma unroll
;     for (int i = 0; i < 32; ++i) tv_[i] = W[(size_t)(k0 + 2 * i + (lane >> 5)) * N + n0 + (lane & 31)];
; #pragma unroll
;     for (int i = 0; i < 32; ++i) scr[(2 * i + (lane >> 5)) * 33 + (lane & 31)] = tv_[i];
; __device__ __forceinline__ void convert_range(LAS unsigned char* lds, const Params& p, const int lo, const int hi, const int gw, const int NGW) {
;     ...
;         if (r < 2 * I_IN) { const int l = r / I_IN; r -= l * I_IN; p0_transpose_item(p.in[5] + (size_t)l * DM * NC, DM, NC, (bf16*)(ws + WS_WIN + l * SZ_WIN), scr, r, lane); continue; } r -= 2 * I_IN;
.LBB0_75:
	s_andn2_saveexec_b64 s[24:25], s[24:25]
	s_cbranch_execz .LBB0_52
	v_mul_hi_i32 v4, v20, s89
	v_lshrrev_b32_e32 v20, 31, v4
	v_ashrrev_i32_e32 v4, 12, v4
	v_add_u32_e32 v33, v4, v20
	v_readlane_b32 s60, v251, 21
	v_mul_i32_i24_e32 v4, 0xffffd800, v33
	s_movk_i32 s26, 0x7a00
	v_readlane_b32 s70, v251, 31
	v_readlane_b32 s71, v251, 32
	v_add3_u32 v4, v4, v27, s26
	s_mov_b32 s26, 0x5000000
	v_mov_b64_e32 v[20:21], s[70:71]
	v_mad_i64_i32 v[34:35], s[26:27], v33, s26, v[20:21]
	v_mul_hi_i32 v20, v4, s89
	v_lshrrev_b32_e32 v21, 31, v20
	v_ashrrev_i32_e32 v20, 7, v20
	v_add_u32_e32 v20, v20, v21
	v_mul_i32_i24_e32 v21, 0x140, v20
	v_sub_u32_e32 v4, v4, v21
	v_lshlrev_b32_e32 v36, 6, v20
	v_lshlrev_b32_e32 v20, 5, v4
	v_ashrrev_i32_e32 v21, 31, v20
	v_or_b32_e32 v37, v36, v1
	v_lshl_add_u64 v[34:35], v[20:21], 2, v[34:35]
	v_lshlrev_b32_e32 v4, 2, v2
	v_lshl_add_u64 v[34:35], v[34:35], 0, v[4:5]
	v_or_b32_e32 v4, 2, v37
	v_mad_i64_i32 v[40:41], s[26:27], v4, s41, v[34:35]
	v_or_b32_e32 v4, 4, v37
	v_mad_i64_i32 v[42:43], s[26:27], v4, s41, v[34:35]
	v_or_b32_e32 v4, 6, v37
	v_mad_i64_i32 v[44:45], s[26:27], v4, s41, v[34:35]
	v_or_b32_e32 v4, 8, v37
	v_mad_i64_i32 v[46:47], s[26:27], v4, s41, v[34:35]
	v_or_b32_e32 v4, 10, v37
	v_mad_i64_i32 v[48:49], s[26:27], v4, s41, v[34:35]
	v_or_b32_e32 v4, 12, v37
	v_mad_i64_i32 v[50:51], s[26:27], v4, s41, v[34:35]
	v_or_b32_e32 v4, 14, v37
	v_mad_i64_i32 v[38:39], s[26:27], v37, s41, v[34:35]
	v_mad_i64_i32 v[52:53], s[26:27], v4, s41, v[34:35]
	global_load_dword v4, v[38:39], off nt
	global_load_dword v21, v[40:41], off nt
	global_load_dword v54, v[42:43], off nt
	global_load_dword v55, v[44:45], off nt
	global_load_dword v56, v[46:47], off nt
	global_load_dword v57, v[48:49], off nt
	global_load_dword v58, v[50:51], off nt
	global_load_dword v59, v[52:53], off nt
	v_or_b32_e32 v38, 16, v37
	v_or_b32_e32 v40, 18, v37
	v_or_b32_e32 v42, 20, v37
	v_or_b32_e32 v44, 22, v37
	v_or_b32_e32 v52, 30, v37
	v_mad_i64_i32 v[38:39], s[26:27], v38, s41, v[34:35]
	v_mad_i64_i32 v[40:41], s[26:27], v40, s41, v[34:35]
	v_mad_i64_i32 v[42:43], s[26:27], v42, s41, v[34:35]
	v_mad_i64_i32 v[44:45], s[26:27], v44, s41, v[34:35]
	v_or_b32_e32 v46, 24, v37
	v_or_b32_e32 v48, 26, v37
	v_or_b32_e32 v50, 28, v37
	v_mad_i64_i32 v[52:53], s[26:27], v52, s41, v[34:35]
	v_mad_i64_i32 v[46:47], s[26:27], v46, s41, v[34:35]
	v_mad_i64_i32 v[48:49], s[26:27], v48, s41, v[34:35]
	v_mad_i64_i32 v[50:51], s[26:27], v50, s41, v[34:35]
	global_load_dword v60, v[38:39], off nt
	global_load_dword v61, v[40:41], off nt
	global_load_dword v62, v[42:43], off nt
	global_load_dword v63, v[44:45], off nt
	global_load_dword v64, v[46:47], off nt
	global_load_dword v65, v[48:49], off nt
	global_load_dword v66, v[50:51], off nt
	global_load_dword v67, v[52:53], off nt
	v_or_b32_e32 v38, 32, v37
	v_or_b32_e32 v40, 34, v37
	v_or_b32_e32 v42, 36, v37
	v_or_b32_e32 v44, 38, v37
	v_or_b32_e32 v52, 46, v37
	v_mad_i64_i32 v[38:39], s[26:27], v38, s41, v[34:35]
	v_mad_i64_i32 v[40:41], s[26:27], v40, s41, v[34:35]
	v_mad_i64_i32 v[42:43], s[26:27], v42, s41, v[34:35]
	v_mad_i64_i32 v[44:45], s[26:27], v44, s41, v[34:35]
	v_or_b32_e32 v46, 40, v37
	v_or_b32_e32 v48, 42, v37
	v_or_b32_e32 v50, 44, v37
	v_mad_i64_i32 v[52:53], s[26:27], v52, s41, v[34:35]
	v_mad_i64_i32 v[46:47], s[26:27], v46, s41, v[34:35]
	v_mad_i64_i32 v[48:49], s[26:27], v48, s41, v[34:35]
	v_mad_i64_i32 v[50:51], s[26:27], v50, s41, v[34:35]
	global_load_dword v68, v[38:39], off nt
	global_load_dword v69, v[40:41], off nt
	global_load_dword v70, v[42:43], off nt
	global_load_dword v71, v[44:45], off nt
	global_load_dword v72, v[46:47], off nt
	global_load_dword v73, v[48:49], off nt
	global_load_dword v74, v[50:51], off nt
	s_nop 0
	global_load_dword v52, v[52:53], off nt
	v_or_b32_e32 v38, 48, v37
	v_or_b32_e32 v40, 50, v37
	v_or_b32_e32 v42, 52, v37
	v_or_b32_e32 v44, 54, v37
	v_mad_i64_i32 v[38:39], s[26:27], v38, s41, v[34:35]
	v_mad_i64_i32 v[40:41], s[26:27], v40, s41, v[34:35]
	v_mad_i64_i32 v[42:43], s[26:27], v42, s41, v[34:35]
	v_mad_i64_i32 v[44:45], s[26:27], v44, s41, v[34:35]
	v_or_b32_e32 v46, 56, v37
	v_or_b32_e32 v48, 58, v37
	v_or_b32_e32 v50, 60, v37
	v_or_b32_e32 v37, 62, v37
	v_mad_i64_i32 v[46:47], s[26:27], v46, s41, v[34:35]
	v_mad_i64_i32 v[48:49], s[26:27], v48, s41, v[34:35]
	v_mad_i64_i32 v[50:51], s[26:27], v50, s41, v[34:35]
	v_mad_i64_i32 v[34:35], s[26:27], v37, s41, v[34:35]
	global_load_dword v37, v[38:39], off nt
	s_nop 0
	global_load_dword v38, v[40:41], off nt
	global_load_dword v39, v[42:43], off nt
	s_nop 0
	global_load_dword v40, v[44:45], off nt
	global_load_dword v41, v[46:47], off nt
	global_load_dword v42, v[48:49], off nt
	global_load_dword v43, v[50:51], off nt
	s_nop 0
	global_load_dword v44, v[34:35], off nt
	s_waitcnt vmcnt(30)
	ds_write2_b32 v3, v4, v21 offset1:66
	s_waitcnt vmcnt(28)
	ds_write2_b32 v3, v54, v55 offset0:132 offset1:198
	s_waitcnt vmcnt(26)
	ds_write2_b32 v31, v56, v57 offset0:8 offset1:74
	s_waitcnt vmcnt(24)
	ds_write2_b32 v31, v58, v59 offset0:140 offset1:206
	s_waitcnt vmcnt(22)
	ds_write2_b32 v32, v60, v61 offset0:16 offset1:82
	s_waitcnt vmcnt(20)
	ds_write2_b32 v32, v62, v63 offset0:148 offset1:214
	v_add_u32_e32 v4, 0xc00, v3
	s_waitcnt vmcnt(18)
	ds_write2_b32 v4, v64, v65 offset0:24 offset1:90
	s_waitcnt vmcnt(16)
	ds_write2_b32 v4, v66, v67 offset0:156 offset1:222
	v_add_u32_e32 v4, 0x1000, v3
	s_waitcnt vmcnt(14)
	ds_write2_b32 v4, v68, v69 offset0:32 offset1:98
	s_waitcnt vmcnt(12)
	ds_write2_b32 v4, v70, v71 offset0:164 offset1:230
	v_add_u32_e32 v4, 0x1400, v3
	s_waitcnt vmcnt(10)
; #define LAS __attribute__((address_space(3)))
; #define LDS_WAIT() asm volatile("s_waitcnt lgkmcnt(0)" ::: "memory")
; __device__ __forceinline__ unsigned pk2(float lo, float hi) { return f2bf(lo) | (f2bf(hi) << 16); }
;     ...
;     for (int i = 0; i < 32; ++i) scr[(2 * i + (lane >> 5)) * 33 + (lane & 31)] = tv_[i];
;     LDS_WAIT(); asm volatile("" ::: "memory");
;     const int c = lane & 7;
; #pragma unroll
;     for (int j = 0; j < 4; ++j) { const int n = (lane >> 3) + 8 * j; const LAS float* s = scr + (8 * c) * 33 + n;
;         v4u o; o.x = pk2(s[0 * 33], s[1 * 33]); o.y = pk2(s[2 * 33], s[3 * 33]); o.z = pk2(s[4 * 33], s[5 * 33]); o.w = pk2(s[6 * 33], s[7 * 33]);
;         *(v4u*)(WT + (size_t)(n0 + n) * ldw + koff + k0 + 8 * c) = o; }
;     LDS_WAIT(); asm volatile("" ::: "memory");
; __device__ __forceinline__ void convert_range(LAS unsigned char* lds, const Params& p, const int lo, const int hi, const int gw, const int NGW) {
;     ...
;         if (r < 2 * I_IN) { const int l = r / I_IN; r -= l * I_IN; p0_transpose_item(p.in[5] + (size_t)l * DM * NC, DM, NC, (bf16*)(ws + WS_WIN + l * SZ_WIN), scr, r, lane); continue; } r -= 2 * I_IN;
	ds_write2_b32 v4, v72, v73 offset0:40 offset1:106
	s_waitcnt vmcnt(8)
	ds_write2_b32 v4, v74, v52 offset0:172 offset1:238
	v_add_u32_e32 v4, 0x1800, v3
	s_waitcnt vmcnt(6)
	ds_write2_b32 v4, v37, v38 offset0:48 offset1:114
	s_waitcnt vmcnt(4)
	ds_write2_b32 v4, v39, v40 offset0:180 offset1:246
	v_add_u32_e32 v4, 0x1c00, v3
	v_mov_b64_e32 v[34:35], s[8:9]
	s_mov_b32 s26, 0x2800000
	s_waitcnt vmcnt(2)
	ds_write2_b32 v4, v41, v42 offset0:56 offset1:122
	s_waitcnt vmcnt(0)
	ds_write2_b32 v4, v43, v44 offset0:188 offset1:254
	v_mad_i64_i32 v[34:35], s[26:27], v33, s26, v[34:35]
	s_waitcnt lgkmcnt(0)
	v_ashrrev_i32_e32 v37, 31, v36
	v_lshl_add_u64 v[34:35], v[36:37], 1, v[34:35]
	v_lshlrev_b32_e32 v4, 1, v6
	v_lshl_add_u64 v[38:39], v[34:35], 0, v[4:5]
	ds_read_b32 v4, v23
	ds_read_b32 v21, v23 offset:132
	ds_read_b32 v33, v23 offset:264
	ds_read_b32 v35, v23 offset:396
	ds_read_b32 v36, v23 offset:528
	ds_read_b32 v37, v23 offset:660
	ds_read_b32 v40, v23 offset:792
	ds_read_b32 v41, v23 offset:924
	s_waitcnt lgkmcnt(0)
	v_bfe_u32 v34, v4, 16, 1
	v_add3_u32 v4, v4, v34, s38
	v_bfe_u32 v34, v21, 16, 1
	v_lshrrev_b32_e32 v4, 16, v4
	v_add3_u32 v21, v21, v34, s38
	v_and_or_b32 v34, v21, s39, v4
	v_bfe_u32 v4, v33, 16, 1
	v_add3_u32 v4, v33, v4, s38
	v_bfe_u32 v21, v35, 16, 1
	v_lshrrev_b32_e32 v4, 16, v4
	v_add3_u32 v21, v35, v21, s38
	v_and_or_b32 v35, v21, s39, v4
	v_bfe_u32 v4, v36, 16, 1
	v_add3_u32 v4, v36, v4, s38
	v_bfe_u32 v21, v37, 16, 1
	v_lshrrev_b32_e32 v4, 16, v4
	v_add3_u32 v21, v37, v21, s38
	v_and_or_b32 v36, v21, s39, v4
	v_bfe_u32 v4, v40, 16, 1
	v_add3_u32 v4, v40, v4, s38
	v_bfe_u32 v21, v41, 16, 1
	v_or_b32_e32 v40, v20, v7
	v_add3_u32 v21, v41, v21, s38
	v_ashrrev_i32_e32 v41, 31, v40
	v_lshrrev_b32_e32 v4, 16, v4
	v_lshlrev_b64 v[40:41], 12, v[40:41]
	v_and_or_b32 v37, v21, s39, v4
	v_lshl_add_u64 v[40:41], v[38:39], 0, v[40:41]
	global_store_dwordx4 v[40:41], v[34:37], off
	ds_read_b32 v4, v23 offset:32
	ds_read_b32 v21, v23 offset:164
	ds_read_b32 v33, v23 offset:296
	ds_read_b32 v35, v23 offset:428
	ds_read_b32 v36, v23 offset:560
	ds_read_b32 v37, v23 offset:692
	ds_read_b32 v40, v23 offset:824
	ds_read_b32 v41, v23 offset:956
	s_waitcnt lgkmcnt(0)
	v_bfe_u32 v34, v4, 16, 1
	v_add3_u32 v4, v4, v34, s38
	v_bfe_u32 v34, v21, 16, 1
	v_lshrrev_b32_e32 v4, 16, v4
	v_add3_u32 v21, v21, v34, s38
	v_and_or_b32 v34, v21, s39, v4
	v_bfe_u32 v4, v33, 16, 1
	v_add3_u32 v4, v33, v4, s38
	v_bfe_u32 v21, v35, 16, 1
	v_lshrrev_b32_e32 v4, 16, v4
	v_add3_u32 v21, v35, v21, s38
	v_and_or_b32 v35, v21, s39, v4
	v_bfe_u32 v4, v36, 16, 1
	v_add3_u32 v4, v36, v4, s38
	v_bfe_u32 v21, v37, 16, 1
	v_lshrrev_b32_e32 v4, 16, v4
	v_add3_u32 v21, v37, v21, s38
	v_and_or_b32 v36, v21, s39, v4
	v_bfe_u32 v4, v40, 16, 1
	v_add3_u32 v4, v40, v4, s38
	v_bfe_u32 v21, v41, 16, 1
	v_or_b32_e32 v40, v20, v24
	v_add3_u32 v21, v41, v21, s38
	v_ashrrev_i32_e32 v41, 31, v40
	v_lshrrev_b32_e32 v4, 16, v4
	v_lshlrev_b64 v[40:41], 12, v[40:41]
	v_and_or_b32 v37, v21, s39, v4
	v_lshl_add_u64 v[40:41], v[38:39], 0, v[40:41]
	global_store_dwordx4 v[40:41], v[34:37], off
	ds_read_b32 v4, v23 offset:64
	ds_read_b32 v21, v23 offset:196
	ds_read_b32 v33, v23 offset:328
	ds_read_b32 v35, v23 offset:460
	ds_read_b32 v36, v23 offset:592
	ds_read_b32 v37, v23 offset:724
	ds_read_b32 v40, v23 offset:856
	ds_read_b32 v41, v23 offset:988
	s_waitcnt lgkmcnt(0)
	v_bfe_u32 v34, v4, 16, 1
	v_add3_u32 v4, v4, v34, s38
	v_bfe_u32 v34, v21, 16, 1
	v_lshrrev_b32_e32 v4, 16, v4
	v_add3_u32 v21, v21, v34, s38
	v_and_or_b32 v34, v21, s39, v4
	v_bfe_u32 v4, v33, 16, 1
	v_add3_u32 v4, v33, v4, s38
	v_bfe_u32 v21, v35, 16, 1
	v_lshrrev_b32_e32 v4, 16, v4
	v_add3_u32 v21, v35, v21, s38
	v_and_or_b32 v35, v21, s39, v4
	v_bfe_u32 v4, v36, 16, 1
	v_add3_u32 v4, v36, v4, s38
	v_bfe_u32 v21, v37, 16, 1
	v_lshrrev_b32_e32 v4, 16, v4
	v_add3_u32 v21, v37, v21, s38
	v_and_or_b32 v36, v21, s39, v4
	v_bfe_u32 v4, v40, 16, 1
	v_add3_u32 v4, v40, v4, s38
	v_bfe_u32 v21, v41, 16, 1
	v_or_b32_e32 v40, v20, v25
	v_add3_u32 v21, v41, v21, s38
	v_ashrrev_i32_e32 v41, 31, v40
	v_lshrrev_b32_e32 v4, 16, v4
	v_lshlrev_b64 v[40:41], 12, v[40:41]
	v_and_or_b32 v37, v21, s39, v4
	v_lshl_add_u64 v[40:41], v[38:39], 0, v[40:41]
	global_store_dwordx4 v[40:41], v[34:37], off
	ds_read_b32 v4, v23 offset:96
	ds_read_b32 v21, v23 offset:228
	ds_read_b32 v33, v23 offset:360
	ds_read_b32 v35, v23 offset:492
	ds_read_b32 v36, v23 offset:624
	ds_read_b32 v37, v23 offset:756
	ds_read_b32 v40, v23 offset:888
	ds_read_b32 v41, v23 offset:1020
	s_waitcnt lgkmcnt(0)
	v_bfe_u32 v34, v4, 16, 1
	v_add3_u32 v4, v4, v34, s38
	v_bfe_u32 v34, v21, 16, 1
	v_lshrrev_b32_e32 v4, 16, v4
	v_add3_u32 v21, v21, v34, s38
	v_and_or_b32 v34, v21, s39, v4
	v_bfe_u32 v4, v33, 16, 1
	v_add3_u32 v4, v33, v4, s38
	v_bfe_u32 v21, v35, 16, 1
	v_lshrrev_b32_e32 v4, 16, v4
	v_add3_u32 v21, v35, v21, s38
	v_and_or_b32 v35, v21, s39, v4
	v_bfe_u32 v4, v36, 16, 1
	v_add3_u32 v4, v36, v4, s38
	v_bfe_u32 v21, v37, 16, 1
	v_lshrrev_b32_e32 v4, 16, v4
	v_add3_u32 v21, v37, v21, s38
	v_and_or_b32 v36, v21, s39, v4
	v_bfe_u32 v4, v40, 16, 1
	v_add3_u32 v4, v40, v4, s38
	v_bfe_u32 v21, v41, 16, 1
	v_lshrrev_b32_e32 v4, 16, v4
	v_add3_u32 v21, v41, v21, s38
	v_or_b32_e32 v20, v20, v26
	v_and_or_b32 v37, v21, s39, v4
	v_ashrrev_i32_e32 v21, 31, v20
	v_lshlrev_b64 v[20:21], 12, v[20:21]
	v_lshl_add_u64 v[20:21], v[38:39], 0, v[20:21]
	global_store_dwordx4 v[20:21], v[34:37], off
	s_waitcnt lgkmcnt(0)
	v_readlane_b32 s61, v251, 22
	v_readlane_b32 s62, v251, 23
	v_readlane_b32 s63, v251, 24
	v_readlane_b32 s64, v251, 25
	v_readlane_b32 s65, v251, 26
	v_readlane_b32 s66, v251, 27
	v_readlane_b32 s67, v251, 28
	v_readlane_b32 s68, v251, 29
	v_readlane_b32 s69, v251, 30
	v_readlane_b32 s72, v251, 33
	v_readlane_b32 s73, v251, 34
	v_readlane_b32 s74, v251, 35
	v_readlane_b32 s75, v251, 36
	s_branch .LBB0_52

; __device__ __forceinline__ unsigned pk2(float lo, float hi) { return f2bf(lo) | (f2bf(hi) << 16); }
; __device__ __forceinline__ void p0_prologue(LAS unsigned char* lds, const Params& p) {
;     ...
;     for (int m = gw; m < MT; m += NGW) {
;         const float* xr = (m < NP) ? p.in[0] + (size_t)m * DM : p.in[1] + (size_t)(m - NP) * DM;
;         unsigned long long* o8 = (unsigned long long*)(XB + (size_t)m * DM) + lane;
; #pragma unroll
;         for (int j = 0; j < 8; ++j) { const f32x4 v = *((const f32x4*)xr + lane + 64 * j); o8[64 * j] = (unsigned long long)pk2(v.x, v.y) | ((unsigned long long)pk2(v.z, v.w) << 32); }
;     }
.LBB0_81:
	s_or_b64 exec, exec, s[14:15]
	v_lshl_add_u64 v[18:19], v[10:11], 0, v[8:9]
	v_add_co_u32_e32 v14, vcc, s19, v18
	s_nop 1
	v_addc_co_u32_e32 v15, vcc, 0, v19, vcc
	global_load_dwordx4 v[100:103], v[18:19], off nt
	global_load_dwordx4 v[104:107], v[18:19], off offset:1024 nt
	global_load_dwordx4 v[108:111], v[18:19], off offset:2048 nt
	global_load_dwordx4 v[112:115], v[18:19], off offset:3072 nt
	global_load_dwordx4 v[116:119], v[14:15], off nt
	global_load_dwordx4 v[120:123], v[14:15], off offset:1024 nt
	global_load_dwordx4 v[124:127], v[14:15], off offset:2048 nt
	global_load_dwordx4 v[128:131], v[14:15], off offset:3072 nt
	v_lshlrev_b64 v[10:11], 12, v[12:13]
	v_lshl_add_u64 v[20:21], v[4:5], 0, v[10:11]
	v_lshl_add_u64 v[0:1], v[0:1], 0, s[6:7]
	v_lshl_add_u64 v[6:7], v[6:7], 0, s[10:11]
	v_cmp_lt_i32_e32 vcc, s20, v0
	s_or_b64 s[12:13], vcc, s[12:13]
	s_waitcnt vmcnt(7)
	v_cvt_pk_bf16_f32 v10, v100, v101
	v_cvt_pk_bf16_f32 v11, v102, v103
	global_store_dwordx2 v[20:21], v[10:11], off
	s_waitcnt vmcnt(7)
	v_cvt_pk_bf16_f32 v10, v104, v105
	v_cvt_pk_bf16_f32 v11, v106, v107
	global_store_dwordx2 v[20:21], v[10:11], off offset:512
	s_waitcnt vmcnt(7)
	v_cvt_pk_bf16_f32 v10, v108, v109
	v_cvt_pk_bf16_f32 v11, v110, v111
	global_store_dwordx2 v[20:21], v[10:11], off offset:1024
	s_waitcnt vmcnt(7)
	v_cvt_pk_bf16_f32 v10, v112, v113
	v_cvt_pk_bf16_f32 v11, v114, v115
	global_store_dwordx2 v[20:21], v[10:11], off offset:1536
	s_waitcnt vmcnt(7)
	v_cvt_pk_bf16_f32 v10, v116, v117
	v_cvt_pk_bf16_f32 v11, v118, v119
	global_store_dwordx2 v[20:21], v[10:11], off offset:2048
	s_waitcnt vmcnt(7)
	v_cvt_pk_bf16_f32 v10, v120, v121
	v_cvt_pk_bf16_f32 v11, v122, v123
	global_store_dwordx2 v[20:21], v[10:11], off offset:2560
	s_waitcnt vmcnt(7)
	v_cvt_pk_bf16_f32 v10, v124, v125
	v_cvt_pk_bf16_f32 v11, v126, v127
	global_store_dwordx2 v[20:21], v[10:11], off offset:3072
	s_waitcnt vmcnt(7)
	v_cvt_pk_bf16_f32 v10, v128, v129
	v_cvt_pk_bf16_f32 v11, v130, v131
	global_store_dwordx2 v[20:21], v[10:11], off offset:3584
	s_andn2_b64 exec, exec, s[12:13]
	s_cbranch_execz .LBB0_84

; __device__ __forceinline__ void p0_prologue(LAS unsigned char* lds, const Params& p) {
;     ...
;     for (int i = blockIdx.x * NTHR + tid; i < 2 * LW; i += gridDim.x * NTHR) { const float x = -p.in[15][i]; C8[i] = 8.0f * (fmaxf(x, 0.f) + log1pf(expf(-fabsf(x)))); }
.LBB0_86:
	v_ashrrev_i32_e32 v1, 31, v0
	v_lshlrev_b64 v[6:7], 2, v[0:1]
	v_lshl_add_u64 v[8:9], s[78:79], 0, v[6:7]
	global_load_dword v1, v[8:9], off nt
	v_add_u32_e32 v0, s12, v0
	v_cmp_lt_i32_e32 vcc, s21, v0
	v_lshl_add_u64 v[6:7], s[8:9], 0, v[6:7]
	s_or_b64 s[10:11], vcc, s[10:11]
	s_waitcnt vmcnt(0)
	v_mul_f32_e64 v3, |v1|, s13
	v_fma_f32 v8, |v1|, s13, -v3
	v_rndne_f32_e32 v9, v3
	v_fma_f32 v8, |v1|, s14, v8
	v_sub_f32_e32 v3, v3, v9
	v_add_f32_e32 v3, v3, v8
	v_cvt_i32_f32_e32 v9, v9
	v_exp_f32_e32 v3, v3
	v_cmp_ngt_f32_e64 s[0:1], |v1|, s15
	v_max_f32_e64 v8, -v1, -v1
	v_max_f32_e32 v22, 0, v8
	v_ldexp_f32 v3, v3, v9
	v_cndmask_b32_e64 v3, 0, v3, s[0:1]
	v_cmp_nlt_f32_e64 s[0:1], |v1|, s16
	s_nop 1
	v_cndmask_b32_e64 v1, v4, v3, s[0:1]
	v_add_f32_e32 v3, 1.0, v1
	v_add_f32_e32 v10, -1.0, v3
	v_frexp_mant_f32_e32 v11, v3
	v_cvt_f64_f32_e32 v[8:9], v3
	v_sub_f32_e32 v12, v10, v3
	v_frexp_exp_i32_f64_e32 v8, v[8:9]
	v_cmp_gt_f32_e64 s[0:1], s18, v11
	v_sub_f32_e32 v10, v1, v10
	v_add_f32_e32 v9, 1.0, v12
	v_subbrev_co_u32_e64 v8, s[0:1], 0, v8, s[0:1]
	v_add_f32_e32 v9, v10, v9
	v_sub_u32_e32 v10, 0, v8
	v_ldexp_f32 v3, v3, v10
	v_ldexp_f32 v9, v9, v10
	v_add_f32_e32 v10, -1.0, v3
	v_add_f32_e32 v12, 1.0, v3
	v_add_f32_e32 v11, 1.0, v10
	v_add_f32_e32 v13, -1.0, v12
	v_sub_f32_e32 v11, v3, v11
	v_sub_f32_e32 v3, v3, v13
	v_add_f32_e32 v3, v9, v3
	v_add_f32_e32 v13, v9, v11
	v_add_f32_e32 v9, v12, v3
	v_rcp_f32_e32 v16, v9
	v_add_f32_e32 v11, v10, v13
	v_sub_f32_e32 v12, v12, v9
	v_add_f32_e32 v3, v3, v12
	v_mul_f32_e32 v18, v11, v16
	v_mul_f32_e32 v12, v9, v18
	v_fma_f32 v14, v18, v9, -v12
	v_sub_f32_e32 v10, v10, v11
	v_fmac_f32_e32 v14, v18, v3
	v_add_f32_e32 v17, v13, v10
	v_add_f32_e32 v10, v12, v14
	v_sub_f32_e32 v13, v11, v10
	v_mov_b32_e32 v15, v10
	v_pk_add_f32 v[10:11], v[10:11], v[12:13] neg_lo:[0,1] neg_hi:[0,1]
	v_cvt_f32_i32_e32 v8, v8
	v_pk_add_f32 v[10:11], v[10:11], v[14:15] neg_lo:[0,1] neg_hi:[0,1]
	v_cmp_neq_f32_e64 s[0:1], s17, v1
	v_add_f32_e32 v11, v17, v11
	v_add_f32_e32 v10, v10, v11
	v_add_f32_e32 v11, v13, v10
	v_mul_f32_e32 v15, v16, v11
	v_mul_f32_e32 v12, v9, v15
	v_fma_f32 v14, v15, v9, -v12
	v_sub_f32_e32 v13, v13, v11
	v_fmac_f32_e32 v14, v15, v3
	v_add_f32_e32 v17, v10, v13
	v_add_f32_e32 v19, v18, v15
	v_add_f32_e32 v10, v12, v14
	v_sub_f32_e32 v9, v19, v18
	v_sub_f32_e32 v13, v11, v10
	v_sub_f32_e32 v3, v15, v9
	v_mov_b32_e32 v15, v10
	v_pk_add_f32 v[10:11], v[10:11], v[12:13] neg_lo:[0,1] neg_hi:[0,1]
	s_nop 0
	v_pk_add_f32 v[10:11], v[10:11], v[14:15] neg_lo:[0,1] neg_hi:[0,1]
	s_nop 0
	v_add_f32_e32 v9, v17, v11
	v_add_f32_e32 v9, v10, v9
	v_add_f32_e32 v9, v13, v9
	v_mul_f32_e32 v9, v16, v9
	v_add_f32_e32 v3, v3, v9
	v_add_f32_e32 v9, v19, v3
	v_mul_f32_e32 v10, v9, v9
	v_sub_f32_e32 v12, v9, v19
	v_fmamk_f32 v13, v10, 0x3e9b6dac, v5
	v_ldexp_f32 v11, v9, 1
	v_sub_f32_e32 v12, v3, v12
	v_mul_f32_e32 v9, v9, v10
	v_fmaak_f32 v3, v10, v13, 0x3f2aaada
	v_ldexp_f32 v15, v12, 1
	v_pk_mul_f32 v[12:13], v[8:9], v[2:3]
	s_nop 0
	v_fma_f32 v10, v8, s19, -v12
	v_fmac_f32_e32 v10, 0xb102e308, v8
	v_pk_add_f32 v[8:9], v[12:13], v[10:11]
	v_mov_b32_e32 v14, v12
	v_sub_f32_e32 v3, v9, v11
	v_sub_f32_e32 v3, v13, v3
	v_add_f32_e32 v15, v15, v3
	v_pk_add_f32 v[16:17], v[8:9], v[12:13] neg_lo:[0,1] neg_hi:[0,1]
	v_pk_add_f32 v[12:13], v[8:9], v[14:15]
	v_mov_b32_e32 v11, v8
	v_mov_b32_e32 v17, v13
	v_pk_add_f32 v[20:21], v[10:11], v[16:17] neg_lo:[0,1] neg_hi:[0,1]
	v_pk_add_f32 v[10:11], v[10:11], v[16:17]
	v_mov_b32_e32 v19, v8
	v_pk_add_f32 v[16:17], v[10:11], v[8:9] op_sel:[1,0] op_sel_hi:[0,1] neg_lo:[0,1] neg_hi:[0,1]
	v_mov_b32_e32 v18, v15
	v_mov_b32_e32 v14, v13
	v_mov_b32_e32 v15, v11
	v_pk_mov_b32 v[8:9], v[8:9], v[16:17] op_sel:[1,0]
	v_pk_add_f32 v[12:13], v[12:13], v[16:17] op_sel_hi:[1,0] neg_lo:[0,1] neg_hi:[0,1]
	v_pk_add_f32 v[8:9], v[14:15], v[8:9] neg_lo:[0,1] neg_hi:[0,1]
	v_mov_b32_e32 v12, v20
	v_pk_add_f32 v[8:9], v[18:19], v[8:9] neg_lo:[0,1] neg_hi:[0,1]
	v_mov_b32_e32 v21, v11
	v_pk_add_f32 v[12:13], v[12:13], v[8:9]
	s_nop 0
	v_pk_add_f32 v[14:15], v[12:13], v[12:13] op_sel:[0,1] op_sel_hi:[1,0]
	s_nop 0
	v_pk_add_f32 v[10:11], v[10:11], v[14:15] op_sel:[1,0] op_sel_hi:[0,1]
	v_mov_b32_e32 v13, v10
	v_mov_b32_e32 v9, v14
	v_pk_add_f32 v[14:15], v[12:13], v[20:21] neg_lo:[0,1] neg_hi:[0,1]
	s_nop 0
	v_sub_f32_e32 v3, v12, v14
	v_pk_add_f32 v[8:9], v[8:9], v[14:15] neg_lo:[0,1] neg_hi:[0,1]
	v_sub_f32_e32 v3, v20, v3
	v_add_f32_e32 v3, v8, v3
	v_add_f32_e32 v3, v3, v9
	v_add_f32_e32 v3, v10, v3
	v_cndmask_b32_e64 v3, v4, v3, s[0:1]
	v_cmp_lt_f32_e64 s[0:1], |v1|, s20
	s_nop 1
	v_cndmask_b32_e64 v1, v3, v1, s[0:1]
	v_add_f32_e32 v1, v22, v1
	v_mul_f32_e32 v1, 0x41000000, v1
	global_store_dword v[6:7], v1, off
	s_andn2_b64 exec, exec, s[10:11]
	s_cbranch_execnz .LBB0_86
